# weight-conversion loops: bf16 weight stores sc0 sc1 nt (write-through streaming, less dirty L2 to flush at the phase barrier)
# baseline (speedup 1.0000x reference)
.LBB0_32:
	s_cmpk_gt_i32 s47, 0x15ff
	s_mov_b64 s[8:9], -1
	s_cbranch_scc0 .LBB0_50
	s_cmpk_gt_u32 s47, 0x20ff
	s_cbranch_scc0 .LBB0_47
	s_cmpk_gt_u32 s47, 0x2cff
	s_cbranch_scc0 .LBB0_44
	s_cmpk_gt_u32 s47, 0x30ff
	s_cbranch_scc0 .LBB0_41
	s_cmpk_gt_u32 s47, 0x46ff
	s_cbranch_scc0 .LBB0_38
	s_load_dwordx2 s[10:11], s[16:17], 0x98
	s_add_i32 s8, s20, 0xffee4000
	s_and_b32 s9, s22, 0x1fc0
	s_and_b32 s8, s8, 0x7c0
	s_add_i32 s6, s47, 0xffffb900
	v_add_u32_e32 v6, s9, v5
	s_lshl_b32 s9, s8, 2
	s_waitcnt lgkmcnt(0)
	s_add_u32 s10, s10, s9
	s_addc_u32 s11, s11, 0
	v_ashrrev_i32_e32 v7, 31, v6
	v_lshl_add_u64 v[46:47], s[10:11], 0, v[2:3]
	v_lshlrev_b64 v[6:7], 13, v[6:7]
	v_lshl_add_u64 v[6:7], v[46:47], 0, v[6:7]
	v_add_co_u32_e32 v50, vcc, s25, v6
	v_add_u32_e32 v45, 0x400, v10
	s_nop 0
	v_addc_co_u32_e32 v51, vcc, 0, v7, vcc
	v_add_co_u32_e32 v54, vcc, s26, v6
	global_load_dwordx4 v[46:49], v[6:7], off nt
	s_nop 0
	global_load_dwordx4 v[50:53], v[50:51], off nt
	v_addc_co_u32_e32 v55, vcc, 0, v7, vcc
	v_add_co_u32_e32 v58, vcc, s27, v6
	s_lshr_b32 s6, s6, 5
	s_nop 0
	v_addc_co_u32_e32 v59, vcc, 0, v7, vcc
	v_add_co_u32_e32 v62, vcc, s28, v6
	global_load_dwordx4 v[54:57], v[54:55], off nt
	s_nop 0
	global_load_dwordx4 v[58:61], v[58:59], off nt
	v_addc_co_u32_e32 v63, vcc, 0, v7, vcc
	v_add_co_u32_e32 v66, vcc, s29, v6
	s_nop 1
	v_addc_co_u32_e32 v67, vcc, 0, v7, vcc
	v_add_co_u32_e32 v70, vcc, s30, v6
	global_load_dwordx4 v[62:65], v[62:63], off nt
	s_nop 0
	global_load_dwordx4 v[66:69], v[66:67], off nt
	v_addc_co_u32_e32 v71, vcc, 0, v7, vcc
	v_add_co_u32_e32 v74, vcc, s31, v6
	s_nop 1
	v_addc_co_u32_e32 v75, vcc, 0, v7, vcc
	v_add_co_u32_e32 v78, vcc, s33, v6
	global_load_dwordx4 v[70:73], v[70:71], off nt
	s_nop 0
	global_load_dwordx4 v[74:77], v[74:75], off nt
	v_addc_co_u32_e32 v79, vcc, 0, v7, vcc
	v_add_co_u32_e32 v82, vcc, s34, v6
	s_nop 1
	v_addc_co_u32_e32 v83, vcc, 0, v7, vcc
	v_add_co_u32_e32 v86, vcc, s35, v6
	global_load_dwordx4 v[78:81], v[78:79], off nt
	s_nop 0
	global_load_dwordx4 v[82:85], v[82:83], off nt
	v_addc_co_u32_e32 v87, vcc, 0, v7, vcc
	v_add_co_u32_e32 v90, vcc, s36, v6
	s_nop 1
	v_addc_co_u32_e32 v91, vcc, 0, v7, vcc
	global_load_dwordx4 v[86:89], v[86:87], off nt
	s_nop 0
	global_load_dwordx4 v[90:93], v[90:91], off nt
	v_add_co_u32_e32 v94, vcc, s37, v6
	s_nop 1
	v_addc_co_u32_e32 v95, vcc, 0, v7, vcc
	global_load_dwordx4 v[94:97], v[94:95], off nt
	v_add_co_u32_e32 v98, vcc, s38, v6
	s_nop 1
	v_addc_co_u32_e32 v99, vcc, 0, v7, vcc
	global_load_dwordx4 v[98:101], v[98:99], off nt
	v_add_co_u32_e32 v102, vcc, s39, v6
	s_nop 1
	v_addc_co_u32_e32 v103, vcc, 0, v7, vcc
	global_load_dwordx4 v[102:105], v[102:103], off nt
	v_add_co_u32_e32 v6, vcc, s40, v6
	s_nop 1
	v_addc_co_u32_e32 v7, vcc, 0, v7, vcc
	global_load_dwordx4 v[106:109], v[6:7], off nt
	v_add_u32_e32 v6, 0x2498, v8
	s_waitcnt vmcnt(15)
	ds_write2_b32 v8, v46, v47 offset1:1
	ds_write2_b32 v8, v48, v49 offset0:2 offset1:3
	s_waitcnt vmcnt(14)
	ds_write2_b32 v26, v50, v51 offset1:1
	ds_write2_b32 v27, v52, v53 offset1:1
	s_waitcnt vmcnt(13)
	ds_write2_b32 v28, v54, v55 offset1:1
	ds_write2_b32 v29, v56, v57 offset1:1
	s_waitcnt vmcnt(12)
	ds_write2_b32 v30, v58, v59 offset1:1
	ds_write2_b32 v31, v60, v61 offset1:1
	s_waitcnt vmcnt(11)
	ds_write2_b32 v32, v62, v63 offset1:1
	ds_write2_b32 v33, v64, v65 offset1:1
	s_waitcnt vmcnt(10)
	ds_write2_b32 v34, v66, v67 offset1:1
	ds_write2_b32 v35, v68, v69 offset1:1
	s_waitcnt vmcnt(9)
	ds_write2_b32 v36, v70, v71 offset1:1
	ds_write2_b32 v37, v72, v73 offset1:1
	s_waitcnt vmcnt(8)
	ds_write2_b32 v38, v74, v75 offset1:1
	ds_write2_b32 v39, v76, v77 offset1:1
	s_waitcnt vmcnt(7)
	ds_write2_b32 v40, v78, v79 offset1:1
	ds_write2_b32 v41, v80, v81 offset1:1
	s_waitcnt vmcnt(6)
	ds_write2_b32 v42, v82, v83 offset1:1
	ds_write2_b32 v6, v84, v85 offset1:1
	v_add_u32_e32 v6, 0x28a0, v8
	v_mov_b32_e32 v67, v3
	v_mov_b32_e32 v69, v3
	s_waitcnt vmcnt(5)
	ds_write2_b32 v6, v86, v87 offset1:1
	v_add_u32_e32 v6, 0x28a8, v8
	ds_write2_b32 v6, v88, v89 offset1:1
	v_add_u32_e32 v6, 0x2cb0, v8
	s_waitcnt vmcnt(4)
	ds_write2_b32 v6, v90, v91 offset1:1
	v_add_u32_e32 v6, 0x2cb8, v8
	ds_write2_b32 v6, v92, v93 offset1:1
	v_add_u32_e32 v6, 0x30c0, v8
	s_waitcnt vmcnt(3)
	ds_write2_b32 v6, v94, v95 offset1:1
	v_add_u32_e32 v6, 0x30c8, v8
	ds_write2_b32 v6, v96, v97 offset1:1
	v_add_u32_e32 v6, 0x34d0, v8
	s_waitcnt vmcnt(2)
	ds_write2_b32 v6, v98, v99 offset1:1
	v_add_u32_e32 v6, 0x34d8, v8
	ds_write2_b32 v6, v100, v101 offset1:1
	v_add_u32_e32 v6, 0x38e0, v8
	s_waitcnt vmcnt(1)
	ds_write2_b32 v6, v102, v103 offset1:1
	v_add_u32_e32 v6, 0x38e8, v8
	ds_write2_b32 v6, v104, v105 offset1:1
	v_add_u32_e32 v6, 0x3cf0, v8
	s_waitcnt vmcnt(0)
	ds_write2_b32 v6, v106, v107 offset1:1
	v_add_u32_e32 v6, 0x3cf8, v8
	ds_write2_b32 v6, v108, v109 offset1:1
	s_waitcnt lgkmcnt(0)
	ds_read2_b32 v[50:51], v10 offset1:8
	ds_read2_b32 v[52:53], v10 offset0:65 offset1:73
	ds_read2_b32 v[54:55], v10 offset0:130 offset1:138
	ds_read2_b32 v[56:57], v10 offset0:195 offset1:203
	ds_read2_b32 v[58:59], v45 offset0:4 offset1:12
	s_waitcnt lgkmcnt(4)
	v_bfe_u32 v6, v50, 16, 1
	v_add3_u32 v6, v50, v6, s41
	s_waitcnt lgkmcnt(3)
	v_bfe_u32 v7, v52, 16, 1
	v_lshrrev_b32_e32 v6, 16, v6
	v_add3_u32 v7, v52, v7, s41
	ds_read2_b32 v[60:61], v45 offset0:69 offset1:77
	v_and_or_b32 v46, v7, s42, v6
	s_waitcnt lgkmcnt(3)
	v_bfe_u32 v6, v54, 16, 1
	v_add3_u32 v6, v54, v6, s41
	s_waitcnt lgkmcnt(2)
	v_bfe_u32 v7, v56, 16, 1
	ds_read2_b32 v[62:63], v45 offset0:134 offset1:142
	v_lshrrev_b32_e32 v6, 16, v6
	v_add3_u32 v7, v56, v7, s41
	ds_read2_b32 v[64:65], v45 offset0:199 offset1:207
	v_and_or_b32 v47, v7, s42, v6
	s_waitcnt lgkmcnt(3)
	v_bfe_u32 v6, v58, 16, 1
	v_add3_u32 v6, v58, v6, s41
	s_waitcnt lgkmcnt(2)
	v_bfe_u32 v7, v60, 16, 1
	v_lshrrev_b32_e32 v6, 16, v6
	v_add3_u32 v7, v60, v7, s41
	v_and_or_b32 v48, v7, s42, v6
	s_waitcnt lgkmcnt(1)
	v_bfe_u32 v6, v62, 16, 1
	v_add3_u32 v6, v62, v6, s41
	s_waitcnt lgkmcnt(0)
	v_bfe_u32 v7, v64, 16, 1
	v_lshrrev_b32_e32 v6, 16, v6
	v_add3_u32 v7, v64, v7, s41
	v_add_u32_e32 v50, s8, v9
	v_and_or_b32 v49, v7, s42, v6
	v_lshrrev_b32_e32 v6, 8, v50
	v_mul_i32_i24_e32 v6, 0x58, v6
	v_ashrrev_i32_e32 v7, 31, v6
	v_lshl_add_u64 v[6:7], v[6:7], 0, s[6:7]
	v_lshlrev_b64 v[6:7], 15, v[6:7]
	v_lshlrev_b32_e32 v50, 7, v50
	v_lshl_add_u64 v[6:7], s[0:1], 0, v[6:7]
	v_and_b32_e32 v66, 0x7f80, v50
	v_lshl_add_u64 v[66:67], v[6:7], 0, v[66:67]
	v_lshlrev_b32_e32 v6, 1, v4
	v_mov_b32_e32 v7, v3
	v_lshl_add_u64 v[66:67], v[66:67], 0, v[6:7]
	global_store_dwordx4 v[66:67], v[46:49], off sc0 sc1 nt
	v_bfe_u32 v50, v65, 16, 1
	v_add3_u32 v50, v65, v50, s41
	v_bfe_u32 v46, v51, 16, 1
	v_add3_u32 v46, v51, v46, s41
	v_bfe_u32 v47, v53, 16, 1
	v_lshrrev_b32_e32 v46, 16, v46
	v_add3_u32 v47, v53, v47, s41
	v_and_or_b32 v46, v47, s42, v46
	v_bfe_u32 v47, v55, 16, 1
	v_add3_u32 v47, v55, v47, s41
	v_bfe_u32 v48, v57, 16, 1
	v_lshrrev_b32_e32 v47, 16, v47
	v_add3_u32 v48, v57, v48, s41
	v_and_or_b32 v47, v48, s42, v47
	v_bfe_u32 v48, v59, 16, 1
	v_add3_u32 v48, v59, v48, s41
	v_bfe_u32 v49, v61, 16, 1
	v_lshrrev_b32_e32 v48, 16, v48
	v_add3_u32 v49, v61, v49, s41
	v_and_or_b32 v48, v49, s42, v48
	v_bfe_u32 v49, v63, 16, 1
	v_add3_u32 v49, v63, v49, s41
	v_lshrrev_b32_e32 v49, 16, v49
	v_add_u32_e32 v52, s8, v11
	v_and_or_b32 v49, v50, s42, v49
	v_lshrrev_b32_e32 v50, 8, v52
	v_mul_i32_i24_e32 v50, 0x58, v50
	v_ashrrev_i32_e32 v51, 31, v50
	v_lshl_add_u64 v[50:51], v[50:51], 0, s[6:7]
	v_lshlrev_b64 v[50:51], 15, v[50:51]
	v_lshlrev_b32_e32 v52, 7, v52
	v_lshl_add_u64 v[50:51], s[0:1], 0, v[50:51]
	v_and_b32_e32 v52, 0x7f80, v52
	v_mov_b32_e32 v53, v3
	v_lshl_add_u64 v[50:51], v[50:51], 0, v[52:53]
	ds_read2_b32 v[54:55], v10 offset0:16 offset1:24
	v_lshl_add_u64 v[50:51], v[50:51], 0, v[6:7]
	global_store_dwordx4 v[50:51], v[46:49], off sc0 sc1 nt
	ds_read2_b32 v[50:51], v10 offset0:81 offset1:89
	ds_read2_b32 v[52:53], v10 offset0:146 offset1:154
	ds_read2_b32 v[56:57], v10 offset0:211 offset1:219
	s_waitcnt lgkmcnt(3)
	v_bfe_u32 v46, v54, 16, 1
	v_add3_u32 v46, v54, v46, s41
	s_waitcnt lgkmcnt(2)
	v_bfe_u32 v47, v50, 16, 1
	ds_read2_b32 v[58:59], v45 offset0:20 offset1:28
	v_lshrrev_b32_e32 v46, 16, v46
	v_add3_u32 v47, v50, v47, s41
	ds_read2_b32 v[60:61], v45 offset0:85 offset1:93
	v_and_or_b32 v46, v47, s42, v46
	s_waitcnt lgkmcnt(3)
	v_bfe_u32 v47, v52, 16, 1
	v_add3_u32 v47, v52, v47, s41
	s_waitcnt lgkmcnt(2)
	v_bfe_u32 v48, v56, 16, 1
	ds_read2_b32 v[62:63], v45 offset0:150 offset1:158
	v_lshrrev_b32_e32 v47, 16, v47
	v_add3_u32 v48, v56, v48, s41
	ds_read2_b32 v[64:65], v45 offset0:215 offset1:223
	v_and_or_b32 v47, v48, s42, v47
	s_waitcnt lgkmcnt(3)
	v_bfe_u32 v48, v58, 16, 1
	v_add3_u32 v48, v58, v48, s41
	s_waitcnt lgkmcnt(2)
	v_bfe_u32 v49, v60, 16, 1
	v_lshrrev_b32_e32 v48, 16, v48
	v_add3_u32 v49, v60, v49, s41
	v_and_or_b32 v48, v49, s42, v48
	s_waitcnt lgkmcnt(1)
	v_bfe_u32 v49, v62, 16, 1
	v_add3_u32 v49, v62, v49, s41
	s_waitcnt lgkmcnt(0)
	v_bfe_u32 v50, v64, 16, 1
	v_lshrrev_b32_e32 v49, 16, v49
	v_add3_u32 v50, v64, v50, s41
	v_and_or_b32 v49, v50, s42, v49
	v_add_u32_e32 v50, s8, v12
	v_lshrrev_b32_e32 v52, 8, v50
	v_mul_i32_i24_e32 v66, 0x58, v52
	v_ashrrev_i32_e32 v67, 31, v66
	v_lshl_add_u64 v[66:67], v[66:67], 0, s[6:7]
	v_lshlrev_b64 v[66:67], 15, v[66:67]
	v_lshlrev_b32_e32 v50, 7, v50
	v_lshl_add_u64 v[66:67], s[0:1], 0, v[66:67]
	v_and_b32_e32 v68, 0x7f80, v50
	v_lshl_add_u64 v[66:67], v[66:67], 0, v[68:69]
	v_lshl_add_u64 v[66:67], v[66:67], 0, v[6:7]
	global_store_dwordx4 v[66:67], v[46:49], off sc0 sc1 nt
	v_bfe_u32 v50, v65, 16, 1
	v_add3_u32 v50, v65, v50, s41
	v_bfe_u32 v46, v55, 16, 1
	v_add3_u32 v46, v55, v46, s41
	v_bfe_u32 v47, v51, 16, 1
	v_lshrrev_b32_e32 v46, 16, v46
	v_add3_u32 v47, v51, v47, s41
	v_and_or_b32 v46, v47, s42, v46
	v_bfe_u32 v47, v53, 16, 1
	v_add3_u32 v47, v53, v47, s41
	v_bfe_u32 v48, v57, 16, 1
	v_lshrrev_b32_e32 v47, 16, v47
	v_add3_u32 v48, v57, v48, s41
	v_and_or_b32 v47, v48, s42, v47
	v_bfe_u32 v48, v59, 16, 1
	v_add3_u32 v48, v59, v48, s41
	v_bfe_u32 v49, v61, 16, 1
	v_lshrrev_b32_e32 v48, 16, v48
	v_add3_u32 v49, v61, v49, s41
	v_and_or_b32 v48, v49, s42, v48
	v_bfe_u32 v49, v63, 16, 1
	v_add3_u32 v49, v63, v49, s41
	v_lshrrev_b32_e32 v49, 16, v49
	v_add_u32_e32 v52, s8, v13
	v_and_or_b32 v49, v50, s42, v49
	v_lshrrev_b32_e32 v50, 8, v52
	v_mul_i32_i24_e32 v50, 0x58, v50
	v_ashrrev_i32_e32 v51, 31, v50
	v_lshl_add_u64 v[50:51], v[50:51], 0, s[6:7]
	v_lshlrev_b64 v[50:51], 15, v[50:51]
	v_lshlrev_b32_e32 v52, 7, v52
	v_lshl_add_u64 v[50:51], s[0:1], 0, v[50:51]
	v_and_b32_e32 v52, 0x7f80, v52
	v_mov_b32_e32 v53, v3
	v_lshl_add_u64 v[50:51], v[50:51], 0, v[52:53]
	ds_read2_b32 v[54:55], v10 offset0:32 offset1:40
	v_lshl_add_u64 v[50:51], v[50:51], 0, v[6:7]
	global_store_dwordx4 v[50:51], v[46:49], off sc0 sc1 nt
	ds_read2_b32 v[50:51], v10 offset0:97 offset1:105
	ds_read2_b32 v[52:53], v10 offset0:162 offset1:170
	ds_read2_b32 v[56:57], v10 offset0:227 offset1:235
	s_waitcnt lgkmcnt(3)
	v_bfe_u32 v46, v54, 16, 1
	v_add3_u32 v46, v54, v46, s41
	s_waitcnt lgkmcnt(2)
	v_bfe_u32 v47, v50, 16, 1
	ds_read2_b32 v[58:59], v45 offset0:36 offset1:44
	v_lshrrev_b32_e32 v46, 16, v46
	v_add3_u32 v47, v50, v47, s41
	ds_read2_b32 v[60:61], v45 offset0:101 offset1:109
	v_and_or_b32 v46, v47, s42, v46
	s_waitcnt lgkmcnt(3)
	v_bfe_u32 v47, v52, 16, 1
	v_add3_u32 v47, v52, v47, s41
	s_waitcnt lgkmcnt(2)
	v_bfe_u32 v48, v56, 16, 1
	ds_read2_b32 v[62:63], v45 offset0:166 offset1:174
	v_lshrrev_b32_e32 v47, 16, v47
	v_add3_u32 v48, v56, v48, s41
	ds_read2_b32 v[64:65], v45 offset0:231 offset1:239
	v_and_or_b32 v47, v48, s42, v47
	s_waitcnt lgkmcnt(3)
	v_bfe_u32 v48, v58, 16, 1
	v_add3_u32 v48, v58, v48, s41
	s_waitcnt lgkmcnt(2)
	v_bfe_u32 v49, v60, 16, 1
	v_lshrrev_b32_e32 v48, 16, v48
	v_add3_u32 v49, v60, v49, s41
	v_and_or_b32 v48, v49, s42, v48
	s_waitcnt lgkmcnt(1)
	v_bfe_u32 v49, v62, 16, 1
	v_add3_u32 v49, v62, v49, s41
	s_waitcnt lgkmcnt(0)
	v_bfe_u32 v50, v64, 16, 1
	v_lshrrev_b32_e32 v49, 16, v49
	v_add3_u32 v50, v64, v50, s41
	v_and_or_b32 v49, v50, s42, v49
	v_add_u32_e32 v50, s8, v14
	v_lshrrev_b32_e32 v52, 8, v50
	v_mul_i32_i24_e32 v66, 0x58, v52
	v_ashrrev_i32_e32 v67, 31, v66
	v_lshl_add_u64 v[66:67], v[66:67], 0, s[6:7]
	v_lshlrev_b64 v[66:67], 15, v[66:67]
	v_lshlrev_b32_e32 v50, 7, v50
	v_lshl_add_u64 v[66:67], s[0:1], 0, v[66:67]
	v_and_b32_e32 v68, 0x7f80, v50
	v_lshl_add_u64 v[66:67], v[66:67], 0, v[68:69]
	v_lshl_add_u64 v[66:67], v[66:67], 0, v[6:7]
	global_store_dwordx4 v[66:67], v[46:49], off sc0 sc1 nt
	v_bfe_u32 v50, v65, 16, 1
	v_add3_u32 v50, v65, v50, s41
	v_bfe_u32 v46, v55, 16, 1
	v_add3_u32 v46, v55, v46, s41
	v_bfe_u32 v47, v51, 16, 1
	v_lshrrev_b32_e32 v46, 16, v46
	v_add3_u32 v47, v51, v47, s41
	v_and_or_b32 v46, v47, s42, v46
	v_bfe_u32 v47, v53, 16, 1
	v_add3_u32 v47, v53, v47, s41
	v_bfe_u32 v48, v57, 16, 1
	v_lshrrev_b32_e32 v47, 16, v47
	v_add3_u32 v48, v57, v48, s41
	v_and_or_b32 v47, v48, s42, v47
	v_bfe_u32 v48, v59, 16, 1
	v_add3_u32 v48, v59, v48, s41
	v_bfe_u32 v49, v61, 16, 1
	v_lshrrev_b32_e32 v48, 16, v48
	v_add3_u32 v49, v61, v49, s41
	v_and_or_b32 v48, v49, s42, v48
	v_bfe_u32 v49, v63, 16, 1
	v_add3_u32 v49, v63, v49, s41
	v_lshrrev_b32_e32 v49, 16, v49
	v_add_u32_e32 v52, s8, v15
	v_and_or_b32 v49, v50, s42, v49
	v_lshrrev_b32_e32 v50, 8, v52
	v_mul_i32_i24_e32 v50, 0x58, v50
	v_ashrrev_i32_e32 v51, 31, v50
	v_lshl_add_u64 v[50:51], v[50:51], 0, s[6:7]
	v_lshlrev_b64 v[50:51], 15, v[50:51]
	v_lshlrev_b32_e32 v52, 7, v52
	v_lshl_add_u64 v[50:51], s[0:1], 0, v[50:51]
	v_and_b32_e32 v52, 0x7f80, v52
	v_mov_b32_e32 v53, v3
	v_lshl_add_u64 v[50:51], v[50:51], 0, v[52:53]
	ds_read2_b32 v[54:55], v10 offset0:48 offset1:56
	v_lshl_add_u64 v[50:51], v[50:51], 0, v[6:7]
	global_store_dwordx4 v[50:51], v[46:49], off sc0 sc1 nt
	ds_read2_b32 v[50:51], v10 offset0:113 offset1:121
	ds_read2_b32 v[52:53], v10 offset0:178 offset1:186
	ds_read2_b32 v[56:57], v10 offset0:243 offset1:251
	s_waitcnt lgkmcnt(3)
	v_bfe_u32 v46, v54, 16, 1
	v_add3_u32 v46, v54, v46, s41
	s_waitcnt lgkmcnt(2)
	v_bfe_u32 v47, v50, 16, 1
	ds_read2_b32 v[58:59], v45 offset0:52 offset1:60
	v_lshrrev_b32_e32 v46, 16, v46
	v_add3_u32 v47, v50, v47, s41
	ds_read2_b32 v[60:61], v45 offset0:117 offset1:125
	v_and_or_b32 v46, v47, s42, v46
	s_waitcnt lgkmcnt(3)
	v_bfe_u32 v47, v52, 16, 1
	ds_read2_b32 v[62:63], v45 offset0:182 offset1:190
	v_add3_u32 v47, v52, v47, s41
	s_waitcnt lgkmcnt(3)
	v_bfe_u32 v48, v56, 16, 1
	ds_read2_b32 v[64:65], v45 offset0:247 offset1:255
	v_lshrrev_b32_e32 v47, 16, v47
	v_add3_u32 v48, v56, v48, s41
	v_and_or_b32 v47, v48, s42, v47
	s_waitcnt lgkmcnt(3)
	v_bfe_u32 v48, v58, 16, 1
	v_add3_u32 v48, v58, v48, s41
	s_waitcnt lgkmcnt(2)
	v_bfe_u32 v49, v60, 16, 1
	v_lshrrev_b32_e32 v48, 16, v48
	v_add3_u32 v49, v60, v49, s41
	s_waitcnt lgkmcnt(1)
	v_bfe_u32 v45, v62, 16, 1
	v_and_or_b32 v48, v49, s42, v48
	v_add3_u32 v45, v62, v45, s41
	s_waitcnt lgkmcnt(0)
	v_bfe_u32 v49, v64, 16, 1
	v_lshrrev_b32_e32 v45, 16, v45
	v_add3_u32 v49, v64, v49, s41
	v_and_or_b32 v49, v49, s42, v45
	v_add_u32_e32 v45, s8, v16
	v_lshrrev_b32_e32 v50, 8, v45
	v_mul_i32_i24_e32 v66, 0x58, v50
	v_ashrrev_i32_e32 v67, 31, v66
	v_lshl_add_u64 v[66:67], v[66:67], 0, s[6:7]
	v_lshlrev_b64 v[66:67], 15, v[66:67]
	v_lshlrev_b32_e32 v45, 7, v45
	v_lshl_add_u64 v[66:67], s[0:1], 0, v[66:67]
	v_and_b32_e32 v68, 0x7f80, v45
	v_lshl_add_u64 v[66:67], v[66:67], 0, v[68:69]
	v_lshl_add_u64 v[66:67], v[66:67], 0, v[6:7]
	v_bfe_u32 v45, v55, 16, 1
	global_store_dwordx4 v[66:67], v[46:49], off sc0 sc1 nt
	v_add3_u32 v45, v55, v45, s41
	v_lshrrev_b32_e32 v45, 16, v45
	v_bfe_u32 v46, v51, 16, 1
	v_add3_u32 v46, v51, v46, s41
	v_and_or_b32 v46, v46, s42, v45
	v_bfe_u32 v45, v53, 16, 1
	v_add3_u32 v45, v53, v45, s41
	v_bfe_u32 v47, v57, 16, 1
	v_lshrrev_b32_e32 v45, 16, v45
	v_add3_u32 v47, v57, v47, s41
	v_and_or_b32 v47, v47, s42, v45
	v_bfe_u32 v45, v59, 16, 1
	v_add3_u32 v45, v59, v45, s41
	v_bfe_u32 v48, v61, 16, 1
	v_lshrrev_b32_e32 v45, 16, v45
	v_add3_u32 v48, v61, v48, s41
	v_and_or_b32 v48, v48, s42, v45
	v_bfe_u32 v45, v63, 16, 1
	v_add3_u32 v45, v63, v45, s41
	v_bfe_u32 v49, v65, 16, 1
	v_lshrrev_b32_e32 v45, 16, v45
	v_add3_u32 v49, v65, v49, s41
	v_and_or_b32 v49, v49, s42, v45
	v_add_u32_e32 v45, s8, v17
	v_lshrrev_b32_e32 v50, 8, v45
	v_mul_i32_i24_e32 v50, 0x58, v50
	v_ashrrev_i32_e32 v51, 31, v50
	v_lshl_add_u64 v[50:51], v[50:51], 0, s[6:7]
	v_lshlrev_b64 v[50:51], 15, v[50:51]
	v_lshlrev_b32_e32 v45, 7, v45
	v_lshl_add_u64 v[50:51], s[0:1], 0, v[50:51]
	v_and_b32_e32 v52, 0x7f80, v45
	v_mov_b32_e32 v53, v3
	v_lshl_add_u64 v[50:51], v[50:51], 0, v[52:53]
	v_lshl_add_u64 v[6:7], v[50:51], 0, v[6:7]
	global_store_dwordx4 v[6:7], v[46:49], off sc0 sc1 nt
	s_waitcnt lgkmcnt(0)
	s_mov_b64 s[8:9], 0
.LBB0_38:
	s_andn2_b64 vcc, exec, s[8:9]
	s_cbranch_vccnz .LBB0_40
	s_add_i32 s6, s47, 0xcf00
	s_and_b32 s10, s6, 0xffff
	s_mul_i32 s10, s10, 0xba2f
	s_lshr_b32 s10, s10, 23
	s_load_dwordx2 s[8:9], s[16:17], 0x90
	s_mul_i32 s11, s10, 0xb0
	s_sub_i32 s6, s6, s11
	s_lshl_b32 s6, s6, 6
	s_and_b32 s6, s6, 0xffc0
	s_lshl_b32 s11, s6, 2
	s_waitcnt lgkmcnt(0)
	s_add_u32 s8, s8, s11
	v_lshl_add_u32 v45, s10, 6, v5
	s_addc_u32 s9, s9, 0
	v_lshl_add_u64 v[6:7], s[8:9], 0, v[2:3]
	v_add_u32_e32 v48, 4, v45
	v_add_u32_e32 v54, 8, v45
	v_add_u32_e32 v56, 12, v45
	v_add_u32_e32 v62, 16, v45
	v_add_u32_e32 v64, 20, v45
	v_add_u32_e32 v70, 24, v45
	v_add_u32_e32 v72, 28, v45
	v_add_u32_e32 v82, 36, v45
	v_mad_i64_i32 v[46:47], s[8:9], v45, s43, v[6:7]
	v_mad_i64_i32 v[50:51], s[8:9], v48, s43, v[6:7]
	v_mad_i64_i32 v[54:55], s[8:9], v54, s43, v[6:7]
	v_mad_i64_i32 v[58:59], s[8:9], v56, s43, v[6:7]
	v_mad_i64_i32 v[62:63], s[8:9], v62, s43, v[6:7]
	v_mad_i64_i32 v[66:67], s[8:9], v64, s43, v[6:7]
	v_mad_i64_i32 v[70:71], s[8:9], v70, s43, v[6:7]
	v_mad_i64_i32 v[74:75], s[8:9], v72, s43, v[6:7]
	v_mad_i64_i32 v[82:83], s[8:9], v82, s43, v[6:7]
	v_add_u32_e32 v86, 40, v45
	global_load_dwordx4 v[46:49], v[46:47], off nt
	s_nop 0
	global_load_dwordx4 v[50:53], v[50:51], off nt
	s_nop 0
	global_load_dwordx4 v[54:57], v[54:55], off nt
	s_nop 0
	global_load_dwordx4 v[58:61], v[58:59], off nt
	s_nop 0
	global_load_dwordx4 v[62:65], v[62:63], off nt
	s_nop 0
	global_load_dwordx4 v[66:69], v[66:67], off nt
	s_nop 0
	global_load_dwordx4 v[70:73], v[70:71], off nt
	s_nop 0
	global_load_dwordx4 v[74:77], v[74:75], off nt
	v_mad_i64_i32 v[86:87], s[8:9], v86, s43, v[6:7]
	global_load_dwordx4 v[82:85], v[82:83], off nt
	v_add_u32_e32 v90, 44, v45
	global_load_dwordx4 v[86:89], v[86:87], off nt
	v_mad_i64_i32 v[90:91], s[8:9], v90, s43, v[6:7]
	global_load_dwordx4 v[90:93], v[90:91], off nt
	v_add_u32_e32 v94, 48, v45
	v_mad_i64_i32 v[94:95], s[8:9], v94, s43, v[6:7]
	global_load_dwordx4 v[94:97], v[94:95], off nt
	v_add_u32_e32 v98, 52, v45
	v_mad_i64_i32 v[98:99], s[8:9], v98, s43, v[6:7]
	global_load_dwordx4 v[98:101], v[98:99], off nt
	v_add_u32_e32 v102, 56, v45
	v_mad_i64_i32 v[102:103], s[8:9], v102, s43, v[6:7]
	v_add_u32_e32 v78, 32, v45
	global_load_dwordx4 v[102:105], v[102:103], off nt
	v_add_u32_e32 v45, 60, v45
	v_mad_i64_i32 v[78:79], s[8:9], v78, s43, v[6:7]
	v_mad_i64_i32 v[6:7], s[8:9], v45, s43, v[6:7]
	global_load_dwordx4 v[78:81], v[78:79], off nt
	v_add_u32_e32 v45, 0x400, v10
	global_load_dwordx4 v[106:109], v[6:7], off nt
	v_add_u32_e32 v6, 0x2498, v8
	s_lshl_b32 s8, s10, 15
	s_add_u32 s8, s14, s8
	s_addc_u32 s9, s15, 0
	s_waitcnt vmcnt(15)
	ds_write2_b32 v8, v46, v47 offset1:1
	ds_write2_b32 v8, v48, v49 offset0:2 offset1:3
	s_waitcnt vmcnt(14)
	ds_write2_b32 v26, v50, v51 offset1:1
	ds_write2_b32 v27, v52, v53 offset1:1
	s_waitcnt vmcnt(13)
	ds_write2_b32 v28, v54, v55 offset1:1
	ds_write2_b32 v29, v56, v57 offset1:1
	s_waitcnt vmcnt(12)
	ds_write2_b32 v30, v58, v59 offset1:1
	ds_write2_b32 v31, v60, v61 offset1:1
	s_waitcnt vmcnt(11)
	ds_write2_b32 v32, v62, v63 offset1:1
	ds_write2_b32 v33, v64, v65 offset1:1
	s_waitcnt vmcnt(10)
	ds_write2_b32 v34, v66, v67 offset1:1
	ds_write2_b32 v35, v68, v69 offset1:1
	s_waitcnt vmcnt(9)
	ds_write2_b32 v36, v70, v71 offset1:1
	ds_write2_b32 v37, v72, v73 offset1:1
	s_waitcnt vmcnt(8)
	ds_write2_b32 v38, v74, v75 offset1:1
	ds_write2_b32 v39, v76, v77 offset1:1
	s_waitcnt vmcnt(1)
	ds_write2_b32 v40, v78, v79 offset1:1
	ds_write2_b32 v41, v80, v81 offset1:1
	ds_write2_b32 v42, v82, v83 offset1:1
	ds_write2_b32 v6, v84, v85 offset1:1
	v_add_u32_e32 v6, 0x28a0, v8
	ds_write2_b32 v6, v86, v87 offset1:1
	v_add_u32_e32 v6, 0x28a8, v8
	ds_write2_b32 v6, v88, v89 offset1:1
	v_add_u32_e32 v6, 0x2cb0, v8
	ds_write2_b32 v6, v90, v91 offset1:1
	v_add_u32_e32 v6, 0x2cb8, v8
	ds_write2_b32 v6, v92, v93 offset1:1
	v_add_u32_e32 v6, 0x30c0, v8
	ds_write2_b32 v6, v94, v95 offset1:1
	v_add_u32_e32 v6, 0x30c8, v8
	ds_write2_b32 v6, v96, v97 offset1:1
	v_add_u32_e32 v6, 0x34d0, v8
	ds_write2_b32 v6, v98, v99 offset1:1
	v_add_u32_e32 v6, 0x34d8, v8
	ds_write2_b32 v6, v100, v101 offset1:1
	v_add_u32_e32 v6, 0x38e0, v8
	ds_write2_b32 v6, v102, v103 offset1:1
	v_add_u32_e32 v6, 0x38e8, v8
	ds_write2_b32 v6, v104, v105 offset1:1
	v_add_u32_e32 v6, 0x3cf0, v8
	s_waitcnt vmcnt(0)
	ds_write2_b32 v6, v106, v107 offset1:1
	v_add_u32_e32 v6, 0x3cf8, v8
	ds_write2_b32 v6, v108, v109 offset1:1
	s_waitcnt lgkmcnt(0)
	ds_read2_b32 v[50:51], v10 offset1:8
	ds_read2_b32 v[52:53], v10 offset0:65 offset1:73
	ds_read2_b32 v[54:55], v10 offset0:130 offset1:138
	ds_read2_b32 v[56:57], v10 offset0:195 offset1:203
	ds_read2_b32 v[58:59], v45 offset0:4 offset1:12
	s_waitcnt lgkmcnt(4)
	v_bfe_u32 v6, v50, 16, 1
	v_add3_u32 v6, v50, v6, s41
	s_waitcnt lgkmcnt(3)
	v_bfe_u32 v7, v52, 16, 1
	v_lshrrev_b32_e32 v6, 16, v6
	v_add3_u32 v7, v52, v7, s41
	ds_read2_b32 v[60:61], v45 offset0:69 offset1:77
	v_and_or_b32 v46, v7, s42, v6
	s_waitcnt lgkmcnt(3)
	v_bfe_u32 v6, v54, 16, 1
	v_add3_u32 v6, v54, v6, s41
	s_waitcnt lgkmcnt(2)
	v_bfe_u32 v7, v56, 16, 1
	ds_read2_b32 v[62:63], v45 offset0:134 offset1:142
	v_lshrrev_b32_e32 v6, 16, v6
	v_add3_u32 v7, v56, v7, s41
	ds_read2_b32 v[64:65], v45 offset0:199 offset1:207
	v_and_or_b32 v47, v7, s42, v6
	s_waitcnt lgkmcnt(3)
	v_bfe_u32 v6, v58, 16, 1
	v_add3_u32 v6, v58, v6, s41
	s_waitcnt lgkmcnt(2)
	v_bfe_u32 v7, v60, 16, 1
	v_lshrrev_b32_e32 v6, 16, v6
	v_add3_u32 v7, v60, v7, s41
	v_and_or_b32 v48, v7, s42, v6
	s_waitcnt lgkmcnt(1)
	v_bfe_u32 v6, v62, 16, 1
	v_add3_u32 v6, v62, v6, s41
	s_waitcnt lgkmcnt(0)
	v_bfe_u32 v7, v64, 16, 1
	v_lshrrev_b32_e32 v6, 16, v6
	v_add3_u32 v7, v64, v7, s41
	v_and_or_b32 v49, v7, s42, v6
	v_add_u32_e32 v6, s6, v9
	v_cmp_lt_i32_e32 vcc, s24, v6
	v_mov_b32_e32 v67, v3
	v_mov_b32_e32 v69, v3
	v_cndmask_b32_e32 v7, 0, v43, vcc
	v_add_u32_e32 v7, v7, v6
	v_cndmask_b32_e32 v50, 0, v44, vcc
	v_and_or_b32 v50, v6, s44, v50
	v_ashrrev_i32_e32 v6, 7, v7
	v_ashrrev_i32_e32 v7, 31, v6
	v_lshlrev_b64 v[6:7], 20, v[6:7]
	v_lshl_add_u64 v[6:7], s[8:9], 0, v[6:7]
	v_lshlrev_b32_e32 v66, 7, v50
	v_lshl_add_u64 v[66:67], v[6:7], 0, v[66:67]
	v_lshlrev_b32_e32 v6, 1, v4
	v_mov_b32_e32 v7, v3
	v_lshl_add_u64 v[66:67], v[66:67], 0, v[6:7]
	global_store_dwordx4 v[66:67], v[46:49], off sc0 sc1 nt
	v_bfe_u32 v50, v65, 16, 1
	v_add3_u32 v50, v65, v50, s41
	v_bfe_u32 v46, v51, 16, 1
	v_add3_u32 v46, v51, v46, s41
	v_bfe_u32 v47, v53, 16, 1
	v_lshrrev_b32_e32 v46, 16, v46
	v_add3_u32 v47, v53, v47, s41
	v_and_or_b32 v46, v47, s42, v46
	v_bfe_u32 v47, v55, 16, 1
	v_add3_u32 v47, v55, v47, s41
	v_bfe_u32 v48, v57, 16, 1
	v_lshrrev_b32_e32 v47, 16, v47
	v_add3_u32 v48, v57, v48, s41
	v_and_or_b32 v47, v48, s42, v47
	v_bfe_u32 v48, v59, 16, 1
	v_add3_u32 v48, v59, v48, s41
	v_bfe_u32 v49, v61, 16, 1
	v_lshrrev_b32_e32 v48, 16, v48
	v_add3_u32 v49, v61, v49, s41
	v_and_or_b32 v48, v49, s42, v48
	v_bfe_u32 v49, v63, 16, 1
	v_add3_u32 v49, v63, v49, s41
	v_lshrrev_b32_e32 v49, 16, v49
	v_and_or_b32 v49, v50, s42, v49
	v_add_u32_e32 v50, s6, v11
	v_cmp_lt_i32_e32 vcc, s24, v50
	v_mov_b32_e32 v53, v3
	ds_read2_b32 v[54:55], v10 offset0:16 offset1:24
	v_cndmask_b32_e32 v51, 0, v43, vcc
	v_add_u32_e32 v51, v51, v50
	v_cndmask_b32_e32 v52, 0, v44, vcc
	v_and_or_b32 v52, v50, s44, v52
	v_ashrrev_i32_e32 v50, 7, v51
	v_ashrrev_i32_e32 v51, 31, v50
	v_lshlrev_b64 v[50:51], 20, v[50:51]
	v_lshl_add_u64 v[50:51], s[8:9], 0, v[50:51]
	v_lshlrev_b32_e32 v52, 7, v52
	v_lshl_add_u64 v[50:51], v[50:51], 0, v[52:53]
	v_lshl_add_u64 v[50:51], v[50:51], 0, v[6:7]
	global_store_dwordx4 v[50:51], v[46:49], off sc0 sc1 nt
	ds_read2_b32 v[50:51], v10 offset0:81 offset1:89
	ds_read2_b32 v[52:53], v10 offset0:146 offset1:154
	ds_read2_b32 v[56:57], v10 offset0:211 offset1:219
	s_waitcnt lgkmcnt(3)
	v_bfe_u32 v46, v54, 16, 1
	v_add3_u32 v46, v54, v46, s41
	s_waitcnt lgkmcnt(2)
	v_bfe_u32 v47, v50, 16, 1
	ds_read2_b32 v[58:59], v45 offset0:20 offset1:28
	v_lshrrev_b32_e32 v46, 16, v46
	v_add3_u32 v47, v50, v47, s41
	ds_read2_b32 v[60:61], v45 offset0:85 offset1:93
	v_and_or_b32 v46, v47, s42, v46
	s_waitcnt lgkmcnt(3)
	v_bfe_u32 v47, v52, 16, 1
	v_add3_u32 v47, v52, v47, s41
	s_waitcnt lgkmcnt(2)
	v_bfe_u32 v48, v56, 16, 1
	ds_read2_b32 v[62:63], v45 offset0:150 offset1:158
	v_lshrrev_b32_e32 v47, 16, v47
	v_add3_u32 v48, v56, v48, s41
	ds_read2_b32 v[64:65], v45 offset0:215 offset1:223
	v_and_or_b32 v47, v48, s42, v47
	s_waitcnt lgkmcnt(3)
	v_bfe_u32 v48, v58, 16, 1
	v_add3_u32 v48, v58, v48, s41
	s_waitcnt lgkmcnt(2)
	v_bfe_u32 v49, v60, 16, 1
	v_lshrrev_b32_e32 v48, 16, v48
	v_add3_u32 v49, v60, v49, s41
	v_and_or_b32 v48, v49, s42, v48
	s_waitcnt lgkmcnt(1)
	v_bfe_u32 v49, v62, 16, 1
	v_add3_u32 v49, v62, v49, s41
	s_waitcnt lgkmcnt(0)
	v_bfe_u32 v50, v64, 16, 1
	v_lshrrev_b32_e32 v49, 16, v49
	v_add3_u32 v50, v64, v50, s41
	v_and_or_b32 v49, v50, s42, v49
	v_add_u32_e32 v50, s6, v12
	v_cmp_lt_i32_e32 vcc, s24, v50
	s_nop 1
	v_cndmask_b32_e32 v52, 0, v43, vcc
	v_add_u32_e32 v52, v52, v50
	v_ashrrev_i32_e32 v66, 7, v52
	v_cndmask_b32_e32 v54, 0, v44, vcc
	v_ashrrev_i32_e32 v67, 31, v66
	v_and_or_b32 v50, v50, s44, v54
	v_lshlrev_b64 v[66:67], 20, v[66:67]
	v_lshl_add_u64 v[66:67], s[8:9], 0, v[66:67]
	v_lshlrev_b32_e32 v68, 7, v50
	v_lshl_add_u64 v[66:67], v[66:67], 0, v[68:69]
	v_lshl_add_u64 v[66:67], v[66:67], 0, v[6:7]
	global_store_dwordx4 v[66:67], v[46:49], off sc0 sc1 nt
	v_bfe_u32 v50, v65, 16, 1
	v_add3_u32 v50, v65, v50, s41
	v_bfe_u32 v46, v55, 16, 1
	v_add3_u32 v46, v55, v46, s41
	v_bfe_u32 v47, v51, 16, 1
	v_lshrrev_b32_e32 v46, 16, v46
	v_add3_u32 v47, v51, v47, s41
	v_and_or_b32 v46, v47, s42, v46
	v_bfe_u32 v47, v53, 16, 1
	v_add3_u32 v47, v53, v47, s41
	v_bfe_u32 v48, v57, 16, 1
	v_lshrrev_b32_e32 v47, 16, v47
	v_add3_u32 v48, v57, v48, s41
	v_and_or_b32 v47, v48, s42, v47
	v_bfe_u32 v48, v59, 16, 1
	v_add3_u32 v48, v59, v48, s41
	v_bfe_u32 v49, v61, 16, 1
	v_lshrrev_b32_e32 v48, 16, v48
	v_add3_u32 v49, v61, v49, s41
	v_and_or_b32 v48, v49, s42, v48
	v_bfe_u32 v49, v63, 16, 1
	v_add3_u32 v49, v63, v49, s41
	v_lshrrev_b32_e32 v49, 16, v49
	v_and_or_b32 v49, v50, s42, v49
	v_add_u32_e32 v50, s6, v13
	v_cmp_lt_i32_e32 vcc, s24, v50
	v_mov_b32_e32 v53, v3
	ds_read2_b32 v[54:55], v10 offset0:32 offset1:40
	v_cndmask_b32_e32 v51, 0, v43, vcc
	v_add_u32_e32 v51, v51, v50
	v_cndmask_b32_e32 v52, 0, v44, vcc
	v_and_or_b32 v52, v50, s44, v52
	v_ashrrev_i32_e32 v50, 7, v51
	v_ashrrev_i32_e32 v51, 31, v50
	v_lshlrev_b64 v[50:51], 20, v[50:51]
	v_lshl_add_u64 v[50:51], s[8:9], 0, v[50:51]
	v_lshlrev_b32_e32 v52, 7, v52
	v_lshl_add_u64 v[50:51], v[50:51], 0, v[52:53]
	v_lshl_add_u64 v[50:51], v[50:51], 0, v[6:7]
	global_store_dwordx4 v[50:51], v[46:49], off sc0 sc1 nt
	ds_read2_b32 v[50:51], v10 offset0:97 offset1:105
	ds_read2_b32 v[52:53], v10 offset0:162 offset1:170
	ds_read2_b32 v[56:57], v10 offset0:227 offset1:235
	s_waitcnt lgkmcnt(3)
	v_bfe_u32 v46, v54, 16, 1
	v_add3_u32 v46, v54, v46, s41
	s_waitcnt lgkmcnt(2)
	v_bfe_u32 v47, v50, 16, 1
	ds_read2_b32 v[58:59], v45 offset0:36 offset1:44
	v_lshrrev_b32_e32 v46, 16, v46
	v_add3_u32 v47, v50, v47, s41
	ds_read2_b32 v[60:61], v45 offset0:101 offset1:109
	v_and_or_b32 v46, v47, s42, v46
	s_waitcnt lgkmcnt(3)
	v_bfe_u32 v47, v52, 16, 1
	v_add3_u32 v47, v52, v47, s41
	s_waitcnt lgkmcnt(2)
	v_bfe_u32 v48, v56, 16, 1
	ds_read2_b32 v[62:63], v45 offset0:166 offset1:174
	v_lshrrev_b32_e32 v47, 16, v47
	v_add3_u32 v48, v56, v48, s41
	ds_read2_b32 v[64:65], v45 offset0:231 offset1:239
	v_and_or_b32 v47, v48, s42, v47
	s_waitcnt lgkmcnt(3)
	v_bfe_u32 v48, v58, 16, 1
	v_add3_u32 v48, v58, v48, s41
	s_waitcnt lgkmcnt(2)
	v_bfe_u32 v49, v60, 16, 1
	v_lshrrev_b32_e32 v48, 16, v48
	v_add3_u32 v49, v60, v49, s41
	v_and_or_b32 v48, v49, s42, v48
	s_waitcnt lgkmcnt(1)
	v_bfe_u32 v49, v62, 16, 1
	v_add3_u32 v49, v62, v49, s41
	s_waitcnt lgkmcnt(0)
	v_bfe_u32 v50, v64, 16, 1
	v_lshrrev_b32_e32 v49, 16, v49
	v_add3_u32 v50, v64, v50, s41
	v_and_or_b32 v49, v50, s42, v49
	v_add_u32_e32 v50, s6, v14
	v_cmp_lt_i32_e32 vcc, s24, v50
	s_nop 1
	v_cndmask_b32_e32 v52, 0, v43, vcc
	v_add_u32_e32 v52, v52, v50
	v_ashrrev_i32_e32 v66, 7, v52
	v_cndmask_b32_e32 v54, 0, v44, vcc
	v_ashrrev_i32_e32 v67, 31, v66
	v_and_or_b32 v50, v50, s44, v54
	v_lshlrev_b64 v[66:67], 20, v[66:67]
	v_lshl_add_u64 v[66:67], s[8:9], 0, v[66:67]
	v_lshlrev_b32_e32 v68, 7, v50
	v_lshl_add_u64 v[66:67], v[66:67], 0, v[68:69]
	v_lshl_add_u64 v[66:67], v[66:67], 0, v[6:7]
	global_store_dwordx4 v[66:67], v[46:49], off sc0 sc1 nt
	v_bfe_u32 v50, v65, 16, 1
	v_add3_u32 v50, v65, v50, s41
	v_bfe_u32 v46, v55, 16, 1
	v_add3_u32 v46, v55, v46, s41
	v_bfe_u32 v47, v51, 16, 1
	v_lshrrev_b32_e32 v46, 16, v46
	v_add3_u32 v47, v51, v47, s41
	v_and_or_b32 v46, v47, s42, v46
	v_bfe_u32 v47, v53, 16, 1
	v_add3_u32 v47, v53, v47, s41
	v_bfe_u32 v48, v57, 16, 1
	v_lshrrev_b32_e32 v47, 16, v47
	v_add3_u32 v48, v57, v48, s41
	v_and_or_b32 v47, v48, s42, v47
	v_bfe_u32 v48, v59, 16, 1
	v_add3_u32 v48, v59, v48, s41
	v_bfe_u32 v49, v61, 16, 1
	v_lshrrev_b32_e32 v48, 16, v48
	v_add3_u32 v49, v61, v49, s41
	v_and_or_b32 v48, v49, s42, v48
	v_bfe_u32 v49, v63, 16, 1
	v_add3_u32 v49, v63, v49, s41
	v_lshrrev_b32_e32 v49, 16, v49
	v_and_or_b32 v49, v50, s42, v49
	v_add_u32_e32 v50, s6, v15
	v_cmp_lt_i32_e32 vcc, s24, v50
	v_mov_b32_e32 v53, v3
	ds_read2_b32 v[54:55], v10 offset0:48 offset1:56
	v_cndmask_b32_e32 v51, 0, v43, vcc
	v_add_u32_e32 v51, v51, v50
	v_cndmask_b32_e32 v52, 0, v44, vcc
	v_and_or_b32 v52, v50, s44, v52
	v_ashrrev_i32_e32 v50, 7, v51
	v_ashrrev_i32_e32 v51, 31, v50
	v_lshlrev_b64 v[50:51], 20, v[50:51]
	v_lshl_add_u64 v[50:51], s[8:9], 0, v[50:51]
	v_lshlrev_b32_e32 v52, 7, v52
	v_lshl_add_u64 v[50:51], v[50:51], 0, v[52:53]
	v_lshl_add_u64 v[50:51], v[50:51], 0, v[6:7]
	global_store_dwordx4 v[50:51], v[46:49], off sc0 sc1 nt
	ds_read2_b32 v[50:51], v10 offset0:113 offset1:121
	ds_read2_b32 v[52:53], v10 offset0:178 offset1:186
	ds_read2_b32 v[56:57], v10 offset0:243 offset1:251
	s_waitcnt lgkmcnt(3)
	v_bfe_u32 v46, v54, 16, 1
	v_add3_u32 v46, v54, v46, s41
	s_waitcnt lgkmcnt(2)
	v_bfe_u32 v47, v50, 16, 1
	ds_read2_b32 v[58:59], v45 offset0:52 offset1:60
	v_lshrrev_b32_e32 v46, 16, v46
	v_add3_u32 v47, v50, v47, s41
	ds_read2_b32 v[60:61], v45 offset0:117 offset1:125
	v_and_or_b32 v46, v47, s42, v46
	s_waitcnt lgkmcnt(3)
	v_bfe_u32 v47, v52, 16, 1
	ds_read2_b32 v[62:63], v45 offset0:182 offset1:190
	v_add3_u32 v47, v52, v47, s41
	s_waitcnt lgkmcnt(3)
	v_bfe_u32 v48, v56, 16, 1
	ds_read2_b32 v[64:65], v45 offset0:247 offset1:255
	v_lshrrev_b32_e32 v47, 16, v47
	v_add3_u32 v48, v56, v48, s41
	v_and_or_b32 v47, v48, s42, v47
	s_waitcnt lgkmcnt(3)
	v_bfe_u32 v48, v58, 16, 1
	v_add3_u32 v48, v58, v48, s41
	s_waitcnt lgkmcnt(2)
	v_bfe_u32 v49, v60, 16, 1
	v_lshrrev_b32_e32 v48, 16, v48
	v_add3_u32 v49, v60, v49, s41
	s_waitcnt lgkmcnt(1)
	v_bfe_u32 v45, v62, 16, 1
	v_and_or_b32 v48, v49, s42, v48
	v_add3_u32 v45, v62, v45, s41
	s_waitcnt lgkmcnt(0)
	v_bfe_u32 v49, v64, 16, 1
	v_lshrrev_b32_e32 v45, 16, v45
	v_add3_u32 v49, v64, v49, s41
	v_and_or_b32 v49, v49, s42, v45
	v_add_u32_e32 v45, s6, v16
	v_cmp_lt_i32_e32 vcc, s24, v45
	s_nop 1
	v_cndmask_b32_e32 v50, 0, v43, vcc
	v_add_u32_e32 v50, v50, v45
	v_ashrrev_i32_e32 v66, 7, v50
	v_cndmask_b32_e32 v52, 0, v44, vcc
	v_ashrrev_i32_e32 v67, 31, v66
	v_and_or_b32 v45, v45, s44, v52
	v_lshlrev_b64 v[66:67], 20, v[66:67]
	v_lshl_add_u64 v[66:67], s[8:9], 0, v[66:67]
	v_lshlrev_b32_e32 v68, 7, v45
	v_lshl_add_u64 v[66:67], v[66:67], 0, v[68:69]
	v_lshl_add_u64 v[66:67], v[66:67], 0, v[6:7]
	v_bfe_u32 v45, v55, 16, 1
	global_store_dwordx4 v[66:67], v[46:49], off sc0 sc1 nt
	v_add3_u32 v45, v55, v45, s41
	v_lshrrev_b32_e32 v45, 16, v45
	v_bfe_u32 v46, v51, 16, 1
	v_add3_u32 v46, v51, v46, s41
	v_and_or_b32 v46, v46, s42, v45
	v_bfe_u32 v45, v53, 16, 1
	v_add3_u32 v45, v53, v45, s41
	v_bfe_u32 v47, v57, 16, 1
	v_lshrrev_b32_e32 v45, 16, v45
	v_add3_u32 v47, v57, v47, s41
	v_and_or_b32 v47, v47, s42, v45
	v_bfe_u32 v45, v59, 16, 1
	v_add3_u32 v45, v59, v45, s41
	v_bfe_u32 v48, v61, 16, 1
	v_lshrrev_b32_e32 v45, 16, v45
	v_add3_u32 v48, v61, v48, s41
	v_and_or_b32 v48, v48, s42, v45
	v_bfe_u32 v45, v63, 16, 1
	v_add3_u32 v45, v63, v45, s41
	v_bfe_u32 v49, v65, 16, 1
	v_lshrrev_b32_e32 v45, 16, v45
	v_add3_u32 v49, v65, v49, s41
	v_and_or_b32 v49, v49, s42, v45
	v_add_u32_e32 v45, s6, v17
	v_cmp_lt_i32_e32 vcc, s24, v45
	v_mov_b32_e32 v53, v3
	s_nop 0
	v_cndmask_b32_e32 v50, 0, v43, vcc
	v_add_u32_e32 v50, v50, v45
	v_cndmask_b32_e32 v51, 0, v44, vcc
	v_ashrrev_i32_e32 v50, 7, v50
	v_and_or_b32 v45, v45, s44, v51
	v_ashrrev_i32_e32 v51, 31, v50
	v_lshlrev_b64 v[50:51], 20, v[50:51]
	v_lshl_add_u64 v[50:51], s[8:9], 0, v[50:51]
	v_lshlrev_b32_e32 v52, 7, v45
	v_lshl_add_u64 v[50:51], v[50:51], 0, v[52:53]
	v_lshl_add_u64 v[6:7], v[50:51], 0, v[6:7]
	global_store_dwordx4 v[6:7], v[46:49], off sc0 sc1 nt
	s_waitcnt lgkmcnt(0)

.LBB0_41:
	s_andn2_b64 vcc, exec, s[8:9]
	s_cbranch_vccnz .LBB0_43
	s_load_dwordx2 s[8:9], s[16:17], 0x58
	s_add_i32 s10, s22, 0x3400
	s_and_b32 s11, s10, 0x1fc0
	s_add_i32 s10, s20, 0xfff4c000
	s_and_b32 s10, s10, 0x7c0
	s_add_i32 s6, s47, 0xffffd300
	v_add_u32_e32 v6, s11, v5
	s_lshl_b32 s11, s10, 2
	s_waitcnt lgkmcnt(0)
	s_add_u32 s8, s8, s11
	s_addc_u32 s9, s9, 0
	v_ashrrev_i32_e32 v7, 31, v6
	v_lshl_add_u64 v[46:47], s[8:9], 0, v[2:3]
	v_lshlrev_b64 v[6:7], 13, v[6:7]
	v_lshl_add_u64 v[6:7], v[46:47], 0, v[6:7]
	v_add_co_u32_e32 v50, vcc, s25, v6
	v_add_u32_e32 v45, 0x400, v10
	s_nop 0
	v_addc_co_u32_e32 v51, vcc, 0, v7, vcc
	v_add_co_u32_e32 v54, vcc, s26, v6
	global_load_dwordx4 v[46:49], v[6:7], off nt
	s_nop 0
	global_load_dwordx4 v[50:53], v[50:51], off nt
	v_addc_co_u32_e32 v55, vcc, 0, v7, vcc
	v_add_co_u32_e32 v58, vcc, s27, v6
	s_lshr_b32 s6, s6, 5
	s_nop 0
	v_addc_co_u32_e32 v59, vcc, 0, v7, vcc
	v_add_co_u32_e32 v62, vcc, s28, v6
	global_load_dwordx4 v[54:57], v[54:55], off nt
	s_nop 0
	global_load_dwordx4 v[58:61], v[58:59], off nt
	v_addc_co_u32_e32 v63, vcc, 0, v7, vcc
	v_add_co_u32_e32 v66, vcc, s29, v6
	s_lshl_b64 s[8:9], s[6:7], 15
	s_nop 0
	v_addc_co_u32_e32 v67, vcc, 0, v7, vcc
	v_add_co_u32_e32 v70, vcc, s30, v6
	global_load_dwordx4 v[62:65], v[62:63], off nt
	s_nop 0
	global_load_dwordx4 v[66:69], v[66:67], off nt
	v_addc_co_u32_e32 v71, vcc, 0, v7, vcc
	v_add_co_u32_e32 v74, vcc, s31, v6
	s_nop 1
	v_addc_co_u32_e32 v75, vcc, 0, v7, vcc
	v_add_co_u32_e32 v78, vcc, s33, v6
	global_load_dwordx4 v[70:73], v[70:71], off nt
	s_nop 0
	global_load_dwordx4 v[74:77], v[74:75], off nt
	v_addc_co_u32_e32 v79, vcc, 0, v7, vcc
	v_add_co_u32_e32 v82, vcc, s34, v6
	s_nop 1
	v_addc_co_u32_e32 v83, vcc, 0, v7, vcc
	v_add_co_u32_e32 v86, vcc, s35, v6
	global_load_dwordx4 v[78:81], v[78:79], off nt
	s_nop 0
	global_load_dwordx4 v[82:85], v[82:83], off nt
	v_addc_co_u32_e32 v87, vcc, 0, v7, vcc
	v_add_co_u32_e32 v90, vcc, s36, v6
	s_nop 1
	v_addc_co_u32_e32 v91, vcc, 0, v7, vcc
	global_load_dwordx4 v[86:89], v[86:87], off nt
	s_nop 0
	global_load_dwordx4 v[90:93], v[90:91], off nt
	v_add_co_u32_e32 v94, vcc, s37, v6
	s_nop 1
	v_addc_co_u32_e32 v95, vcc, 0, v7, vcc
	global_load_dwordx4 v[94:97], v[94:95], off nt
	v_add_co_u32_e32 v98, vcc, s38, v6
	s_nop 1
	v_addc_co_u32_e32 v99, vcc, 0, v7, vcc
	global_load_dwordx4 v[98:101], v[98:99], off nt
	v_add_co_u32_e32 v102, vcc, s39, v6
	s_nop 1
	v_addc_co_u32_e32 v103, vcc, 0, v7, vcc
	global_load_dwordx4 v[102:105], v[102:103], off nt
	v_add_co_u32_e32 v6, vcc, s40, v6
	s_nop 1
	v_addc_co_u32_e32 v7, vcc, 0, v7, vcc
	global_load_dwordx4 v[106:109], v[6:7], off nt
	v_add_u32_e32 v6, 0x2498, v8
	s_waitcnt vmcnt(15)
	ds_write2_b32 v8, v46, v47 offset1:1
	ds_write2_b32 v8, v48, v49 offset0:2 offset1:3
	s_waitcnt vmcnt(14)
	ds_write2_b32 v26, v50, v51 offset1:1
	ds_write2_b32 v27, v52, v53 offset1:1
	s_waitcnt vmcnt(13)
	ds_write2_b32 v28, v54, v55 offset1:1
	ds_write2_b32 v29, v56, v57 offset1:1
	s_waitcnt vmcnt(12)
	ds_write2_b32 v30, v58, v59 offset1:1
	ds_write2_b32 v31, v60, v61 offset1:1
	s_waitcnt vmcnt(11)
	ds_write2_b32 v32, v62, v63 offset1:1
	ds_write2_b32 v33, v64, v65 offset1:1
	s_waitcnt vmcnt(10)
	ds_write2_b32 v34, v66, v67 offset1:1
	ds_write2_b32 v35, v68, v69 offset1:1
	s_waitcnt vmcnt(9)
	ds_write2_b32 v36, v70, v71 offset1:1
	ds_write2_b32 v37, v72, v73 offset1:1
	s_waitcnt vmcnt(8)
	ds_write2_b32 v38, v74, v75 offset1:1
	ds_write2_b32 v39, v76, v77 offset1:1
	s_waitcnt vmcnt(7)
	ds_write2_b32 v40, v78, v79 offset1:1
	ds_write2_b32 v41, v80, v81 offset1:1
	s_waitcnt vmcnt(6)
	ds_write2_b32 v42, v82, v83 offset1:1
	ds_write2_b32 v6, v84, v85 offset1:1
	v_add_u32_e32 v6, 0x28a0, v8
	v_mov_b32_e32 v67, v3
	v_mov_b32_e32 v69, v3
	s_waitcnt vmcnt(5)
	ds_write2_b32 v6, v86, v87 offset1:1
	v_add_u32_e32 v6, 0x28a8, v8
	ds_write2_b32 v6, v88, v89 offset1:1
	v_add_u32_e32 v6, 0x2cb0, v8
	s_waitcnt vmcnt(4)
	ds_write2_b32 v6, v90, v91 offset1:1
	v_add_u32_e32 v6, 0x2cb8, v8
	ds_write2_b32 v6, v92, v93 offset1:1
	v_add_u32_e32 v6, 0x30c0, v8
	s_waitcnt vmcnt(3)
	ds_write2_b32 v6, v94, v95 offset1:1
	v_add_u32_e32 v6, 0x30c8, v8
	ds_write2_b32 v6, v96, v97 offset1:1
	v_add_u32_e32 v6, 0x34d0, v8
	s_waitcnt vmcnt(2)
	ds_write2_b32 v6, v98, v99 offset1:1
	v_add_u32_e32 v6, 0x34d8, v8
	ds_write2_b32 v6, v100, v101 offset1:1
	v_add_u32_e32 v6, 0x38e0, v8
	s_waitcnt vmcnt(1)
	ds_write2_b32 v6, v102, v103 offset1:1
	v_add_u32_e32 v6, 0x38e8, v8
	ds_write2_b32 v6, v104, v105 offset1:1
	v_add_u32_e32 v6, 0x3cf0, v8
	s_waitcnt vmcnt(0)
	ds_write2_b32 v6, v106, v107 offset1:1
	v_add_u32_e32 v6, 0x3cf8, v8
	ds_write2_b32 v6, v108, v109 offset1:1
	s_waitcnt lgkmcnt(0)
	ds_read2_b32 v[50:51], v10 offset1:8
	ds_read2_b32 v[52:53], v10 offset0:65 offset1:73
	ds_read2_b32 v[54:55], v10 offset0:130 offset1:138
	ds_read2_b32 v[56:57], v10 offset0:195 offset1:203
	ds_read2_b32 v[58:59], v45 offset0:4 offset1:12
	s_waitcnt lgkmcnt(4)
	v_bfe_u32 v6, v50, 16, 1
	v_add3_u32 v6, v50, v6, s41
	s_waitcnt lgkmcnt(3)
	v_bfe_u32 v7, v52, 16, 1
	v_lshrrev_b32_e32 v6, 16, v6
	v_add3_u32 v7, v52, v7, s41
	ds_read2_b32 v[60:61], v45 offset0:69 offset1:77
	v_and_or_b32 v46, v7, s42, v6
	s_waitcnt lgkmcnt(3)
	v_bfe_u32 v6, v54, 16, 1
	v_add3_u32 v6, v54, v6, s41
	s_waitcnt lgkmcnt(2)
	v_bfe_u32 v7, v56, 16, 1
	ds_read2_b32 v[62:63], v45 offset0:134 offset1:142
	v_lshrrev_b32_e32 v6, 16, v6
	v_add3_u32 v7, v56, v7, s41
	ds_read2_b32 v[64:65], v45 offset0:199 offset1:207
	v_and_or_b32 v47, v7, s42, v6
	s_waitcnt lgkmcnt(3)
	v_bfe_u32 v6, v58, 16, 1
	v_add3_u32 v6, v58, v6, s41
	s_waitcnt lgkmcnt(2)
	v_bfe_u32 v7, v60, 16, 1
	v_lshrrev_b32_e32 v6, 16, v6
	v_add3_u32 v7, v60, v7, s41
	v_and_or_b32 v48, v7, s42, v6
	s_waitcnt lgkmcnt(1)
	v_bfe_u32 v6, v62, 16, 1
	v_add3_u32 v6, v62, v6, s41
	s_waitcnt lgkmcnt(0)
	v_bfe_u32 v7, v64, 16, 1
	v_lshrrev_b32_e32 v6, 16, v6
	v_add3_u32 v7, v64, v7, s41
	v_add_u32_e32 v50, s10, v9
	v_and_or_b32 v49, v7, s42, v6
	v_ashrrev_i32_e32 v6, 8, v50
	v_ashrrev_i32_e32 v7, 31, v6
	v_lshlrev_b64 v[6:7], 20, v[6:7]
	v_lshl_add_u64 v[6:7], s[2:3], 0, v[6:7]
	v_lshlrev_b32_e32 v50, 7, v50
	v_lshl_add_u64 v[6:7], v[6:7], 0, s[8:9]
	v_and_b32_e32 v66, 0x7f80, v50
	v_lshl_add_u64 v[66:67], v[6:7], 0, v[66:67]
	v_lshlrev_b32_e32 v6, 1, v4
	v_mov_b32_e32 v7, v3
	v_lshl_add_u64 v[66:67], v[66:67], 0, v[6:7]
	global_store_dwordx4 v[66:67], v[46:49], off sc0 sc1 nt
	v_bfe_u32 v50, v65, 16, 1
	v_add3_u32 v50, v65, v50, s41
	v_bfe_u32 v46, v51, 16, 1
	v_add3_u32 v46, v51, v46, s41
	v_bfe_u32 v47, v53, 16, 1
	v_lshrrev_b32_e32 v46, 16, v46
	v_add3_u32 v47, v53, v47, s41
	v_and_or_b32 v46, v47, s42, v46
	v_bfe_u32 v47, v55, 16, 1
	v_add3_u32 v47, v55, v47, s41
	v_bfe_u32 v48, v57, 16, 1
	v_lshrrev_b32_e32 v47, 16, v47
	v_add3_u32 v48, v57, v48, s41
	v_and_or_b32 v47, v48, s42, v47
	v_bfe_u32 v48, v59, 16, 1
	v_add3_u32 v48, v59, v48, s41
	v_bfe_u32 v49, v61, 16, 1
	v_lshrrev_b32_e32 v48, 16, v48
	v_add3_u32 v49, v61, v49, s41
	v_and_or_b32 v48, v49, s42, v48
	v_bfe_u32 v49, v63, 16, 1
	v_add3_u32 v49, v63, v49, s41
	v_lshrrev_b32_e32 v49, 16, v49
	v_add_u32_e32 v52, s10, v11
	v_and_or_b32 v49, v50, s42, v49
	v_ashrrev_i32_e32 v50, 8, v52
	v_ashrrev_i32_e32 v51, 31, v50
	v_lshlrev_b64 v[50:51], 20, v[50:51]
	v_lshl_add_u64 v[50:51], s[2:3], 0, v[50:51]
	v_lshlrev_b32_e32 v52, 7, v52
	v_lshl_add_u64 v[50:51], v[50:51], 0, s[8:9]
	v_and_b32_e32 v52, 0x7f80, v52
	v_mov_b32_e32 v53, v3
	v_lshl_add_u64 v[50:51], v[50:51], 0, v[52:53]
	ds_read2_b32 v[54:55], v10 offset0:16 offset1:24
	v_lshl_add_u64 v[50:51], v[50:51], 0, v[6:7]
	global_store_dwordx4 v[50:51], v[46:49], off sc0 sc1 nt
	ds_read2_b32 v[50:51], v10 offset0:81 offset1:89
	ds_read2_b32 v[52:53], v10 offset0:146 offset1:154
	ds_read2_b32 v[56:57], v10 offset0:211 offset1:219
	s_waitcnt lgkmcnt(3)
	v_bfe_u32 v46, v54, 16, 1
	v_add3_u32 v46, v54, v46, s41
	s_waitcnt lgkmcnt(2)
	v_bfe_u32 v47, v50, 16, 1
	ds_read2_b32 v[58:59], v45 offset0:20 offset1:28
	v_lshrrev_b32_e32 v46, 16, v46
	v_add3_u32 v47, v50, v47, s41
	ds_read2_b32 v[60:61], v45 offset0:85 offset1:93
	v_and_or_b32 v46, v47, s42, v46
	s_waitcnt lgkmcnt(3)
	v_bfe_u32 v47, v52, 16, 1
	v_add3_u32 v47, v52, v47, s41
	s_waitcnt lgkmcnt(2)
	v_bfe_u32 v48, v56, 16, 1
	ds_read2_b32 v[62:63], v45 offset0:150 offset1:158
	v_lshrrev_b32_e32 v47, 16, v47
	v_add3_u32 v48, v56, v48, s41
	ds_read2_b32 v[64:65], v45 offset0:215 offset1:223
	v_and_or_b32 v47, v48, s42, v47
	s_waitcnt lgkmcnt(3)
	v_bfe_u32 v48, v58, 16, 1
	v_add3_u32 v48, v58, v48, s41
	s_waitcnt lgkmcnt(2)
	v_bfe_u32 v49, v60, 16, 1
	v_lshrrev_b32_e32 v48, 16, v48
	v_add3_u32 v49, v60, v49, s41
	v_and_or_b32 v48, v49, s42, v48
	s_waitcnt lgkmcnt(1)
	v_bfe_u32 v49, v62, 16, 1
	v_add3_u32 v49, v62, v49, s41
	s_waitcnt lgkmcnt(0)
	v_bfe_u32 v50, v64, 16, 1
	v_lshrrev_b32_e32 v49, 16, v49
	v_add3_u32 v50, v64, v50, s41
	v_and_or_b32 v49, v50, s42, v49
	v_add_u32_e32 v50, s10, v12
	v_ashrrev_i32_e32 v66, 8, v50
	v_ashrrev_i32_e32 v67, 31, v66
	v_lshlrev_b64 v[66:67], 20, v[66:67]
	v_lshl_add_u64 v[66:67], s[2:3], 0, v[66:67]
	v_lshlrev_b32_e32 v50, 7, v50
	v_lshl_add_u64 v[66:67], v[66:67], 0, s[8:9]
	v_and_b32_e32 v68, 0x7f80, v50
	v_lshl_add_u64 v[66:67], v[66:67], 0, v[68:69]
	v_lshl_add_u64 v[66:67], v[66:67], 0, v[6:7]
	global_store_dwordx4 v[66:67], v[46:49], off sc0 sc1 nt
	v_bfe_u32 v50, v65, 16, 1
	v_add3_u32 v50, v65, v50, s41
	v_bfe_u32 v46, v55, 16, 1
	v_add3_u32 v46, v55, v46, s41
	v_bfe_u32 v47, v51, 16, 1
	v_lshrrev_b32_e32 v46, 16, v46
	v_add3_u32 v47, v51, v47, s41
	v_and_or_b32 v46, v47, s42, v46
	v_bfe_u32 v47, v53, 16, 1
	v_add3_u32 v47, v53, v47, s41
	v_bfe_u32 v48, v57, 16, 1
	v_lshrrev_b32_e32 v47, 16, v47
	v_add3_u32 v48, v57, v48, s41
	v_and_or_b32 v47, v48, s42, v47
	v_bfe_u32 v48, v59, 16, 1
	v_add3_u32 v48, v59, v48, s41
	v_bfe_u32 v49, v61, 16, 1
	v_lshrrev_b32_e32 v48, 16, v48
	v_add3_u32 v49, v61, v49, s41
	v_and_or_b32 v48, v49, s42, v48
	v_bfe_u32 v49, v63, 16, 1
	v_add3_u32 v49, v63, v49, s41
	v_lshrrev_b32_e32 v49, 16, v49
	v_add_u32_e32 v52, s10, v13
	v_and_or_b32 v49, v50, s42, v49
	v_ashrrev_i32_e32 v50, 8, v52
	v_ashrrev_i32_e32 v51, 31, v50
	v_lshlrev_b64 v[50:51], 20, v[50:51]
	v_lshl_add_u64 v[50:51], s[2:3], 0, v[50:51]
	v_lshlrev_b32_e32 v52, 7, v52
	v_lshl_add_u64 v[50:51], v[50:51], 0, s[8:9]
	v_and_b32_e32 v52, 0x7f80, v52
	v_mov_b32_e32 v53, v3
	v_lshl_add_u64 v[50:51], v[50:51], 0, v[52:53]
	ds_read2_b32 v[54:55], v10 offset0:32 offset1:40
	v_lshl_add_u64 v[50:51], v[50:51], 0, v[6:7]
	global_store_dwordx4 v[50:51], v[46:49], off sc0 sc1 nt
	ds_read2_b32 v[50:51], v10 offset0:97 offset1:105
	ds_read2_b32 v[52:53], v10 offset0:162 offset1:170
	ds_read2_b32 v[56:57], v10 offset0:227 offset1:235
	s_waitcnt lgkmcnt(3)
	v_bfe_u32 v46, v54, 16, 1
	v_add3_u32 v46, v54, v46, s41
	s_waitcnt lgkmcnt(2)
	v_bfe_u32 v47, v50, 16, 1
	ds_read2_b32 v[58:59], v45 offset0:36 offset1:44
	v_lshrrev_b32_e32 v46, 16, v46
	v_add3_u32 v47, v50, v47, s41
	ds_read2_b32 v[60:61], v45 offset0:101 offset1:109
	v_and_or_b32 v46, v47, s42, v46
	s_waitcnt lgkmcnt(3)
	v_bfe_u32 v47, v52, 16, 1
	v_add3_u32 v47, v52, v47, s41
	s_waitcnt lgkmcnt(2)
	v_bfe_u32 v48, v56, 16, 1
	ds_read2_b32 v[62:63], v45 offset0:166 offset1:174
	v_lshrrev_b32_e32 v47, 16, v47
	v_add3_u32 v48, v56, v48, s41
	ds_read2_b32 v[64:65], v45 offset0:231 offset1:239
	v_and_or_b32 v47, v48, s42, v47
	s_waitcnt lgkmcnt(3)
	v_bfe_u32 v48, v58, 16, 1
	v_add3_u32 v48, v58, v48, s41
	s_waitcnt lgkmcnt(2)
	v_bfe_u32 v49, v60, 16, 1
	v_lshrrev_b32_e32 v48, 16, v48
	v_add3_u32 v49, v60, v49, s41
	v_and_or_b32 v48, v49, s42, v48
	s_waitcnt lgkmcnt(1)
	v_bfe_u32 v49, v62, 16, 1
	v_add3_u32 v49, v62, v49, s41
	s_waitcnt lgkmcnt(0)
	v_bfe_u32 v50, v64, 16, 1
	v_lshrrev_b32_e32 v49, 16, v49
	v_add3_u32 v50, v64, v50, s41
	v_and_or_b32 v49, v50, s42, v49
	v_add_u32_e32 v50, s10, v14
	v_ashrrev_i32_e32 v66, 8, v50
	v_ashrrev_i32_e32 v67, 31, v66
	v_lshlrev_b64 v[66:67], 20, v[66:67]
	v_lshl_add_u64 v[66:67], s[2:3], 0, v[66:67]
	v_lshlrev_b32_e32 v50, 7, v50
	v_lshl_add_u64 v[66:67], v[66:67], 0, s[8:9]
	v_and_b32_e32 v68, 0x7f80, v50
	v_lshl_add_u64 v[66:67], v[66:67], 0, v[68:69]
	v_lshl_add_u64 v[66:67], v[66:67], 0, v[6:7]
	global_store_dwordx4 v[66:67], v[46:49], off sc0 sc1 nt
	v_bfe_u32 v50, v65, 16, 1
	v_add3_u32 v50, v65, v50, s41
	v_bfe_u32 v46, v55, 16, 1
	v_add3_u32 v46, v55, v46, s41
	v_bfe_u32 v47, v51, 16, 1
	v_lshrrev_b32_e32 v46, 16, v46
	v_add3_u32 v47, v51, v47, s41
	v_and_or_b32 v46, v47, s42, v46
	v_bfe_u32 v47, v53, 16, 1
	v_add3_u32 v47, v53, v47, s41
	v_bfe_u32 v48, v57, 16, 1
	v_lshrrev_b32_e32 v47, 16, v47
	v_add3_u32 v48, v57, v48, s41
	v_and_or_b32 v47, v48, s42, v47
	v_bfe_u32 v48, v59, 16, 1
	v_add3_u32 v48, v59, v48, s41
	v_bfe_u32 v49, v61, 16, 1
	v_lshrrev_b32_e32 v48, 16, v48
	v_add3_u32 v49, v61, v49, s41
	v_and_or_b32 v48, v49, s42, v48
	v_bfe_u32 v49, v63, 16, 1
	v_add3_u32 v49, v63, v49, s41
	v_lshrrev_b32_e32 v49, 16, v49
	v_add_u32_e32 v52, s10, v15
	v_and_or_b32 v49, v50, s42, v49
	v_ashrrev_i32_e32 v50, 8, v52
	v_ashrrev_i32_e32 v51, 31, v50
	v_lshlrev_b64 v[50:51], 20, v[50:51]
	v_lshl_add_u64 v[50:51], s[2:3], 0, v[50:51]
	v_lshlrev_b32_e32 v52, 7, v52
	v_lshl_add_u64 v[50:51], v[50:51], 0, s[8:9]
	v_and_b32_e32 v52, 0x7f80, v52
	v_mov_b32_e32 v53, v3
	v_lshl_add_u64 v[50:51], v[50:51], 0, v[52:53]
	ds_read2_b32 v[54:55], v10 offset0:48 offset1:56
	v_lshl_add_u64 v[50:51], v[50:51], 0, v[6:7]
	global_store_dwordx4 v[50:51], v[46:49], off sc0 sc1 nt
	ds_read2_b32 v[50:51], v10 offset0:113 offset1:121
	ds_read2_b32 v[52:53], v10 offset0:178 offset1:186
	ds_read2_b32 v[56:57], v10 offset0:243 offset1:251
	s_waitcnt lgkmcnt(3)
	v_bfe_u32 v46, v54, 16, 1
	v_add3_u32 v46, v54, v46, s41
	s_waitcnt lgkmcnt(2)
	v_bfe_u32 v47, v50, 16, 1
	ds_read2_b32 v[58:59], v45 offset0:52 offset1:60
	v_lshrrev_b32_e32 v46, 16, v46
	v_add3_u32 v47, v50, v47, s41
	ds_read2_b32 v[60:61], v45 offset0:117 offset1:125
	v_and_or_b32 v46, v47, s42, v46
	s_waitcnt lgkmcnt(3)
	v_bfe_u32 v47, v52, 16, 1
	ds_read2_b32 v[62:63], v45 offset0:182 offset1:190
	v_add3_u32 v47, v52, v47, s41
	s_waitcnt lgkmcnt(3)
	v_bfe_u32 v48, v56, 16, 1
	ds_read2_b32 v[64:65], v45 offset0:247 offset1:255
	v_lshrrev_b32_e32 v47, 16, v47
	v_add3_u32 v48, v56, v48, s41
	v_and_or_b32 v47, v48, s42, v47
	s_waitcnt lgkmcnt(3)
	v_bfe_u32 v48, v58, 16, 1
	v_add3_u32 v48, v58, v48, s41
	s_waitcnt lgkmcnt(2)
	v_bfe_u32 v49, v60, 16, 1
	v_lshrrev_b32_e32 v48, 16, v48
	v_add3_u32 v49, v60, v49, s41
	s_waitcnt lgkmcnt(1)
	v_bfe_u32 v45, v62, 16, 1
	v_and_or_b32 v48, v49, s42, v48
	v_add3_u32 v45, v62, v45, s41
	s_waitcnt lgkmcnt(0)
	v_bfe_u32 v49, v64, 16, 1
	v_lshrrev_b32_e32 v45, 16, v45
	v_add3_u32 v49, v64, v49, s41
	v_and_or_b32 v49, v49, s42, v45
	v_add_u32_e32 v45, s10, v16
	v_ashrrev_i32_e32 v66, 8, v45
	v_ashrrev_i32_e32 v67, 31, v66
	v_lshlrev_b64 v[66:67], 20, v[66:67]
	v_lshl_add_u64 v[66:67], s[2:3], 0, v[66:67]
	v_lshlrev_b32_e32 v45, 7, v45
	v_lshl_add_u64 v[66:67], v[66:67], 0, s[8:9]
	v_and_b32_e32 v68, 0x7f80, v45
	v_lshl_add_u64 v[66:67], v[66:67], 0, v[68:69]
	v_lshl_add_u64 v[66:67], v[66:67], 0, v[6:7]
	v_bfe_u32 v45, v55, 16, 1
	global_store_dwordx4 v[66:67], v[46:49], off sc0 sc1 nt
	v_add3_u32 v45, v55, v45, s41
	v_lshrrev_b32_e32 v45, 16, v45
	v_bfe_u32 v46, v51, 16, 1
	v_add3_u32 v46, v51, v46, s41
	v_and_or_b32 v46, v46, s42, v45
	v_bfe_u32 v45, v53, 16, 1
	v_add3_u32 v45, v53, v45, s41
	v_bfe_u32 v47, v57, 16, 1
	v_lshrrev_b32_e32 v45, 16, v45
	v_add3_u32 v47, v57, v47, s41
	v_and_or_b32 v47, v47, s42, v45
	v_bfe_u32 v45, v59, 16, 1
	v_add3_u32 v45, v59, v45, s41
	v_bfe_u32 v48, v61, 16, 1
	v_lshrrev_b32_e32 v45, 16, v45
	v_add3_u32 v48, v61, v48, s41
	v_and_or_b32 v48, v48, s42, v45
	v_bfe_u32 v45, v63, 16, 1
	v_add3_u32 v45, v63, v45, s41
	v_bfe_u32 v49, v65, 16, 1
	v_lshrrev_b32_e32 v45, 16, v45
	v_add3_u32 v49, v65, v49, s41
	v_and_or_b32 v49, v49, s42, v45
	v_add_u32_e32 v45, s10, v17
	v_ashrrev_i32_e32 v50, 8, v45
	v_ashrrev_i32_e32 v51, 31, v50
	v_lshlrev_b64 v[50:51], 20, v[50:51]
	v_lshl_add_u64 v[50:51], s[2:3], 0, v[50:51]
	v_lshlrev_b32_e32 v45, 7, v45
	v_lshl_add_u64 v[50:51], v[50:51], 0, s[8:9]
	v_and_b32_e32 v52, 0x7f80, v45
	v_mov_b32_e32 v53, v3
	v_lshl_add_u64 v[50:51], v[50:51], 0, v[52:53]
	v_lshl_add_u64 v[6:7], v[50:51], 0, v[6:7]
	global_store_dwordx4 v[6:7], v[46:49], off sc0 sc1 nt
	s_waitcnt lgkmcnt(0)

.LBB0_44:
	s_andn2_b64 vcc, exec, s[8:9]
	s_cbranch_vccnz .LBB0_46
	s_add_i32 s6, s47, 0xdf00
	s_and_b32 s10, s6, 0xffff
	s_mul_i32 s10, s10, 0xaaab
	s_lshr_b32 s10, s10, 22
	s_load_dwordx2 s[8:9], s[16:17], 0x50
	s_mul_i32 s11, s10, 0x60
	s_sub_i32 s6, s6, s11
	s_lshl_b32 s6, s6, 6
	s_and_b32 s6, s6, 0xffc0
	s_lshl_b32 s11, s6, 2
	s_waitcnt lgkmcnt(0)
	s_add_u32 s8, s8, s11
	v_lshl_add_u32 v45, s10, 6, v5
	s_addc_u32 s9, s9, 0
	v_lshl_add_u64 v[6:7], s[8:9], 0, v[2:3]
	v_add_u32_e32 v48, 4, v45
	v_add_u32_e32 v54, 8, v45
	v_add_u32_e32 v56, 12, v45
	v_add_u32_e32 v62, 16, v45
	v_add_u32_e32 v64, 20, v45
	v_add_u32_e32 v70, 24, v45
	v_add_u32_e32 v72, 28, v45
	v_add_u32_e32 v82, 36, v45
	v_mad_i64_i32 v[46:47], s[8:9], v45, s45, v[6:7]
	v_mad_i64_i32 v[50:51], s[8:9], v48, s45, v[6:7]
	v_mad_i64_i32 v[54:55], s[8:9], v54, s45, v[6:7]
	v_mad_i64_i32 v[58:59], s[8:9], v56, s45, v[6:7]
	v_mad_i64_i32 v[62:63], s[8:9], v62, s45, v[6:7]
	v_mad_i64_i32 v[66:67], s[8:9], v64, s45, v[6:7]
	v_mad_i64_i32 v[70:71], s[8:9], v70, s45, v[6:7]
	v_mad_i64_i32 v[74:75], s[8:9], v72, s45, v[6:7]
	v_mad_i64_i32 v[82:83], s[8:9], v82, s45, v[6:7]
	v_add_u32_e32 v86, 40, v45
	global_load_dwordx4 v[46:49], v[46:47], off nt
	s_nop 0
	global_load_dwordx4 v[50:53], v[50:51], off nt
	s_nop 0
	global_load_dwordx4 v[54:57], v[54:55], off nt
	s_nop 0
	global_load_dwordx4 v[58:61], v[58:59], off nt
	s_nop 0
	global_load_dwordx4 v[62:65], v[62:63], off nt
	s_nop 0
	global_load_dwordx4 v[66:69], v[66:67], off nt
	s_nop 0
	global_load_dwordx4 v[70:73], v[70:71], off nt
	s_nop 0
	global_load_dwordx4 v[74:77], v[74:75], off nt
	v_mad_i64_i32 v[86:87], s[8:9], v86, s45, v[6:7]
	global_load_dwordx4 v[82:85], v[82:83], off nt
	v_add_u32_e32 v90, 44, v45
	global_load_dwordx4 v[86:89], v[86:87], off nt
	v_mad_i64_i32 v[90:91], s[8:9], v90, s45, v[6:7]
	global_load_dwordx4 v[90:93], v[90:91], off nt
	v_add_u32_e32 v94, 48, v45
	v_mad_i64_i32 v[94:95], s[8:9], v94, s45, v[6:7]
	global_load_dwordx4 v[94:97], v[94:95], off nt
	v_add_u32_e32 v98, 52, v45
	v_mad_i64_i32 v[98:99], s[8:9], v98, s45, v[6:7]
	global_load_dwordx4 v[98:101], v[98:99], off nt
	v_add_u32_e32 v102, 56, v45
	v_mad_i64_i32 v[102:103], s[8:9], v102, s45, v[6:7]
	v_add_u32_e32 v78, 32, v45
	global_load_dwordx4 v[102:105], v[102:103], off nt
	v_add_u32_e32 v45, 60, v45
	v_mad_i64_i32 v[78:79], s[8:9], v78, s45, v[6:7]
	v_mad_i64_i32 v[6:7], s[8:9], v45, s45, v[6:7]
	global_load_dwordx4 v[78:81], v[78:79], off nt
	v_add_u32_e32 v45, 0x400, v10
	global_load_dwordx4 v[106:109], v[6:7], off nt
	v_add_u32_e32 v6, 0x2498, v8
	s_lshl_b32 s8, s10, 15
	s_add_u32 s8, s18, s8
	s_addc_u32 s9, s19, 0
	s_waitcnt vmcnt(15)
	ds_write2_b32 v8, v46, v47 offset1:1
	ds_write2_b32 v8, v48, v49 offset0:2 offset1:3
	s_waitcnt vmcnt(14)
	ds_write2_b32 v26, v50, v51 offset1:1
	ds_write2_b32 v27, v52, v53 offset1:1
	s_waitcnt vmcnt(13)
	ds_write2_b32 v28, v54, v55 offset1:1
	ds_write2_b32 v29, v56, v57 offset1:1
	s_waitcnt vmcnt(12)
	ds_write2_b32 v30, v58, v59 offset1:1
	ds_write2_b32 v31, v60, v61 offset1:1
	s_waitcnt vmcnt(11)
	ds_write2_b32 v32, v62, v63 offset1:1
	ds_write2_b32 v33, v64, v65 offset1:1
	s_waitcnt vmcnt(10)
	ds_write2_b32 v34, v66, v67 offset1:1
	ds_write2_b32 v35, v68, v69 offset1:1
	s_waitcnt vmcnt(9)
	ds_write2_b32 v36, v70, v71 offset1:1
	ds_write2_b32 v37, v72, v73 offset1:1
	s_waitcnt vmcnt(8)
	ds_write2_b32 v38, v74, v75 offset1:1
	ds_write2_b32 v39, v76, v77 offset1:1
	s_waitcnt vmcnt(1)
	ds_write2_b32 v40, v78, v79 offset1:1
	ds_write2_b32 v41, v80, v81 offset1:1
	ds_write2_b32 v42, v82, v83 offset1:1
	ds_write2_b32 v6, v84, v85 offset1:1
	v_add_u32_e32 v6, 0x28a0, v8
	ds_write2_b32 v6, v86, v87 offset1:1
	v_add_u32_e32 v6, 0x28a8, v8
	ds_write2_b32 v6, v88, v89 offset1:1
	v_add_u32_e32 v6, 0x2cb0, v8
	ds_write2_b32 v6, v90, v91 offset1:1
	v_add_u32_e32 v6, 0x2cb8, v8
	ds_write2_b32 v6, v92, v93 offset1:1
	v_add_u32_e32 v6, 0x30c0, v8
	ds_write2_b32 v6, v94, v95 offset1:1
	v_add_u32_e32 v6, 0x30c8, v8
	ds_write2_b32 v6, v96, v97 offset1:1
	v_add_u32_e32 v6, 0x34d0, v8
	ds_write2_b32 v6, v98, v99 offset1:1
	v_add_u32_e32 v6, 0x34d8, v8
	ds_write2_b32 v6, v100, v101 offset1:1
	v_add_u32_e32 v6, 0x38e0, v8
	ds_write2_b32 v6, v102, v103 offset1:1
	v_add_u32_e32 v6, 0x38e8, v8
	ds_write2_b32 v6, v104, v105 offset1:1
	v_add_u32_e32 v6, 0x3cf0, v8
	s_waitcnt vmcnt(0)
	ds_write2_b32 v6, v106, v107 offset1:1
	v_add_u32_e32 v6, 0x3cf8, v8
	ds_write2_b32 v6, v108, v109 offset1:1
	s_waitcnt lgkmcnt(0)
	ds_read2_b32 v[50:51], v10 offset1:8
	ds_read2_b32 v[52:53], v10 offset0:65 offset1:73
	ds_read2_b32 v[54:55], v10 offset0:130 offset1:138
	ds_read2_b32 v[56:57], v10 offset0:195 offset1:203
	ds_read2_b32 v[58:59], v45 offset0:4 offset1:12
	s_waitcnt lgkmcnt(4)
	v_bfe_u32 v6, v50, 16, 1
	v_add3_u32 v6, v50, v6, s41
	s_waitcnt lgkmcnt(3)
	v_bfe_u32 v7, v52, 16, 1
	v_lshrrev_b32_e32 v6, 16, v6
	v_add3_u32 v7, v52, v7, s41
	ds_read2_b32 v[60:61], v45 offset0:69 offset1:77
	v_and_or_b32 v46, v7, s42, v6
	s_waitcnt lgkmcnt(3)
	v_bfe_u32 v6, v54, 16, 1
	v_add3_u32 v6, v54, v6, s41
	s_waitcnt lgkmcnt(2)
	v_bfe_u32 v7, v56, 16, 1
	ds_read2_b32 v[62:63], v45 offset0:134 offset1:142
	v_lshrrev_b32_e32 v6, 16, v6
	v_add3_u32 v7, v56, v7, s41
	ds_read2_b32 v[64:65], v45 offset0:199 offset1:207
	v_and_or_b32 v47, v7, s42, v6
	s_waitcnt lgkmcnt(3)
	v_bfe_u32 v6, v58, 16, 1
	v_add3_u32 v6, v58, v6, s41
	s_waitcnt lgkmcnt(2)
	v_bfe_u32 v7, v60, 16, 1
	v_lshrrev_b32_e32 v6, 16, v6
	v_add3_u32 v7, v60, v7, s41
	v_and_or_b32 v48, v7, s42, v6
	s_waitcnt lgkmcnt(1)
	v_bfe_u32 v6, v62, 16, 1
	v_add3_u32 v6, v62, v6, s41
	s_waitcnt lgkmcnt(0)
	v_bfe_u32 v7, v64, 16, 1
	v_lshrrev_b32_e32 v6, 16, v6
	v_add3_u32 v7, v64, v7, s41
	v_and_or_b32 v49, v7, s42, v6
	v_add_u32_e32 v6, s6, v9
	v_and_b32_e32 v7, 0xffffffc0, v6
	v_add_u32_e32 v7, v7, v18
	v_cmp_gt_i32_e32 vcc, s46, v6
	v_mov_b32_e32 v67, v3
	v_mov_b32_e32 v69, v3
	v_cndmask_b32_e32 v50, v6, v7, vcc
	v_ashrrev_i32_e32 v6, 8, v50
	v_ashrrev_i32_e32 v7, 31, v6
	v_lshlrev_b64 v[6:7], 20, v[6:7]
	v_lshlrev_b32_e32 v50, 7, v50
	v_lshl_add_u64 v[6:7], s[8:9], 0, v[6:7]
	v_and_b32_e32 v66, 0x7f80, v50
	v_lshl_add_u64 v[66:67], v[6:7], 0, v[66:67]
	v_lshlrev_b32_e32 v6, 1, v4
	v_mov_b32_e32 v7, v3
	v_lshl_add_u64 v[66:67], v[66:67], 0, v[6:7]
	global_store_dwordx4 v[66:67], v[46:49], off sc0 sc1 nt
	v_bfe_u32 v50, v65, 16, 1
	v_add3_u32 v50, v65, v50, s41
	v_bfe_u32 v46, v51, 16, 1
	v_add3_u32 v46, v51, v46, s41
	v_bfe_u32 v47, v53, 16, 1
	v_lshrrev_b32_e32 v46, 16, v46
	v_add3_u32 v47, v53, v47, s41
	v_and_or_b32 v46, v47, s42, v46
	v_bfe_u32 v47, v55, 16, 1
	v_add3_u32 v47, v55, v47, s41
	v_bfe_u32 v48, v57, 16, 1
	v_lshrrev_b32_e32 v47, 16, v47
	v_add3_u32 v48, v57, v48, s41
	v_and_or_b32 v47, v48, s42, v47
	v_bfe_u32 v48, v59, 16, 1
	v_add3_u32 v48, v59, v48, s41
	v_bfe_u32 v49, v61, 16, 1
	v_lshrrev_b32_e32 v48, 16, v48
	v_add3_u32 v49, v61, v49, s41
	v_and_or_b32 v48, v49, s42, v48
	v_bfe_u32 v49, v63, 16, 1
	v_add3_u32 v49, v63, v49, s41
	v_lshrrev_b32_e32 v49, 16, v49
	v_and_or_b32 v49, v50, s42, v49
	v_add_u32_e32 v50, s6, v11
	v_and_b32_e32 v51, 0xffffffc0, v50
	v_add_u32_e32 v51, v51, v19
	v_cmp_gt_i32_e32 vcc, s46, v50
	v_mov_b32_e32 v53, v3
	ds_read2_b32 v[54:55], v10 offset0:16 offset1:24
	v_cndmask_b32_e32 v52, v50, v51, vcc
	v_ashrrev_i32_e32 v50, 8, v52
	v_ashrrev_i32_e32 v51, 31, v50
	v_lshlrev_b64 v[50:51], 20, v[50:51]
	v_lshlrev_b32_e32 v52, 7, v52
	v_lshl_add_u64 v[50:51], s[8:9], 0, v[50:51]
	v_and_b32_e32 v52, 0x7f80, v52
	v_lshl_add_u64 v[50:51], v[50:51], 0, v[52:53]
	v_lshl_add_u64 v[50:51], v[50:51], 0, v[6:7]
	global_store_dwordx4 v[50:51], v[46:49], off sc0 sc1 nt
	ds_read2_b32 v[50:51], v10 offset0:81 offset1:89
	ds_read2_b32 v[52:53], v10 offset0:146 offset1:154
	ds_read2_b32 v[56:57], v10 offset0:211 offset1:219
	s_waitcnt lgkmcnt(3)
	v_bfe_u32 v46, v54, 16, 1
	v_add3_u32 v46, v54, v46, s41
	s_waitcnt lgkmcnt(2)
	v_bfe_u32 v47, v50, 16, 1
	ds_read2_b32 v[58:59], v45 offset0:20 offset1:28
	v_lshrrev_b32_e32 v46, 16, v46
	v_add3_u32 v47, v50, v47, s41
	ds_read2_b32 v[60:61], v45 offset0:85 offset1:93
	v_and_or_b32 v46, v47, s42, v46
	s_waitcnt lgkmcnt(3)
	v_bfe_u32 v47, v52, 16, 1
	v_add3_u32 v47, v52, v47, s41
	s_waitcnt lgkmcnt(2)
	v_bfe_u32 v48, v56, 16, 1
	ds_read2_b32 v[62:63], v45 offset0:150 offset1:158
	v_lshrrev_b32_e32 v47, 16, v47
	v_add3_u32 v48, v56, v48, s41
	ds_read2_b32 v[64:65], v45 offset0:215 offset1:223
	v_and_or_b32 v47, v48, s42, v47
	s_waitcnt lgkmcnt(3)
	v_bfe_u32 v48, v58, 16, 1
	v_add3_u32 v48, v58, v48, s41
	s_waitcnt lgkmcnt(2)
	v_bfe_u32 v49, v60, 16, 1
	v_lshrrev_b32_e32 v48, 16, v48
	v_add3_u32 v49, v60, v49, s41
	v_and_or_b32 v48, v49, s42, v48
	s_waitcnt lgkmcnt(1)
	v_bfe_u32 v49, v62, 16, 1
	v_add3_u32 v49, v62, v49, s41
	s_waitcnt lgkmcnt(0)
	v_bfe_u32 v50, v64, 16, 1
	v_lshrrev_b32_e32 v49, 16, v49
	v_add3_u32 v50, v64, v50, s41
	v_and_or_b32 v49, v50, s42, v49
	v_add_u32_e32 v50, s6, v12
	v_and_b32_e32 v52, 0xffffffc0, v50
	v_add_u32_e32 v52, v52, v20
	v_cmp_gt_i32_e32 vcc, s46, v50
	s_nop 1
	v_cndmask_b32_e32 v50, v50, v52, vcc
	v_ashrrev_i32_e32 v66, 8, v50
	v_ashrrev_i32_e32 v67, 31, v66
	v_lshlrev_b64 v[66:67], 20, v[66:67]
	v_lshlrev_b32_e32 v50, 7, v50
	v_lshl_add_u64 v[66:67], s[8:9], 0, v[66:67]
	v_and_b32_e32 v68, 0x7f80, v50
	v_lshl_add_u64 v[66:67], v[66:67], 0, v[68:69]
	v_lshl_add_u64 v[66:67], v[66:67], 0, v[6:7]
	global_store_dwordx4 v[66:67], v[46:49], off sc0 sc1 nt
	v_bfe_u32 v50, v65, 16, 1
	v_add3_u32 v50, v65, v50, s41
	v_bfe_u32 v46, v55, 16, 1
	v_add3_u32 v46, v55, v46, s41
	v_bfe_u32 v47, v51, 16, 1
	v_lshrrev_b32_e32 v46, 16, v46
	v_add3_u32 v47, v51, v47, s41
	v_and_or_b32 v46, v47, s42, v46
	v_bfe_u32 v47, v53, 16, 1
	v_add3_u32 v47, v53, v47, s41
	v_bfe_u32 v48, v57, 16, 1
	v_lshrrev_b32_e32 v47, 16, v47
	v_add3_u32 v48, v57, v48, s41
	v_and_or_b32 v47, v48, s42, v47
	v_bfe_u32 v48, v59, 16, 1
	v_add3_u32 v48, v59, v48, s41
	v_bfe_u32 v49, v61, 16, 1
	v_lshrrev_b32_e32 v48, 16, v48
	v_add3_u32 v49, v61, v49, s41
	v_and_or_b32 v48, v49, s42, v48
	v_bfe_u32 v49, v63, 16, 1
	v_add3_u32 v49, v63, v49, s41
	v_lshrrev_b32_e32 v49, 16, v49
	v_and_or_b32 v49, v50, s42, v49
	v_add_u32_e32 v50, s6, v13
	v_and_b32_e32 v51, 0xffffffc0, v50
	v_add_u32_e32 v51, v51, v21
	v_cmp_gt_i32_e32 vcc, s46, v50
	v_mov_b32_e32 v53, v3
	ds_read2_b32 v[54:55], v10 offset0:32 offset1:40
	v_cndmask_b32_e32 v52, v50, v51, vcc
	v_ashrrev_i32_e32 v50, 8, v52
	v_ashrrev_i32_e32 v51, 31, v50
	v_lshlrev_b64 v[50:51], 20, v[50:51]
	v_lshlrev_b32_e32 v52, 7, v52
	v_lshl_add_u64 v[50:51], s[8:9], 0, v[50:51]
	v_and_b32_e32 v52, 0x7f80, v52
	v_lshl_add_u64 v[50:51], v[50:51], 0, v[52:53]
	v_lshl_add_u64 v[50:51], v[50:51], 0, v[6:7]
	global_store_dwordx4 v[50:51], v[46:49], off sc0 sc1 nt
	ds_read2_b32 v[50:51], v10 offset0:97 offset1:105
	ds_read2_b32 v[52:53], v10 offset0:162 offset1:170
	ds_read2_b32 v[56:57], v10 offset0:227 offset1:235
	s_waitcnt lgkmcnt(3)
	v_bfe_u32 v46, v54, 16, 1
	v_add3_u32 v46, v54, v46, s41
	s_waitcnt lgkmcnt(2)
	v_bfe_u32 v47, v50, 16, 1
	ds_read2_b32 v[58:59], v45 offset0:36 offset1:44
	v_lshrrev_b32_e32 v46, 16, v46
	v_add3_u32 v47, v50, v47, s41
	ds_read2_b32 v[60:61], v45 offset0:101 offset1:109
	v_and_or_b32 v46, v47, s42, v46
	s_waitcnt lgkmcnt(3)
	v_bfe_u32 v47, v52, 16, 1
	v_add3_u32 v47, v52, v47, s41
	s_waitcnt lgkmcnt(2)
	v_bfe_u32 v48, v56, 16, 1
	ds_read2_b32 v[62:63], v45 offset0:166 offset1:174
	v_lshrrev_b32_e32 v47, 16, v47
	v_add3_u32 v48, v56, v48, s41
	ds_read2_b32 v[64:65], v45 offset0:231 offset1:239
	v_and_or_b32 v47, v48, s42, v47
	s_waitcnt lgkmcnt(3)
	v_bfe_u32 v48, v58, 16, 1
	v_add3_u32 v48, v58, v48, s41
	s_waitcnt lgkmcnt(2)
	v_bfe_u32 v49, v60, 16, 1
	v_lshrrev_b32_e32 v48, 16, v48
	v_add3_u32 v49, v60, v49, s41
	v_and_or_b32 v48, v49, s42, v48
	s_waitcnt lgkmcnt(1)
	v_bfe_u32 v49, v62, 16, 1
	v_add3_u32 v49, v62, v49, s41
	s_waitcnt lgkmcnt(0)
	v_bfe_u32 v50, v64, 16, 1
	v_lshrrev_b32_e32 v49, 16, v49
	v_add3_u32 v50, v64, v50, s41
	v_and_or_b32 v49, v50, s42, v49
	v_add_u32_e32 v50, s6, v14
	v_and_b32_e32 v52, 0xffffffc0, v50
	v_add_u32_e32 v52, v52, v22
	v_cmp_gt_i32_e32 vcc, s46, v50
	s_nop 1
	v_cndmask_b32_e32 v50, v50, v52, vcc
	v_ashrrev_i32_e32 v66, 8, v50
	v_ashrrev_i32_e32 v67, 31, v66
	v_lshlrev_b64 v[66:67], 20, v[66:67]
	v_lshlrev_b32_e32 v50, 7, v50
	v_lshl_add_u64 v[66:67], s[8:9], 0, v[66:67]
	v_and_b32_e32 v68, 0x7f80, v50
	v_lshl_add_u64 v[66:67], v[66:67], 0, v[68:69]
	v_lshl_add_u64 v[66:67], v[66:67], 0, v[6:7]
	global_store_dwordx4 v[66:67], v[46:49], off sc0 sc1 nt
	v_bfe_u32 v50, v65, 16, 1
	v_add3_u32 v50, v65, v50, s41
	v_bfe_u32 v46, v55, 16, 1
	v_add3_u32 v46, v55, v46, s41
	v_bfe_u32 v47, v51, 16, 1
	v_lshrrev_b32_e32 v46, 16, v46
	v_add3_u32 v47, v51, v47, s41
	v_and_or_b32 v46, v47, s42, v46
	v_bfe_u32 v47, v53, 16, 1
	v_add3_u32 v47, v53, v47, s41
	v_bfe_u32 v48, v57, 16, 1
	v_lshrrev_b32_e32 v47, 16, v47
	v_add3_u32 v48, v57, v48, s41
	v_and_or_b32 v47, v48, s42, v47
	v_bfe_u32 v48, v59, 16, 1
	v_add3_u32 v48, v59, v48, s41
	v_bfe_u32 v49, v61, 16, 1
	v_lshrrev_b32_e32 v48, 16, v48
	v_add3_u32 v49, v61, v49, s41
	v_and_or_b32 v48, v49, s42, v48
	v_bfe_u32 v49, v63, 16, 1
	v_add3_u32 v49, v63, v49, s41
	v_lshrrev_b32_e32 v49, 16, v49
	v_and_or_b32 v49, v50, s42, v49
	v_add_u32_e32 v50, s6, v15
	v_and_b32_e32 v51, 0xffffffc0, v50
	v_add_u32_e32 v51, v51, v23
	v_cmp_gt_i32_e32 vcc, s46, v50
	v_mov_b32_e32 v53, v3
	ds_read2_b32 v[54:55], v10 offset0:48 offset1:56
	v_cndmask_b32_e32 v52, v50, v51, vcc
	v_ashrrev_i32_e32 v50, 8, v52
	v_ashrrev_i32_e32 v51, 31, v50
	v_lshlrev_b64 v[50:51], 20, v[50:51]
	v_lshlrev_b32_e32 v52, 7, v52
	v_lshl_add_u64 v[50:51], s[8:9], 0, v[50:51]
	v_and_b32_e32 v52, 0x7f80, v52
	v_lshl_add_u64 v[50:51], v[50:51], 0, v[52:53]
	v_lshl_add_u64 v[50:51], v[50:51], 0, v[6:7]
	global_store_dwordx4 v[50:51], v[46:49], off sc0 sc1 nt
	ds_read2_b32 v[50:51], v10 offset0:113 offset1:121
	ds_read2_b32 v[52:53], v10 offset0:178 offset1:186
	ds_read2_b32 v[56:57], v10 offset0:243 offset1:251
	s_waitcnt lgkmcnt(3)
	v_bfe_u32 v46, v54, 16, 1
	v_add3_u32 v46, v54, v46, s41
	s_waitcnt lgkmcnt(2)
	v_bfe_u32 v47, v50, 16, 1
	ds_read2_b32 v[58:59], v45 offset0:52 offset1:60
	v_lshrrev_b32_e32 v46, 16, v46
	v_add3_u32 v47, v50, v47, s41
	ds_read2_b32 v[60:61], v45 offset0:117 offset1:125
	v_and_or_b32 v46, v47, s42, v46
	s_waitcnt lgkmcnt(3)
	v_bfe_u32 v47, v52, 16, 1
	ds_read2_b32 v[62:63], v45 offset0:182 offset1:190
	v_add3_u32 v47, v52, v47, s41
	s_waitcnt lgkmcnt(3)
	v_bfe_u32 v48, v56, 16, 1
	ds_read2_b32 v[64:65], v45 offset0:247 offset1:255
	v_lshrrev_b32_e32 v47, 16, v47
	v_add3_u32 v48, v56, v48, s41
	v_and_or_b32 v47, v48, s42, v47
	s_waitcnt lgkmcnt(3)
	v_bfe_u32 v48, v58, 16, 1
	v_add3_u32 v48, v58, v48, s41
	s_waitcnt lgkmcnt(2)
	v_bfe_u32 v49, v60, 16, 1
	v_lshrrev_b32_e32 v48, 16, v48
	v_add3_u32 v49, v60, v49, s41
	s_waitcnt lgkmcnt(1)
	v_bfe_u32 v45, v62, 16, 1
	v_and_or_b32 v48, v49, s42, v48
	v_add3_u32 v45, v62, v45, s41
	s_waitcnt lgkmcnt(0)
	v_bfe_u32 v49, v64, 16, 1
	v_lshrrev_b32_e32 v45, 16, v45
	v_add3_u32 v49, v64, v49, s41
	v_and_or_b32 v49, v49, s42, v45
	v_add_u32_e32 v45, s6, v16
	v_and_b32_e32 v50, 0xffffffc0, v45
	v_add_u32_e32 v50, v50, v24
	v_cmp_gt_i32_e32 vcc, s46, v45
	s_nop 1
	v_cndmask_b32_e32 v45, v45, v50, vcc
	v_ashrrev_i32_e32 v66, 8, v45
	v_ashrrev_i32_e32 v67, 31, v66
	v_lshlrev_b64 v[66:67], 20, v[66:67]
	v_lshlrev_b32_e32 v45, 7, v45
	v_lshl_add_u64 v[66:67], s[8:9], 0, v[66:67]
	v_and_b32_e32 v68, 0x7f80, v45
	v_lshl_add_u64 v[66:67], v[66:67], 0, v[68:69]
	v_lshl_add_u64 v[66:67], v[66:67], 0, v[6:7]
	v_bfe_u32 v45, v55, 16, 1
	global_store_dwordx4 v[66:67], v[46:49], off sc0 sc1 nt
	v_add3_u32 v45, v55, v45, s41
	v_lshrrev_b32_e32 v45, 16, v45
	v_bfe_u32 v46, v51, 16, 1
	v_add3_u32 v46, v51, v46, s41
	v_and_or_b32 v46, v46, s42, v45
	v_bfe_u32 v45, v53, 16, 1
	v_add3_u32 v45, v53, v45, s41
	v_bfe_u32 v47, v57, 16, 1
	v_lshrrev_b32_e32 v45, 16, v45
	v_add3_u32 v47, v57, v47, s41
	v_and_or_b32 v47, v47, s42, v45
	v_bfe_u32 v45, v59, 16, 1
	v_add3_u32 v45, v59, v45, s41
	v_bfe_u32 v48, v61, 16, 1
	v_lshrrev_b32_e32 v45, 16, v45
	v_add3_u32 v48, v61, v48, s41
	v_and_or_b32 v48, v48, s42, v45
	v_bfe_u32 v45, v63, 16, 1
	v_add3_u32 v45, v63, v45, s41
	v_bfe_u32 v49, v65, 16, 1
	v_lshrrev_b32_e32 v45, 16, v45
	v_add3_u32 v49, v65, v49, s41
	v_and_or_b32 v49, v49, s42, v45
	v_add_u32_e32 v45, s6, v17
	v_and_b32_e32 v50, 0xffffffc0, v45
	v_add_u32_e32 v50, v50, v25
	v_cmp_gt_i32_e32 vcc, s46, v45
	v_mov_b32_e32 v53, v3
	s_nop 0
	v_cndmask_b32_e32 v45, v45, v50, vcc
	v_ashrrev_i32_e32 v50, 8, v45
	v_ashrrev_i32_e32 v51, 31, v50
	v_lshlrev_b64 v[50:51], 20, v[50:51]
	v_lshlrev_b32_e32 v45, 7, v45
	v_lshl_add_u64 v[50:51], s[8:9], 0, v[50:51]
	v_and_b32_e32 v52, 0x7f80, v45
	v_lshl_add_u64 v[50:51], v[50:51], 0, v[52:53]
	v_lshl_add_u64 v[6:7], v[50:51], 0, v[6:7]
	global_store_dwordx4 v[6:7], v[46:49], off sc0 sc1 nt
	s_waitcnt lgkmcnt(0)

.LBB0_47:
	s_andn2_b64 vcc, exec, s[8:9]
	s_cbranch_vccnz .LBB0_49
	s_load_dwordx2 s[10:11], s[16:17], 0x48
	s_add_i32 s8, s22, 0x6200
	s_and_b32 s9, s8, 0x1fc0
	s_add_i32 s8, s20, 0xfffa8000
	s_and_b32 s8, s8, 0x7c0
	s_add_i32 s6, s47, 0xffffea00
	v_add_u32_e32 v6, s9, v5
	s_lshl_b32 s9, s8, 2
	s_waitcnt lgkmcnt(0)
	s_add_u32 s10, s10, s9
	s_addc_u32 s11, s11, 0
	v_ashrrev_i32_e32 v7, 31, v6
	v_lshl_add_u64 v[46:47], s[10:11], 0, v[2:3]
	v_lshlrev_b64 v[6:7], 13, v[6:7]
	v_lshl_add_u64 v[6:7], v[46:47], 0, v[6:7]
	v_add_co_u32_e32 v50, vcc, s25, v6
	v_add_u32_e32 v45, 0x400, v10
	s_nop 0
	v_addc_co_u32_e32 v51, vcc, 0, v7, vcc
	v_add_co_u32_e32 v54, vcc, s26, v6
	global_load_dwordx4 v[46:49], v[6:7], off nt
	s_nop 0
	global_load_dwordx4 v[50:53], v[50:51], off nt
	v_addc_co_u32_e32 v55, vcc, 0, v7, vcc
	v_add_co_u32_e32 v58, vcc, s27, v6
	s_lshr_b32 s6, s6, 5
	s_nop 0
	v_addc_co_u32_e32 v59, vcc, 0, v7, vcc
	v_add_co_u32_e32 v62, vcc, s28, v6
	global_load_dwordx4 v[54:57], v[54:55], off nt
	s_nop 0
	global_load_dwordx4 v[58:61], v[58:59], off nt
	v_addc_co_u32_e32 v63, vcc, 0, v7, vcc
	v_add_co_u32_e32 v66, vcc, s29, v6
	s_nop 1
	v_addc_co_u32_e32 v67, vcc, 0, v7, vcc
	v_add_co_u32_e32 v70, vcc, s30, v6
	global_load_dwordx4 v[62:65], v[62:63], off nt
	s_nop 0
	global_load_dwordx4 v[66:69], v[66:67], off nt
	v_addc_co_u32_e32 v71, vcc, 0, v7, vcc
	v_add_co_u32_e32 v74, vcc, s31, v6
	s_nop 1
	v_addc_co_u32_e32 v75, vcc, 0, v7, vcc
	v_add_co_u32_e32 v78, vcc, s33, v6
	global_load_dwordx4 v[70:73], v[70:71], off nt
	s_nop 0
	global_load_dwordx4 v[74:77], v[74:75], off nt
	v_addc_co_u32_e32 v79, vcc, 0, v7, vcc
	v_add_co_u32_e32 v82, vcc, s34, v6
	s_nop 1
	v_addc_co_u32_e32 v83, vcc, 0, v7, vcc
	v_add_co_u32_e32 v86, vcc, s35, v6
	global_load_dwordx4 v[78:81], v[78:79], off nt
	s_nop 0
	global_load_dwordx4 v[82:85], v[82:83], off nt
	v_addc_co_u32_e32 v87, vcc, 0, v7, vcc
	v_add_co_u32_e32 v90, vcc, s36, v6
	s_nop 1
	v_addc_co_u32_e32 v91, vcc, 0, v7, vcc
	global_load_dwordx4 v[86:89], v[86:87], off nt
	s_nop 0
	global_load_dwordx4 v[90:93], v[90:91], off nt
	v_add_co_u32_e32 v94, vcc, s37, v6
	s_nop 1
	v_addc_co_u32_e32 v95, vcc, 0, v7, vcc
	global_load_dwordx4 v[94:97], v[94:95], off nt
	v_add_co_u32_e32 v98, vcc, s38, v6
	s_nop 1
	v_addc_co_u32_e32 v99, vcc, 0, v7, vcc
	global_load_dwordx4 v[98:101], v[98:99], off nt
	v_add_co_u32_e32 v102, vcc, s39, v6
	s_nop 1
	v_addc_co_u32_e32 v103, vcc, 0, v7, vcc
	global_load_dwordx4 v[102:105], v[102:103], off nt
	v_add_co_u32_e32 v6, vcc, s40, v6
	s_nop 1
	v_addc_co_u32_e32 v7, vcc, 0, v7, vcc
	global_load_dwordx4 v[106:109], v[6:7], off nt
	v_add_u32_e32 v6, 0x2498, v8
	s_waitcnt vmcnt(15)
	ds_write2_b32 v8, v46, v47 offset1:1
	ds_write2_b32 v8, v48, v49 offset0:2 offset1:3
	s_waitcnt vmcnt(14)
	ds_write2_b32 v26, v50, v51 offset1:1
	ds_write2_b32 v27, v52, v53 offset1:1
	s_waitcnt vmcnt(13)
	ds_write2_b32 v28, v54, v55 offset1:1
	ds_write2_b32 v29, v56, v57 offset1:1
	s_waitcnt vmcnt(12)
	ds_write2_b32 v30, v58, v59 offset1:1
	ds_write2_b32 v31, v60, v61 offset1:1
	s_waitcnt vmcnt(11)
	ds_write2_b32 v32, v62, v63 offset1:1
	ds_write2_b32 v33, v64, v65 offset1:1
	s_waitcnt vmcnt(10)
	ds_write2_b32 v34, v66, v67 offset1:1
	ds_write2_b32 v35, v68, v69 offset1:1
	s_waitcnt vmcnt(9)
	ds_write2_b32 v36, v70, v71 offset1:1
	ds_write2_b32 v37, v72, v73 offset1:1
	s_waitcnt vmcnt(8)
	ds_write2_b32 v38, v74, v75 offset1:1
	ds_write2_b32 v39, v76, v77 offset1:1
	s_waitcnt vmcnt(7)
	ds_write2_b32 v40, v78, v79 offset1:1
	ds_write2_b32 v41, v80, v81 offset1:1
	s_waitcnt vmcnt(6)
	ds_write2_b32 v42, v82, v83 offset1:1
	ds_write2_b32 v6, v84, v85 offset1:1
	v_add_u32_e32 v6, 0x28a0, v8
	v_mov_b32_e32 v67, v3
	v_mov_b32_e32 v69, v3
	s_waitcnt vmcnt(5)
	ds_write2_b32 v6, v86, v87 offset1:1
	v_add_u32_e32 v6, 0x28a8, v8
	ds_write2_b32 v6, v88, v89 offset1:1
	v_add_u32_e32 v6, 0x2cb0, v8
	s_waitcnt vmcnt(4)
	ds_write2_b32 v6, v90, v91 offset1:1
	v_add_u32_e32 v6, 0x2cb8, v8
	ds_write2_b32 v6, v92, v93 offset1:1
	v_add_u32_e32 v6, 0x30c0, v8
	s_waitcnt vmcnt(3)
	ds_write2_b32 v6, v94, v95 offset1:1
	v_add_u32_e32 v6, 0x30c8, v8
	ds_write2_b32 v6, v96, v97 offset1:1
	v_add_u32_e32 v6, 0x34d0, v8
	s_waitcnt vmcnt(2)
	ds_write2_b32 v6, v98, v99 offset1:1
	v_add_u32_e32 v6, 0x34d8, v8
	ds_write2_b32 v6, v100, v101 offset1:1
	v_add_u32_e32 v6, 0x38e0, v8
	s_waitcnt vmcnt(1)
	ds_write2_b32 v6, v102, v103 offset1:1
	v_add_u32_e32 v6, 0x38e8, v8
	ds_write2_b32 v6, v104, v105 offset1:1
	v_add_u32_e32 v6, 0x3cf0, v8
	s_waitcnt vmcnt(0)
	ds_write2_b32 v6, v106, v107 offset1:1
	v_add_u32_e32 v6, 0x3cf8, v8
	ds_write2_b32 v6, v108, v109 offset1:1
	s_waitcnt lgkmcnt(0)
	ds_read2_b32 v[50:51], v10 offset1:8
	ds_read2_b32 v[52:53], v10 offset0:65 offset1:73
	ds_read2_b32 v[54:55], v10 offset0:130 offset1:138
	ds_read2_b32 v[56:57], v10 offset0:195 offset1:203
	ds_read2_b32 v[58:59], v45 offset0:4 offset1:12
	s_waitcnt lgkmcnt(4)
	v_bfe_u32 v6, v50, 16, 1
	v_add3_u32 v6, v50, v6, s41
	s_waitcnt lgkmcnt(3)
	v_bfe_u32 v7, v52, 16, 1
	v_lshrrev_b32_e32 v6, 16, v6
	v_add3_u32 v7, v52, v7, s41
	ds_read2_b32 v[60:61], v45 offset0:69 offset1:77
	v_and_or_b32 v46, v7, s42, v6
	s_waitcnt lgkmcnt(3)
	v_bfe_u32 v6, v54, 16, 1
	v_add3_u32 v6, v54, v6, s41
	s_waitcnt lgkmcnt(2)
	v_bfe_u32 v7, v56, 16, 1
	ds_read2_b32 v[62:63], v45 offset0:134 offset1:142
	v_lshrrev_b32_e32 v6, 16, v6
	v_add3_u32 v7, v56, v7, s41
	ds_read2_b32 v[64:65], v45 offset0:199 offset1:207
	v_and_or_b32 v47, v7, s42, v6
	s_waitcnt lgkmcnt(3)
	v_bfe_u32 v6, v58, 16, 1
	v_add3_u32 v6, v58, v6, s41
	s_waitcnt lgkmcnt(2)
	v_bfe_u32 v7, v60, 16, 1
	v_lshrrev_b32_e32 v6, 16, v6
	v_add3_u32 v7, v60, v7, s41
	v_and_or_b32 v48, v7, s42, v6
	s_waitcnt lgkmcnt(1)
	v_bfe_u32 v6, v62, 16, 1
	v_add3_u32 v6, v62, v6, s41
	s_waitcnt lgkmcnt(0)
	v_bfe_u32 v7, v64, 16, 1
	v_lshrrev_b32_e32 v6, 16, v6
	v_add3_u32 v7, v64, v7, s41
	v_add_u32_e32 v50, s8, v9
	v_and_or_b32 v49, v7, s42, v6
	v_lshrrev_b32_e32 v6, 8, v50
	v_mul_i32_i24_e32 v6, 0x58, v6
	v_ashrrev_i32_e32 v7, 31, v6
	v_lshl_add_u64 v[6:7], v[6:7], 0, s[6:7]
	v_lshlrev_b64 v[6:7], 15, v[6:7]
	v_lshlrev_b32_e32 v50, 7, v50
	v_lshl_add_u64 v[6:7], s[4:5], 0, v[6:7]
	v_and_b32_e32 v66, 0x7f80, v50
	v_lshl_add_u64 v[66:67], v[6:7], 0, v[66:67]
	v_lshlrev_b32_e32 v6, 1, v4
	v_mov_b32_e32 v7, v3
	v_lshl_add_u64 v[66:67], v[66:67], 0, v[6:7]
	global_store_dwordx4 v[66:67], v[46:49], off sc0 sc1 nt
	v_bfe_u32 v50, v65, 16, 1
	v_add3_u32 v50, v65, v50, s41
	v_bfe_u32 v46, v51, 16, 1
	v_add3_u32 v46, v51, v46, s41
	v_bfe_u32 v47, v53, 16, 1
	v_lshrrev_b32_e32 v46, 16, v46
	v_add3_u32 v47, v53, v47, s41
	v_and_or_b32 v46, v47, s42, v46
	v_bfe_u32 v47, v55, 16, 1
	v_add3_u32 v47, v55, v47, s41
	v_bfe_u32 v48, v57, 16, 1
	v_lshrrev_b32_e32 v47, 16, v47
	v_add3_u32 v48, v57, v48, s41
	v_and_or_b32 v47, v48, s42, v47
	v_bfe_u32 v48, v59, 16, 1
	v_add3_u32 v48, v59, v48, s41
	v_bfe_u32 v49, v61, 16, 1
	v_lshrrev_b32_e32 v48, 16, v48
	v_add3_u32 v49, v61, v49, s41
	v_and_or_b32 v48, v49, s42, v48
	v_bfe_u32 v49, v63, 16, 1
	v_add3_u32 v49, v63, v49, s41
	v_lshrrev_b32_e32 v49, 16, v49
	v_add_u32_e32 v52, s8, v11
	v_and_or_b32 v49, v50, s42, v49
	v_lshrrev_b32_e32 v50, 8, v52
	v_mul_i32_i24_e32 v50, 0x58, v50
	v_ashrrev_i32_e32 v51, 31, v50
	v_lshl_add_u64 v[50:51], v[50:51], 0, s[6:7]
	v_lshlrev_b64 v[50:51], 15, v[50:51]
	v_lshlrev_b32_e32 v52, 7, v52
	v_lshl_add_u64 v[50:51], s[4:5], 0, v[50:51]
	v_and_b32_e32 v52, 0x7f80, v52
	v_mov_b32_e32 v53, v3
	v_lshl_add_u64 v[50:51], v[50:51], 0, v[52:53]
	ds_read2_b32 v[54:55], v10 offset0:16 offset1:24
	v_lshl_add_u64 v[50:51], v[50:51], 0, v[6:7]
	global_store_dwordx4 v[50:51], v[46:49], off sc0 sc1 nt
	ds_read2_b32 v[50:51], v10 offset0:81 offset1:89
	ds_read2_b32 v[52:53], v10 offset0:146 offset1:154
	ds_read2_b32 v[56:57], v10 offset0:211 offset1:219
	s_waitcnt lgkmcnt(3)
	v_bfe_u32 v46, v54, 16, 1
	v_add3_u32 v46, v54, v46, s41
	s_waitcnt lgkmcnt(2)
	v_bfe_u32 v47, v50, 16, 1
	ds_read2_b32 v[58:59], v45 offset0:20 offset1:28
	v_lshrrev_b32_e32 v46, 16, v46
	v_add3_u32 v47, v50, v47, s41
	ds_read2_b32 v[60:61], v45 offset0:85 offset1:93
	v_and_or_b32 v46, v47, s42, v46
	s_waitcnt lgkmcnt(3)
	v_bfe_u32 v47, v52, 16, 1
	v_add3_u32 v47, v52, v47, s41
	s_waitcnt lgkmcnt(2)
	v_bfe_u32 v48, v56, 16, 1
	ds_read2_b32 v[62:63], v45 offset0:150 offset1:158
	v_lshrrev_b32_e32 v47, 16, v47
	v_add3_u32 v48, v56, v48, s41
	ds_read2_b32 v[64:65], v45 offset0:215 offset1:223
	v_and_or_b32 v47, v48, s42, v47
	s_waitcnt lgkmcnt(3)
	v_bfe_u32 v48, v58, 16, 1
	v_add3_u32 v48, v58, v48, s41
	s_waitcnt lgkmcnt(2)
	v_bfe_u32 v49, v60, 16, 1
	v_lshrrev_b32_e32 v48, 16, v48
	v_add3_u32 v49, v60, v49, s41
	v_and_or_b32 v48, v49, s42, v48
	s_waitcnt lgkmcnt(1)
	v_bfe_u32 v49, v62, 16, 1
	v_add3_u32 v49, v62, v49, s41
	s_waitcnt lgkmcnt(0)
	v_bfe_u32 v50, v64, 16, 1
	v_lshrrev_b32_e32 v49, 16, v49
	v_add3_u32 v50, v64, v50, s41
	v_and_or_b32 v49, v50, s42, v49
	v_add_u32_e32 v50, s8, v12
	v_lshrrev_b32_e32 v52, 8, v50
	v_mul_i32_i24_e32 v66, 0x58, v52
	v_ashrrev_i32_e32 v67, 31, v66
	v_lshl_add_u64 v[66:67], v[66:67], 0, s[6:7]
	v_lshlrev_b64 v[66:67], 15, v[66:67]
	v_lshlrev_b32_e32 v50, 7, v50
	v_lshl_add_u64 v[66:67], s[4:5], 0, v[66:67]
	v_and_b32_e32 v68, 0x7f80, v50
	v_lshl_add_u64 v[66:67], v[66:67], 0, v[68:69]
	v_lshl_add_u64 v[66:67], v[66:67], 0, v[6:7]
	global_store_dwordx4 v[66:67], v[46:49], off sc0 sc1 nt
	v_bfe_u32 v50, v65, 16, 1
	v_add3_u32 v50, v65, v50, s41
	v_bfe_u32 v46, v55, 16, 1
	v_add3_u32 v46, v55, v46, s41
	v_bfe_u32 v47, v51, 16, 1
	v_lshrrev_b32_e32 v46, 16, v46
	v_add3_u32 v47, v51, v47, s41
	v_and_or_b32 v46, v47, s42, v46
	v_bfe_u32 v47, v53, 16, 1
	v_add3_u32 v47, v53, v47, s41
	v_bfe_u32 v48, v57, 16, 1
	v_lshrrev_b32_e32 v47, 16, v47
	v_add3_u32 v48, v57, v48, s41
	v_and_or_b32 v47, v48, s42, v47
	v_bfe_u32 v48, v59, 16, 1
	v_add3_u32 v48, v59, v48, s41
	v_bfe_u32 v49, v61, 16, 1
	v_lshrrev_b32_e32 v48, 16, v48
	v_add3_u32 v49, v61, v49, s41
	v_and_or_b32 v48, v49, s42, v48
	v_bfe_u32 v49, v63, 16, 1
	v_add3_u32 v49, v63, v49, s41
	v_lshrrev_b32_e32 v49, 16, v49
	v_add_u32_e32 v52, s8, v13
	v_and_or_b32 v49, v50, s42, v49
	v_lshrrev_b32_e32 v50, 8, v52
	v_mul_i32_i24_e32 v50, 0x58, v50
	v_ashrrev_i32_e32 v51, 31, v50
	v_lshl_add_u64 v[50:51], v[50:51], 0, s[6:7]
	v_lshlrev_b64 v[50:51], 15, v[50:51]
	v_lshlrev_b32_e32 v52, 7, v52
	v_lshl_add_u64 v[50:51], s[4:5], 0, v[50:51]
	v_and_b32_e32 v52, 0x7f80, v52
	v_mov_b32_e32 v53, v3
	v_lshl_add_u64 v[50:51], v[50:51], 0, v[52:53]
	ds_read2_b32 v[54:55], v10 offset0:32 offset1:40
	v_lshl_add_u64 v[50:51], v[50:51], 0, v[6:7]
	global_store_dwordx4 v[50:51], v[46:49], off sc0 sc1 nt
	ds_read2_b32 v[50:51], v10 offset0:97 offset1:105
	ds_read2_b32 v[52:53], v10 offset0:162 offset1:170
	ds_read2_b32 v[56:57], v10 offset0:227 offset1:235
	s_waitcnt lgkmcnt(3)
	v_bfe_u32 v46, v54, 16, 1
	v_add3_u32 v46, v54, v46, s41
	s_waitcnt lgkmcnt(2)
	v_bfe_u32 v47, v50, 16, 1
	ds_read2_b32 v[58:59], v45 offset0:36 offset1:44
	v_lshrrev_b32_e32 v46, 16, v46
	v_add3_u32 v47, v50, v47, s41
	ds_read2_b32 v[60:61], v45 offset0:101 offset1:109
	v_and_or_b32 v46, v47, s42, v46
	s_waitcnt lgkmcnt(3)
	v_bfe_u32 v47, v52, 16, 1
	v_add3_u32 v47, v52, v47, s41
	s_waitcnt lgkmcnt(2)
	v_bfe_u32 v48, v56, 16, 1
	ds_read2_b32 v[62:63], v45 offset0:166 offset1:174
	v_lshrrev_b32_e32 v47, 16, v47
	v_add3_u32 v48, v56, v48, s41
	ds_read2_b32 v[64:65], v45 offset0:231 offset1:239
	v_and_or_b32 v47, v48, s42, v47
	s_waitcnt lgkmcnt(3)
	v_bfe_u32 v48, v58, 16, 1
	v_add3_u32 v48, v58, v48, s41
	s_waitcnt lgkmcnt(2)
	v_bfe_u32 v49, v60, 16, 1
	v_lshrrev_b32_e32 v48, 16, v48
	v_add3_u32 v49, v60, v49, s41
	v_and_or_b32 v48, v49, s42, v48
	s_waitcnt lgkmcnt(1)
	v_bfe_u32 v49, v62, 16, 1
	v_add3_u32 v49, v62, v49, s41
	s_waitcnt lgkmcnt(0)
	v_bfe_u32 v50, v64, 16, 1
	v_lshrrev_b32_e32 v49, 16, v49
	v_add3_u32 v50, v64, v50, s41
	v_and_or_b32 v49, v50, s42, v49
	v_add_u32_e32 v50, s8, v14
	v_lshrrev_b32_e32 v52, 8, v50
	v_mul_i32_i24_e32 v66, 0x58, v52
	v_ashrrev_i32_e32 v67, 31, v66
	v_lshl_add_u64 v[66:67], v[66:67], 0, s[6:7]
	v_lshlrev_b64 v[66:67], 15, v[66:67]
	v_lshlrev_b32_e32 v50, 7, v50
	v_lshl_add_u64 v[66:67], s[4:5], 0, v[66:67]
	v_and_b32_e32 v68, 0x7f80, v50
	v_lshl_add_u64 v[66:67], v[66:67], 0, v[68:69]
	v_lshl_add_u64 v[66:67], v[66:67], 0, v[6:7]
	global_store_dwordx4 v[66:67], v[46:49], off sc0 sc1 nt
	v_bfe_u32 v50, v65, 16, 1
	v_add3_u32 v50, v65, v50, s41
	v_bfe_u32 v46, v55, 16, 1
	v_add3_u32 v46, v55, v46, s41
	v_bfe_u32 v47, v51, 16, 1
	v_lshrrev_b32_e32 v46, 16, v46
	v_add3_u32 v47, v51, v47, s41
	v_and_or_b32 v46, v47, s42, v46
	v_bfe_u32 v47, v53, 16, 1
	v_add3_u32 v47, v53, v47, s41
	v_bfe_u32 v48, v57, 16, 1
	v_lshrrev_b32_e32 v47, 16, v47
	v_add3_u32 v48, v57, v48, s41
	v_and_or_b32 v47, v48, s42, v47
	v_bfe_u32 v48, v59, 16, 1
	v_add3_u32 v48, v59, v48, s41
	v_bfe_u32 v49, v61, 16, 1
	v_lshrrev_b32_e32 v48, 16, v48
	v_add3_u32 v49, v61, v49, s41
	v_and_or_b32 v48, v49, s42, v48
	v_bfe_u32 v49, v63, 16, 1
	v_add3_u32 v49, v63, v49, s41
	v_lshrrev_b32_e32 v49, 16, v49
	v_add_u32_e32 v52, s8, v15
	v_and_or_b32 v49, v50, s42, v49
	v_lshrrev_b32_e32 v50, 8, v52
	v_mul_i32_i24_e32 v50, 0x58, v50
	v_ashrrev_i32_e32 v51, 31, v50
	v_lshl_add_u64 v[50:51], v[50:51], 0, s[6:7]
	v_lshlrev_b64 v[50:51], 15, v[50:51]
	v_lshlrev_b32_e32 v52, 7, v52
	v_lshl_add_u64 v[50:51], s[4:5], 0, v[50:51]
	v_and_b32_e32 v52, 0x7f80, v52
	v_mov_b32_e32 v53, v3
	v_lshl_add_u64 v[50:51], v[50:51], 0, v[52:53]
	ds_read2_b32 v[54:55], v10 offset0:48 offset1:56
	v_lshl_add_u64 v[50:51], v[50:51], 0, v[6:7]
	global_store_dwordx4 v[50:51], v[46:49], off sc0 sc1 nt
	ds_read2_b32 v[50:51], v10 offset0:113 offset1:121
	ds_read2_b32 v[52:53], v10 offset0:178 offset1:186
	ds_read2_b32 v[56:57], v10 offset0:243 offset1:251
	s_waitcnt lgkmcnt(3)
	v_bfe_u32 v46, v54, 16, 1
	v_add3_u32 v46, v54, v46, s41
	s_waitcnt lgkmcnt(2)
	v_bfe_u32 v47, v50, 16, 1
	ds_read2_b32 v[58:59], v45 offset0:52 offset1:60
	v_lshrrev_b32_e32 v46, 16, v46
	v_add3_u32 v47, v50, v47, s41
	ds_read2_b32 v[60:61], v45 offset0:117 offset1:125
	v_and_or_b32 v46, v47, s42, v46
	s_waitcnt lgkmcnt(3)
	v_bfe_u32 v47, v52, 16, 1
	ds_read2_b32 v[62:63], v45 offset0:182 offset1:190
	v_add3_u32 v47, v52, v47, s41
	s_waitcnt lgkmcnt(3)
	v_bfe_u32 v48, v56, 16, 1
	ds_read2_b32 v[64:65], v45 offset0:247 offset1:255
	v_lshrrev_b32_e32 v47, 16, v47
	v_add3_u32 v48, v56, v48, s41
	v_and_or_b32 v47, v48, s42, v47
	s_waitcnt lgkmcnt(3)
	v_bfe_u32 v48, v58, 16, 1
	v_add3_u32 v48, v58, v48, s41
	s_waitcnt lgkmcnt(2)
	v_bfe_u32 v49, v60, 16, 1
	v_lshrrev_b32_e32 v48, 16, v48
	v_add3_u32 v49, v60, v49, s41
	s_waitcnt lgkmcnt(1)
	v_bfe_u32 v45, v62, 16, 1
	v_and_or_b32 v48, v49, s42, v48
	v_add3_u32 v45, v62, v45, s41
	s_waitcnt lgkmcnt(0)
	v_bfe_u32 v49, v64, 16, 1
	v_lshrrev_b32_e32 v45, 16, v45
	v_add3_u32 v49, v64, v49, s41
	v_and_or_b32 v49, v49, s42, v45
	v_add_u32_e32 v45, s8, v16
	v_lshrrev_b32_e32 v50, 8, v45
	v_mul_i32_i24_e32 v66, 0x58, v50
	v_ashrrev_i32_e32 v67, 31, v66
	v_lshl_add_u64 v[66:67], v[66:67], 0, s[6:7]
	v_lshlrev_b64 v[66:67], 15, v[66:67]
	v_lshlrev_b32_e32 v45, 7, v45
	v_lshl_add_u64 v[66:67], s[4:5], 0, v[66:67]
	v_and_b32_e32 v68, 0x7f80, v45
	v_lshl_add_u64 v[66:67], v[66:67], 0, v[68:69]
	v_lshl_add_u64 v[66:67], v[66:67], 0, v[6:7]
	v_bfe_u32 v45, v55, 16, 1
	global_store_dwordx4 v[66:67], v[46:49], off sc0 sc1 nt
	v_add3_u32 v45, v55, v45, s41
	v_lshrrev_b32_e32 v45, 16, v45
	v_bfe_u32 v46, v51, 16, 1
	v_add3_u32 v46, v51, v46, s41
	v_and_or_b32 v46, v46, s42, v45
	v_bfe_u32 v45, v53, 16, 1
	v_add3_u32 v45, v53, v45, s41
	v_bfe_u32 v47, v57, 16, 1
	v_lshrrev_b32_e32 v45, 16, v45
	v_add3_u32 v47, v57, v47, s41
	v_and_or_b32 v47, v47, s42, v45
	v_bfe_u32 v45, v59, 16, 1
	v_add3_u32 v45, v59, v45, s41
	v_bfe_u32 v48, v61, 16, 1
	v_lshrrev_b32_e32 v45, 16, v45
	v_add3_u32 v48, v61, v48, s41
	v_and_or_b32 v48, v48, s42, v45
	v_bfe_u32 v45, v63, 16, 1
	v_add3_u32 v45, v63, v45, s41
	v_bfe_u32 v49, v65, 16, 1
	v_lshrrev_b32_e32 v45, 16, v45
	v_add3_u32 v49, v65, v49, s41
	v_and_or_b32 v49, v49, s42, v45
	v_add_u32_e32 v45, s8, v17
	v_lshrrev_b32_e32 v50, 8, v45
	v_mul_i32_i24_e32 v50, 0x58, v50
	v_ashrrev_i32_e32 v51, 31, v50
	v_lshl_add_u64 v[50:51], v[50:51], 0, s[6:7]
	v_lshlrev_b64 v[50:51], 15, v[50:51]
	v_lshlrev_b32_e32 v45, 7, v45
	v_lshl_add_u64 v[50:51], s[4:5], 0, v[50:51]
	v_and_b32_e32 v52, 0x7f80, v45
	v_mov_b32_e32 v53, v3
	v_lshl_add_u64 v[50:51], v[50:51], 0, v[52:53]
	v_lshl_add_u64 v[6:7], v[50:51], 0, v[6:7]
	global_store_dwordx4 v[6:7], v[46:49], off sc0 sc1 nt
	s_waitcnt lgkmcnt(0)

.LBB0_50:
	s_andn2_b64 vcc, exec, s[8:9]
	s_cbranch_vccnz .LBB0_31
	s_mul_hi_i32 s6, s47, 0x2e8ba2e9
	s_lshr_b32 s10, s6, 31
	s_ashr_i32 s6, s6, 5
	s_load_dwordx2 s[8:9], s[16:17], 0x40
	s_add_i32 s10, s6, s10
	s_mul_i32 s6, s10, 0xffffd400
	s_add_i32 s48, s20, s6
	s_ashr_i32 s49, s48, 31
	s_lshl_b64 s[48:49], s[48:49], 2
	s_waitcnt lgkmcnt(0)
	s_add_u32 s8, s8, s48
	v_lshl_add_u32 v45, s10, 6, v5
	s_addc_u32 s9, s9, s49
	v_lshl_add_u64 v[6:7], s[8:9], 0, v[2:3]
	v_add_u32_e32 v48, 4, v45
	v_add_u32_e32 v54, 8, v45
	v_add_u32_e32 v56, 12, v45
	v_add_u32_e32 v62, 16, v45
	v_add_u32_e32 v64, 20, v45
	v_add_u32_e32 v70, 24, v45
	v_add_u32_e32 v72, 28, v45
	v_add_u32_e32 v82, 36, v45
	v_mad_i64_i32 v[46:47], s[8:9], v45, s43, v[6:7]
	v_mad_i64_i32 v[50:51], s[8:9], v48, s43, v[6:7]
	v_mad_i64_i32 v[54:55], s[8:9], v54, s43, v[6:7]
	v_mad_i64_i32 v[58:59], s[8:9], v56, s43, v[6:7]
	v_mad_i64_i32 v[62:63], s[8:9], v62, s43, v[6:7]
	v_mad_i64_i32 v[66:67], s[8:9], v64, s43, v[6:7]
	v_mad_i64_i32 v[70:71], s[8:9], v70, s43, v[6:7]
	v_mad_i64_i32 v[74:75], s[8:9], v72, s43, v[6:7]
	v_mad_i64_i32 v[82:83], s[8:9], v82, s43, v[6:7]
	v_add_u32_e32 v86, 40, v45
	global_load_dwordx4 v[46:49], v[46:47], off nt
	s_nop 0
	global_load_dwordx4 v[50:53], v[50:51], off nt
	s_nop 0
	global_load_dwordx4 v[54:57], v[54:55], off nt
	s_nop 0
	global_load_dwordx4 v[58:61], v[58:59], off nt
	s_nop 0
	global_load_dwordx4 v[62:65], v[62:63], off nt
	s_nop 0
	global_load_dwordx4 v[66:69], v[66:67], off nt
	s_nop 0
	global_load_dwordx4 v[70:73], v[70:71], off nt
	s_nop 0
	global_load_dwordx4 v[74:77], v[74:75], off nt
	v_mad_i64_i32 v[86:87], s[8:9], v86, s43, v[6:7]
	global_load_dwordx4 v[82:85], v[82:83], off nt
	v_add_u32_e32 v90, 44, v45
	global_load_dwordx4 v[86:89], v[86:87], off nt
	v_mad_i64_i32 v[90:91], s[8:9], v90, s43, v[6:7]
	global_load_dwordx4 v[90:93], v[90:91], off nt
	v_add_u32_e32 v94, 48, v45
	v_mad_i64_i32 v[94:95], s[8:9], v94, s43, v[6:7]
	global_load_dwordx4 v[94:97], v[94:95], off nt
	v_add_u32_e32 v98, 52, v45
	v_mad_i64_i32 v[98:99], s[8:9], v98, s43, v[6:7]
	global_load_dwordx4 v[98:101], v[98:99], off nt
	v_add_u32_e32 v102, 56, v45
	v_mad_i64_i32 v[102:103], s[8:9], v102, s43, v[6:7]
	v_add_u32_e32 v78, 32, v45
	global_load_dwordx4 v[102:105], v[102:103], off nt
	v_add_u32_e32 v45, 60, v45
	v_mad_i64_i32 v[78:79], s[8:9], v78, s43, v[6:7]
	v_mad_i64_i32 v[6:7], s[8:9], v45, s43, v[6:7]
	global_load_dwordx4 v[78:81], v[78:79], off nt
	v_add_u32_e32 v45, 0x400, v10
	global_load_dwordx4 v[106:109], v[6:7], off nt
	v_add_u32_e32 v6, 0x2498, v8
	s_ashr_i32 s11, s10, 31
	s_lshl_b64 s[8:9], s[10:11], 15
	s_add_u32 s8, s12, s8
	s_addc_u32 s9, s13, s9
	s_waitcnt vmcnt(15)
	ds_write2_b32 v8, v46, v47 offset1:1
	ds_write2_b32 v8, v48, v49 offset0:2 offset1:3
	s_waitcnt vmcnt(14)
	ds_write2_b32 v26, v50, v51 offset1:1
	ds_write2_b32 v27, v52, v53 offset1:1
	s_waitcnt vmcnt(13)
	ds_write2_b32 v28, v54, v55 offset1:1
	ds_write2_b32 v29, v56, v57 offset1:1
	s_waitcnt vmcnt(12)
	ds_write2_b32 v30, v58, v59 offset1:1
	ds_write2_b32 v31, v60, v61 offset1:1
	s_waitcnt vmcnt(11)
	ds_write2_b32 v32, v62, v63 offset1:1
	ds_write2_b32 v33, v64, v65 offset1:1
	s_waitcnt vmcnt(10)
	ds_write2_b32 v34, v66, v67 offset1:1
	ds_write2_b32 v35, v68, v69 offset1:1
	s_waitcnt vmcnt(9)
	ds_write2_b32 v36, v70, v71 offset1:1
	ds_write2_b32 v37, v72, v73 offset1:1
	s_waitcnt vmcnt(8)
	ds_write2_b32 v38, v74, v75 offset1:1
	ds_write2_b32 v39, v76, v77 offset1:1
	s_waitcnt vmcnt(1)
	ds_write2_b32 v40, v78, v79 offset1:1
	ds_write2_b32 v41, v80, v81 offset1:1
	ds_write2_b32 v42, v82, v83 offset1:1
	ds_write2_b32 v6, v84, v85 offset1:1
	v_add_u32_e32 v6, 0x28a0, v8
	ds_write2_b32 v6, v86, v87 offset1:1
	v_add_u32_e32 v6, 0x28a8, v8
	ds_write2_b32 v6, v88, v89 offset1:1
	v_add_u32_e32 v6, 0x2cb0, v8
	ds_write2_b32 v6, v90, v91 offset1:1
	v_add_u32_e32 v6, 0x2cb8, v8
	ds_write2_b32 v6, v92, v93 offset1:1
	v_add_u32_e32 v6, 0x30c0, v8
	ds_write2_b32 v6, v94, v95 offset1:1
	v_add_u32_e32 v6, 0x30c8, v8
	ds_write2_b32 v6, v96, v97 offset1:1
	v_add_u32_e32 v6, 0x34d0, v8
	ds_write2_b32 v6, v98, v99 offset1:1
	v_add_u32_e32 v6, 0x34d8, v8
	ds_write2_b32 v6, v100, v101 offset1:1
	v_add_u32_e32 v6, 0x38e0, v8
	ds_write2_b32 v6, v102, v103 offset1:1
	v_add_u32_e32 v6, 0x38e8, v8
	ds_write2_b32 v6, v104, v105 offset1:1
	v_add_u32_e32 v6, 0x3cf0, v8
	s_waitcnt vmcnt(0)
	ds_write2_b32 v6, v106, v107 offset1:1
	v_add_u32_e32 v6, 0x3cf8, v8
	ds_write2_b32 v6, v108, v109 offset1:1
	s_waitcnt lgkmcnt(0)
	ds_read2_b32 v[50:51], v10 offset1:8
	ds_read2_b32 v[52:53], v10 offset0:65 offset1:73
	ds_read2_b32 v[54:55], v10 offset0:130 offset1:138
	ds_read2_b32 v[56:57], v10 offset0:195 offset1:203
	ds_read2_b32 v[58:59], v45 offset0:4 offset1:12
	s_waitcnt lgkmcnt(4)
	v_bfe_u32 v6, v50, 16, 1
	v_add3_u32 v6, v50, v6, s41
	s_waitcnt lgkmcnt(3)
	v_bfe_u32 v7, v52, 16, 1
	v_lshrrev_b32_e32 v6, 16, v6
	v_add3_u32 v7, v52, v7, s41
	ds_read2_b32 v[60:61], v45 offset0:69 offset1:77
	v_and_or_b32 v46, v7, s42, v6
	s_waitcnt lgkmcnt(3)
	v_bfe_u32 v6, v54, 16, 1
	v_add3_u32 v6, v54, v6, s41
	s_waitcnt lgkmcnt(2)
	v_bfe_u32 v7, v56, 16, 1
	ds_read2_b32 v[62:63], v45 offset0:134 offset1:142
	v_lshrrev_b32_e32 v6, 16, v6
	v_add3_u32 v7, v56, v7, s41
	ds_read2_b32 v[64:65], v45 offset0:199 offset1:207
	v_and_or_b32 v47, v7, s42, v6
	s_waitcnt lgkmcnt(3)
	v_bfe_u32 v6, v58, 16, 1
	v_add3_u32 v6, v58, v6, s41
	s_waitcnt lgkmcnt(2)
	v_bfe_u32 v7, v60, 16, 1
	v_lshrrev_b32_e32 v6, 16, v6
	v_add3_u32 v7, v60, v7, s41
	v_and_or_b32 v48, v7, s42, v6
	s_waitcnt lgkmcnt(1)
	v_bfe_u32 v6, v62, 16, 1
	v_add_u32_e32 v70, s20, v9
	v_add3_u32 v6, v62, v6, s41
	s_waitcnt lgkmcnt(0)
	v_bfe_u32 v7, v64, 16, 1
	v_add_u32_e32 v71, s6, v70
	v_lshrrev_b32_e32 v6, 16, v6
	v_add3_u32 v7, v64, v7, s41
	v_cmp_lt_i32_e32 vcc, s24, v71
	v_and_or_b32 v49, v7, s42, v6
	s_mul_i32 s6, s10, 0x2c00
	v_cndmask_b32_e32 v6, 0, v43, vcc
	v_subrev_u32_e32 v6, s6, v6
	v_add_u32_e32 v6, v70, v6
	v_cndmask_b32_e32 v7, 0, v44, vcc
	v_ashrrev_i32_e32 v6, 7, v6
	v_and_or_b32 v50, v71, s44, v7
	v_ashrrev_i32_e32 v7, 31, v6
	v_lshlrev_b64 v[6:7], 20, v[6:7]
	v_lshl_add_u64 v[6:7], s[8:9], 0, v[6:7]
	v_lshlrev_b32_e32 v66, 7, v50
	v_mov_b32_e32 v67, v3
	v_lshl_add_u64 v[66:67], v[6:7], 0, v[66:67]
	v_lshlrev_b32_e32 v6, 1, v4
	v_mov_b32_e32 v7, v3
	v_lshl_add_u64 v[66:67], v[66:67], 0, v[6:7]
	global_store_dwordx4 v[66:67], v[46:49], off sc0 sc1 nt
	v_bfe_u32 v50, v65, 16, 1
	v_add3_u32 v50, v65, v50, s41
	v_bfe_u32 v46, v51, 16, 1
	v_add3_u32 v46, v51, v46, s41
	v_bfe_u32 v47, v53, 16, 1
	v_lshrrev_b32_e32 v46, 16, v46
	v_add3_u32 v47, v53, v47, s41
	v_and_or_b32 v46, v47, s42, v46
	v_bfe_u32 v47, v55, 16, 1
	v_add3_u32 v47, v55, v47, s41
	v_bfe_u32 v48, v57, 16, 1
	v_lshrrev_b32_e32 v47, 16, v47
	v_add3_u32 v48, v57, v48, s41
	v_and_or_b32 v47, v48, s42, v47
	v_bfe_u32 v48, v59, 16, 1
	v_add3_u32 v48, v59, v48, s41
	v_bfe_u32 v49, v61, 16, 1
	v_lshrrev_b32_e32 v48, 16, v48
	v_add3_u32 v49, v61, v49, s41
	v_and_or_b32 v48, v49, s42, v48
	v_bfe_u32 v49, v63, 16, 1
	v_add3_u32 v49, v63, v49, s41
	v_lshrrev_b32_e32 v49, 16, v49
	v_and_or_b32 v49, v50, s42, v49
	v_add_u32_e32 v50, 8, v71
	v_cmp_lt_i32_e32 vcc, s24, v50
	v_mov_b32_e32 v53, v3
	ds_read2_b32 v[54:55], v10 offset0:16 offset1:24
	v_cndmask_b32_e32 v51, 0, v43, vcc
	v_subrev_u32_e32 v51, s6, v51
	v_add3_u32 v51, v70, v51, 8
	v_cndmask_b32_e32 v52, 0, v44, vcc
	v_and_or_b32 v52, v50, s44, v52
	v_ashrrev_i32_e32 v50, 7, v51
	v_ashrrev_i32_e32 v51, 31, v50
	v_lshlrev_b64 v[50:51], 20, v[50:51]
	v_lshl_add_u64 v[50:51], s[8:9], 0, v[50:51]
	v_lshlrev_b32_e32 v52, 7, v52
	v_lshl_add_u64 v[50:51], v[50:51], 0, v[52:53]
	v_lshl_add_u64 v[50:51], v[50:51], 0, v[6:7]
	global_store_dwordx4 v[50:51], v[46:49], off sc0 sc1 nt
	ds_read2_b32 v[50:51], v10 offset0:81 offset1:89
	ds_read2_b32 v[52:53], v10 offset0:146 offset1:154
	ds_read2_b32 v[56:57], v10 offset0:211 offset1:219
	s_waitcnt lgkmcnt(3)
	v_bfe_u32 v46, v54, 16, 1
	v_add3_u32 v46, v54, v46, s41
	s_waitcnt lgkmcnt(2)
	v_bfe_u32 v47, v50, 16, 1
	ds_read2_b32 v[58:59], v45 offset0:20 offset1:28
	v_lshrrev_b32_e32 v46, 16, v46
	v_add3_u32 v47, v50, v47, s41
	ds_read2_b32 v[60:61], v45 offset0:85 offset1:93
	v_and_or_b32 v46, v47, s42, v46
	s_waitcnt lgkmcnt(3)
	v_bfe_u32 v47, v52, 16, 1
	v_add3_u32 v47, v52, v47, s41
	s_waitcnt lgkmcnt(2)
	v_bfe_u32 v48, v56, 16, 1
	ds_read2_b32 v[62:63], v45 offset0:150 offset1:158
	v_lshrrev_b32_e32 v47, 16, v47
	v_add3_u32 v48, v56, v48, s41
	ds_read2_b32 v[64:65], v45 offset0:215 offset1:223
	v_and_or_b32 v47, v48, s42, v47
	s_waitcnt lgkmcnt(3)
	v_bfe_u32 v48, v58, 16, 1
	v_add3_u32 v48, v58, v48, s41
	s_waitcnt lgkmcnt(2)
	v_bfe_u32 v49, v60, 16, 1
	v_lshrrev_b32_e32 v48, 16, v48
	v_add3_u32 v49, v60, v49, s41
	v_and_or_b32 v48, v49, s42, v48
	s_waitcnt lgkmcnt(1)
	v_bfe_u32 v49, v62, 16, 1
	v_add3_u32 v49, v62, v49, s41
	s_waitcnt lgkmcnt(0)
	v_bfe_u32 v50, v64, 16, 1
	v_lshrrev_b32_e32 v49, 16, v49
	v_add3_u32 v50, v64, v50, s41
	v_and_or_b32 v49, v50, s42, v49
	v_add_u32_e32 v50, 16, v71
	v_cmp_lt_i32_e32 vcc, s24, v50
	v_mov_b32_e32 v69, v3
	s_nop 0
	v_cndmask_b32_e32 v52, 0, v43, vcc
	v_subrev_u32_e32 v52, s6, v52
	v_add3_u32 v52, v70, v52, 16
	v_ashrrev_i32_e32 v66, 7, v52
	v_cndmask_b32_e32 v54, 0, v44, vcc
	v_ashrrev_i32_e32 v67, 31, v66
	v_and_or_b32 v50, v50, s44, v54
	v_lshlrev_b64 v[66:67], 20, v[66:67]
	v_lshl_add_u64 v[66:67], s[8:9], 0, v[66:67]
	v_lshlrev_b32_e32 v68, 7, v50
	v_lshl_add_u64 v[66:67], v[66:67], 0, v[68:69]
	v_lshl_add_u64 v[66:67], v[66:67], 0, v[6:7]
	global_store_dwordx4 v[66:67], v[46:49], off sc0 sc1 nt
	v_bfe_u32 v50, v65, 16, 1
	v_add3_u32 v50, v65, v50, s41
	v_bfe_u32 v46, v55, 16, 1
	v_add3_u32 v46, v55, v46, s41
	v_bfe_u32 v47, v51, 16, 1
	v_lshrrev_b32_e32 v46, 16, v46
	v_add3_u32 v47, v51, v47, s41
	v_and_or_b32 v46, v47, s42, v46
	v_bfe_u32 v47, v53, 16, 1
	v_add3_u32 v47, v53, v47, s41
	v_bfe_u32 v48, v57, 16, 1
	v_lshrrev_b32_e32 v47, 16, v47
	v_add3_u32 v48, v57, v48, s41
	v_and_or_b32 v47, v48, s42, v47
	v_bfe_u32 v48, v59, 16, 1
	v_add3_u32 v48, v59, v48, s41
	v_bfe_u32 v49, v61, 16, 1
	v_lshrrev_b32_e32 v48, 16, v48
	v_add3_u32 v49, v61, v49, s41
	v_and_or_b32 v48, v49, s42, v48
	v_bfe_u32 v49, v63, 16, 1
	v_add3_u32 v49, v63, v49, s41
	v_lshrrev_b32_e32 v49, 16, v49
	v_and_or_b32 v49, v50, s42, v49
	v_add_u32_e32 v50, 24, v71
	v_cmp_lt_i32_e32 vcc, s24, v50
	v_mov_b32_e32 v53, v3
	ds_read2_b32 v[54:55], v10 offset0:32 offset1:40
	v_cndmask_b32_e32 v51, 0, v43, vcc
	v_subrev_u32_e32 v51, s6, v51
	v_add3_u32 v51, v70, v51, 24
	v_cndmask_b32_e32 v52, 0, v44, vcc
	v_and_or_b32 v52, v50, s44, v52
	v_ashrrev_i32_e32 v50, 7, v51
	v_ashrrev_i32_e32 v51, 31, v50
	v_lshlrev_b64 v[50:51], 20, v[50:51]
	v_lshl_add_u64 v[50:51], s[8:9], 0, v[50:51]
	v_lshlrev_b32_e32 v52, 7, v52
	v_lshl_add_u64 v[50:51], v[50:51], 0, v[52:53]
	v_lshl_add_u64 v[50:51], v[50:51], 0, v[6:7]
	global_store_dwordx4 v[50:51], v[46:49], off sc0 sc1 nt
	ds_read2_b32 v[50:51], v10 offset0:97 offset1:105
	ds_read2_b32 v[52:53], v10 offset0:162 offset1:170
	ds_read2_b32 v[56:57], v10 offset0:227 offset1:235
	s_waitcnt lgkmcnt(3)
	v_bfe_u32 v46, v54, 16, 1
	v_add3_u32 v46, v54, v46, s41
	s_waitcnt lgkmcnt(2)
	v_bfe_u32 v47, v50, 16, 1
	ds_read2_b32 v[58:59], v45 offset0:36 offset1:44
	v_lshrrev_b32_e32 v46, 16, v46
	v_add3_u32 v47, v50, v47, s41
	ds_read2_b32 v[60:61], v45 offset0:101 offset1:109
	v_and_or_b32 v46, v47, s42, v46
	s_waitcnt lgkmcnt(3)
	v_bfe_u32 v47, v52, 16, 1
	v_add3_u32 v47, v52, v47, s41
	s_waitcnt lgkmcnt(2)
	v_bfe_u32 v48, v56, 16, 1
	ds_read2_b32 v[62:63], v45 offset0:166 offset1:174
	v_lshrrev_b32_e32 v47, 16, v47
	v_add3_u32 v48, v56, v48, s41
	ds_read2_b32 v[64:65], v45 offset0:231 offset1:239
	v_and_or_b32 v47, v48, s42, v47
	s_waitcnt lgkmcnt(3)
	v_bfe_u32 v48, v58, 16, 1
	v_add3_u32 v48, v58, v48, s41
	s_waitcnt lgkmcnt(2)
	v_bfe_u32 v49, v60, 16, 1
	v_lshrrev_b32_e32 v48, 16, v48
	v_add3_u32 v49, v60, v49, s41
	v_and_or_b32 v48, v49, s42, v48
	s_waitcnt lgkmcnt(1)
	v_bfe_u32 v49, v62, 16, 1
	v_add3_u32 v49, v62, v49, s41
	s_waitcnt lgkmcnt(0)
	v_bfe_u32 v50, v64, 16, 1
	v_lshrrev_b32_e32 v49, 16, v49
	v_add3_u32 v50, v64, v50, s41
	v_and_or_b32 v49, v50, s42, v49
	v_add_u32_e32 v50, 32, v71
	v_cmp_lt_i32_e32 vcc, s24, v50
	s_nop 1
	v_cndmask_b32_e32 v52, 0, v43, vcc
	v_subrev_u32_e32 v52, s6, v52
	v_add3_u32 v52, v70, v52, 32
	v_ashrrev_i32_e32 v66, 7, v52
	v_cndmask_b32_e32 v54, 0, v44, vcc
	v_ashrrev_i32_e32 v67, 31, v66
	v_and_or_b32 v50, v50, s44, v54
	v_lshlrev_b64 v[66:67], 20, v[66:67]
	v_lshl_add_u64 v[66:67], s[8:9], 0, v[66:67]
	v_lshlrev_b32_e32 v68, 7, v50
	v_lshl_add_u64 v[66:67], v[66:67], 0, v[68:69]
	v_lshl_add_u64 v[66:67], v[66:67], 0, v[6:7]
	global_store_dwordx4 v[66:67], v[46:49], off sc0 sc1 nt
	v_bfe_u32 v50, v65, 16, 1
	v_add3_u32 v50, v65, v50, s41
	v_bfe_u32 v46, v55, 16, 1
	v_add3_u32 v46, v55, v46, s41
	v_bfe_u32 v47, v51, 16, 1
	v_lshrrev_b32_e32 v46, 16, v46
	v_add3_u32 v47, v51, v47, s41
	v_and_or_b32 v46, v47, s42, v46
	v_bfe_u32 v47, v53, 16, 1
	v_add3_u32 v47, v53, v47, s41
	v_bfe_u32 v48, v57, 16, 1
	v_lshrrev_b32_e32 v47, 16, v47
	v_add3_u32 v48, v57, v48, s41
	v_and_or_b32 v47, v48, s42, v47
	v_bfe_u32 v48, v59, 16, 1
	v_add3_u32 v48, v59, v48, s41
	v_bfe_u32 v49, v61, 16, 1
	v_lshrrev_b32_e32 v48, 16, v48
	v_add3_u32 v49, v61, v49, s41
	v_and_or_b32 v48, v49, s42, v48
	v_bfe_u32 v49, v63, 16, 1
	v_add3_u32 v49, v63, v49, s41
	v_lshrrev_b32_e32 v49, 16, v49
	v_and_or_b32 v49, v50, s42, v49
	v_add_u32_e32 v50, 40, v71
	v_cmp_lt_i32_e32 vcc, s24, v50
	v_mov_b32_e32 v53, v3
	ds_read2_b32 v[54:55], v10 offset0:48 offset1:56
	v_cndmask_b32_e32 v51, 0, v43, vcc
	v_subrev_u32_e32 v51, s6, v51
	v_add3_u32 v51, v70, v51, 40
	v_cndmask_b32_e32 v52, 0, v44, vcc
	v_and_or_b32 v52, v50, s44, v52
	v_ashrrev_i32_e32 v50, 7, v51
	v_ashrrev_i32_e32 v51, 31, v50
	v_lshlrev_b64 v[50:51], 20, v[50:51]
	v_lshl_add_u64 v[50:51], s[8:9], 0, v[50:51]
	v_lshlrev_b32_e32 v52, 7, v52
	v_lshl_add_u64 v[50:51], v[50:51], 0, v[52:53]
	v_lshl_add_u64 v[50:51], v[50:51], 0, v[6:7]
	global_store_dwordx4 v[50:51], v[46:49], off sc0 sc1 nt
	ds_read2_b32 v[50:51], v10 offset0:113 offset1:121
	ds_read2_b32 v[52:53], v10 offset0:178 offset1:186
	ds_read2_b32 v[56:57], v10 offset0:243 offset1:251
	s_waitcnt lgkmcnt(3)
	v_bfe_u32 v46, v54, 16, 1
	v_add3_u32 v46, v54, v46, s41
	s_waitcnt lgkmcnt(2)
	v_bfe_u32 v47, v50, 16, 1
	ds_read2_b32 v[58:59], v45 offset0:52 offset1:60
	v_lshrrev_b32_e32 v46, 16, v46
	v_add3_u32 v47, v50, v47, s41
	ds_read2_b32 v[60:61], v45 offset0:117 offset1:125
	v_and_or_b32 v46, v47, s42, v46
	s_waitcnt lgkmcnt(3)
	v_bfe_u32 v47, v52, 16, 1
	ds_read2_b32 v[62:63], v45 offset0:182 offset1:190
	v_add3_u32 v47, v52, v47, s41
	s_waitcnt lgkmcnt(3)
	v_bfe_u32 v48, v56, 16, 1
	ds_read2_b32 v[64:65], v45 offset0:247 offset1:255
	v_lshrrev_b32_e32 v47, 16, v47
	v_add3_u32 v48, v56, v48, s41
	v_and_or_b32 v47, v48, s42, v47
	s_waitcnt lgkmcnt(3)
	v_bfe_u32 v48, v58, 16, 1
	v_add3_u32 v48, v58, v48, s41
	s_waitcnt lgkmcnt(2)
	v_bfe_u32 v49, v60, 16, 1
	v_lshrrev_b32_e32 v48, 16, v48
	v_add3_u32 v49, v60, v49, s41
	s_waitcnt lgkmcnt(1)
	v_bfe_u32 v45, v62, 16, 1
	v_and_or_b32 v48, v49, s42, v48
	v_add3_u32 v45, v62, v45, s41
	s_waitcnt lgkmcnt(0)
	v_bfe_u32 v49, v64, 16, 1
	v_lshrrev_b32_e32 v45, 16, v45
	v_add3_u32 v49, v64, v49, s41
	v_and_or_b32 v49, v49, s42, v45
	v_add_u32_e32 v45, 48, v71
	v_cmp_lt_i32_e32 vcc, s24, v45
	s_nop 1
	v_cndmask_b32_e32 v50, 0, v43, vcc
	v_subrev_u32_e32 v50, s6, v50
	v_add3_u32 v50, v70, v50, 48
	v_ashrrev_i32_e32 v66, 7, v50
	v_cndmask_b32_e32 v52, 0, v44, vcc
	v_ashrrev_i32_e32 v67, 31, v66
	v_and_or_b32 v45, v45, s44, v52
	v_lshlrev_b64 v[66:67], 20, v[66:67]
	v_lshl_add_u64 v[66:67], s[8:9], 0, v[66:67]
	v_lshlrev_b32_e32 v68, 7, v45
	v_lshl_add_u64 v[66:67], v[66:67], 0, v[68:69]
	v_lshl_add_u64 v[66:67], v[66:67], 0, v[6:7]
	v_bfe_u32 v45, v55, 16, 1
	global_store_dwordx4 v[66:67], v[46:49], off sc0 sc1 nt
	v_add3_u32 v45, v55, v45, s41
	v_lshrrev_b32_e32 v45, 16, v45
	v_bfe_u32 v46, v51, 16, 1
	v_add3_u32 v46, v51, v46, s41
	v_and_or_b32 v46, v46, s42, v45
	v_bfe_u32 v45, v53, 16, 1
	v_add3_u32 v45, v53, v45, s41
	v_bfe_u32 v47, v57, 16, 1
	v_lshrrev_b32_e32 v45, 16, v45
	v_add3_u32 v47, v57, v47, s41
	v_and_or_b32 v47, v47, s42, v45
	v_bfe_u32 v45, v59, 16, 1
	v_add3_u32 v45, v59, v45, s41
	v_bfe_u32 v48, v61, 16, 1
	v_lshrrev_b32_e32 v45, 16, v45
	v_add3_u32 v48, v61, v48, s41
	v_and_or_b32 v48, v48, s42, v45
	v_bfe_u32 v45, v63, 16, 1
	v_add3_u32 v45, v63, v45, s41
	v_bfe_u32 v49, v65, 16, 1
	v_lshrrev_b32_e32 v45, 16, v45
	v_add3_u32 v49, v65, v49, s41
	v_and_or_b32 v49, v49, s42, v45
	v_add_u32_e32 v45, 56, v71
	v_cmp_lt_i32_e32 vcc, s24, v45
	v_mov_b32_e32 v53, v3
	s_nop 0
	v_cndmask_b32_e32 v50, 0, v43, vcc
	v_subrev_u32_e32 v50, s6, v50
	v_add3_u32 v50, v70, v50, 56
	v_cndmask_b32_e32 v51, 0, v44, vcc
	v_ashrrev_i32_e32 v50, 7, v50
	v_and_or_b32 v45, v45, s44, v51
	v_ashrrev_i32_e32 v51, 31, v50
	v_lshlrev_b64 v[50:51], 20, v[50:51]
	v_lshl_add_u64 v[50:51], s[8:9], 0, v[50:51]
	v_lshlrev_b32_e32 v52, 7, v45
	v_lshl_add_u64 v[50:51], v[50:51], 0, v[52:53]
	v_lshl_add_u64 v[6:7], v[50:51], 0, v[6:7]
	global_store_dwordx4 v[6:7], v[46:49], off sc0 sc1 nt
	s_waitcnt lgkmcnt(0)
	s_branch .LBB0_31

.LBB0_945:
	s_cmpk_gt_i32 s22, 0x15ff
	s_mov_b64 s[0:1], -1
	s_cbranch_scc0 .LBB0_963
	s_cmpk_gt_u32 s22, 0x20ff
	s_cbranch_scc0 .LBB0_960
	s_cmpk_gt_u32 s22, 0x2cff
	s_cbranch_scc0 .LBB0_957
	s_cmpk_gt_u32 s22, 0x30ff
	s_cbranch_scc0 .LBB0_954
	s_cmpk_gt_u32 s22, 0x46ff
	s_cbranch_scc0 .LBB0_951
	s_load_dwordx2 s[2:3], s[6:7], 0x98
	s_add_i32 s0, s18, 0xffee4000
	s_and_b32 s23, s20, 0x1fc0
	s_and_b32 s0, s0, 0x7c0
	s_add_i32 s1, s22, 0xffffb900
	v_add_u32_e32 v26, s23, v5
	s_lshl_b32 s23, s0, 2
	s_waitcnt lgkmcnt(0)
	s_add_u32 s2, s2, s23
	s_addc_u32 s3, s3, 0
	v_lshlrev_b32_e32 v2, 2, v4
	v_ashrrev_i32_e32 v27, 31, v26
	v_lshl_add_u64 v[28:29], s[2:3], 0, v[2:3]
	v_lshlrev_b64 v[26:27], 13, v[26:27]
	v_lshl_add_u64 v[86:87], v[28:29], 0, v[26:27]
	v_add_co_u32_e32 v26, vcc, s42, v86
	v_add_u32_e32 v2, 0x410, v7
	s_nop 0
	v_addc_co_u32_e32 v27, vcc, 0, v87, vcc
	v_add_co_u32_e32 v30, vcc, s43, v86
	s_lshr_b32 s72, s1, 5
	s_nop 0
	v_addc_co_u32_e32 v31, vcc, 0, v87, vcc
	v_add_co_u32_e32 v34, vcc, s44, v86
	global_load_dwordx4 v[26:29], v[26:27], off nt
	s_nop 0
	global_load_dwordx4 v[30:33], v[30:31], off nt
	v_addc_co_u32_e32 v35, vcc, 0, v87, vcc
	v_add_co_u32_e32 v38, vcc, s46, v86
	s_nop 1
	v_addc_co_u32_e32 v39, vcc, 0, v87, vcc
	global_load_dwordx4 v[34:37], v[34:35], off nt
	s_nop 0
	global_load_dwordx4 v[38:41], v[38:39], off nt
	v_add_co_u32_e32 v42, vcc, s49, v86
	s_nop 1
	v_addc_co_u32_e32 v43, vcc, 0, v87, vcc
	v_add_co_u32_e32 v46, vcc, s50, v86
	s_nop 1
	v_addc_co_u32_e32 v47, vcc, 0, v87, vcc
	global_load_dwordx4 v[42:45], v[42:43], off nt
	s_nop 0
	global_load_dwordx4 v[46:49], v[46:47], off nt
	v_add_co_u32_e32 v50, vcc, s53, v86
	s_nop 1
	v_addc_co_u32_e32 v51, vcc, 0, v87, vcc
	v_add_co_u32_e32 v54, vcc, s55, v86
	s_nop 1
	v_addc_co_u32_e32 v55, vcc, 0, v87, vcc
	global_load_dwordx4 v[50:53], v[50:51], off nt
	s_nop 0
	global_load_dwordx4 v[54:57], v[54:55], off nt
	v_add_co_u32_e32 v58, vcc, s56, v86
	s_nop 1
	v_addc_co_u32_e32 v59, vcc, 0, v87, vcc
	v_add_co_u32_e32 v62, vcc, s57, v86
	s_nop 1
	v_addc_co_u32_e32 v63, vcc, 0, v87, vcc
	global_load_dwordx4 v[58:61], v[58:59], off nt
	s_nop 0
	global_load_dwordx4 v[62:65], v[62:63], off nt
	v_add_co_u32_e32 v66, vcc, s58, v86
	s_nop 1
	v_addc_co_u32_e32 v67, vcc, 0, v87, vcc
	v_add_co_u32_e32 v70, vcc, s61, v86
	s_nop 1
	v_addc_co_u32_e32 v71, vcc, 0, v87, vcc
	global_load_dwordx4 v[66:69], v[66:67], off nt
	s_nop 0
	global_load_dwordx4 v[70:73], v[70:71], off nt
	v_add_co_u32_e32 v74, vcc, s62, v86
	s_nop 1
	v_addc_co_u32_e32 v75, vcc, 0, v87, vcc
	global_load_dwordx4 v[74:77], v[74:75], off nt
	v_add_co_u32_e32 v78, vcc, s63, v86
	s_nop 1
	v_addc_co_u32_e32 v79, vcc, 0, v87, vcc
	global_load_dwordx4 v[78:81], v[78:79], off nt
	v_add_co_u32_e32 v82, vcc, s64, v86
	s_nop 1
	v_addc_co_u32_e32 v83, vcc, 0, v87, vcc
	global_load_dwordx4 v[82:85], v[82:83], off nt
	v_add_co_u32_e32 v86, vcc, s65, v86
	s_nop 1
	v_addc_co_u32_e32 v87, vcc, 0, v87, vcc
	global_load_dwordx4 v[86:89], v[86:87], off nt
	s_waitcnt vmcnt(0)
	ds_write2_b32 v7, v26, v27 offset1:1
	ds_write2_b32 v7, v28, v29 offset0:2 offset1:3
	ds_write2_b32 v2, v30, v31 offset1:1
	v_add_u32_e32 v2, 0x418, v7
	ds_write2_b32 v2, v32, v33 offset1:1
	v_add_u32_e32 v2, 0x820, v7
	ds_write2_b32 v2, v34, v35 offset1:1
	v_add_u32_e32 v2, 0x828, v7
	ds_write2_b32 v2, v36, v37 offset1:1
	v_add_u32_e32 v2, 0xc30, v7
	ds_write2_b32 v2, v38, v39 offset1:1
	v_add_u32_e32 v2, 0xc38, v7
	ds_write2_b32 v2, v40, v41 offset1:1
	v_add_u32_e32 v2, 0x1040, v7
	ds_write2_b32 v2, v42, v43 offset1:1
	v_add_u32_e32 v2, 0x1048, v7
	ds_write2_b32 v2, v44, v45 offset1:1
	v_add_u32_e32 v2, 0x1450, v7
	ds_write2_b32 v2, v46, v47 offset1:1
	v_add_u32_e32 v2, 0x1458, v7
	ds_write2_b32 v2, v48, v49 offset1:1
	v_add_u32_e32 v2, 0x1860, v7
	v_mov_b32_e32 v49, v3
	ds_write2_b32 v2, v50, v51 offset1:1
	v_add_u32_e32 v2, 0x1868, v7
	ds_write2_b32 v2, v52, v53 offset1:1
	v_add_u32_e32 v2, 0x1c70, v7
	ds_write2_b32 v2, v54, v55 offset1:1
	v_add_u32_e32 v2, 0x1c78, v7
	ds_write2_b32 v2, v56, v57 offset1:1
	v_add_u32_e32 v2, 0x2080, v7
	ds_write2_b32 v2, v58, v59 offset1:1
	v_add_u32_e32 v2, 0x2088, v7
	ds_write2_b32 v2, v60, v61 offset1:1
	v_add_u32_e32 v2, 0x2490, v7
	ds_write2_b32 v2, v62, v63 offset1:1
	v_add_u32_e32 v2, 0x2498, v7
	ds_write2_b32 v2, v64, v65 offset1:1
	v_add_u32_e32 v2, 0x28a0, v7
	ds_write2_b32 v2, v66, v67 offset1:1
	v_add_u32_e32 v2, 0x28a8, v7
	ds_write2_b32 v2, v68, v69 offset1:1
	v_add_u32_e32 v2, 0x2cb0, v7
	ds_write2_b32 v2, v70, v71 offset1:1
	v_add_u32_e32 v2, 0x2cb8, v7
	ds_write2_b32 v2, v72, v73 offset1:1
	v_add_u32_e32 v2, 0x30c0, v7
	ds_write2_b32 v2, v74, v75 offset1:1
	v_add_u32_e32 v2, 0x30c8, v7
	ds_write2_b32 v2, v76, v77 offset1:1
	v_add_u32_e32 v2, 0x34d0, v7
	ds_write2_b32 v2, v78, v79 offset1:1
	v_add_u32_e32 v2, 0x34d8, v7
	ds_write2_b32 v2, v80, v81 offset1:1
	v_add_u32_e32 v2, 0x38e0, v7
	ds_write2_b32 v2, v82, v83 offset1:1
	v_add_u32_e32 v2, 0x38e8, v7
	ds_write2_b32 v2, v84, v85 offset1:1
	v_add_u32_e32 v2, 0x3cf0, v7
	ds_write2_b32 v2, v86, v87 offset1:1
	v_add_u32_e32 v2, 0x3cf8, v7
	ds_write2_b32 v2, v88, v89 offset1:1
	s_waitcnt lgkmcnt(0)
	ds_read2_b32 v[30:31], v9 offset1:8
	ds_read2_b32 v[32:33], v9 offset0:65 offset1:73
	ds_read2_b32 v[34:35], v9 offset0:130 offset1:138
	ds_read2_b32 v[36:37], v9 offset0:195 offset1:203
	s_waitcnt lgkmcnt(3)
	v_bfe_u32 v2, v30, 16, 1
	v_add3_u32 v2, v30, v2, s81
	s_waitcnt lgkmcnt(2)
	v_bfe_u32 v25, v32, 16, 1
	v_lshrrev_b32_e32 v2, 16, v2
	v_add3_u32 v25, v32, v25, s81
	v_and_or_b32 v26, v25, s39, v2
	v_add_u32_e32 v25, 0x400, v9
	ds_read2_b32 v[38:39], v25 offset0:4 offset1:12
	ds_read2_b32 v[40:41], v25 offset0:69 offset1:77
	s_waitcnt lgkmcnt(3)
	v_bfe_u32 v2, v34, 16, 1
	v_add3_u32 v2, v34, v2, s81
	s_waitcnt lgkmcnt(2)
	v_bfe_u32 v27, v36, 16, 1
	ds_read2_b32 v[42:43], v25 offset0:134 offset1:142
	v_lshrrev_b32_e32 v2, 16, v2
	v_add3_u32 v27, v36, v27, s81
	ds_read2_b32 v[44:45], v25 offset0:199 offset1:207
	v_and_or_b32 v27, v27, s39, v2
	s_waitcnt lgkmcnt(3)
	v_bfe_u32 v2, v38, 16, 1
	v_add3_u32 v2, v38, v2, s81
	s_waitcnt lgkmcnt(2)
	v_bfe_u32 v28, v40, 16, 1
	v_lshrrev_b32_e32 v2, 16, v2
	v_add3_u32 v28, v40, v28, s81
	v_and_or_b32 v28, v28, s39, v2
	s_waitcnt lgkmcnt(1)
	v_bfe_u32 v2, v42, 16, 1
	v_add3_u32 v2, v42, v2, s81
	s_waitcnt lgkmcnt(0)
	v_bfe_u32 v29, v44, 16, 1
	v_lshrrev_b32_e32 v2, 16, v2
	v_add3_u32 v29, v44, v29, s81
	v_and_or_b32 v29, v29, s39, v2
	v_add_u32_e32 v2, s0, v8
	v_lshrrev_b32_e32 v30, 8, v2
	v_mul_i32_i24_e32 v46, 0x58, v30
	v_ashrrev_i32_e32 v47, 31, v46
	v_lshl_add_u64 v[46:47], v[46:47], 0, s[72:73]
	v_lshlrev_b64 v[46:47], 15, v[46:47]
	v_lshlrev_b32_e32 v2, 7, v2
	v_lshl_add_u64 v[46:47], s[8:9], 0, v[46:47]
	v_and_b32_e32 v2, 0x7f80, v2
	v_lshl_add_u64 v[46:47], v[46:47], 0, v[2:3]
	v_lshlrev_b32_e32 v2, 1, v6
	v_lshl_add_u64 v[46:47], v[46:47], 0, v[2:3]
	global_store_dwordx4 v[46:47], v[26:29], off sc0 sc1 nt
	v_bfe_u32 v30, v45, 16, 1
	v_add3_u32 v30, v45, v30, s81
	v_bfe_u32 v26, v31, 16, 1
	v_add3_u32 v26, v31, v26, s81
	v_bfe_u32 v27, v33, 16, 1
	v_lshrrev_b32_e32 v26, 16, v26
	v_add3_u32 v27, v33, v27, s81
	v_and_or_b32 v26, v27, s39, v26
	v_bfe_u32 v27, v35, 16, 1
	v_add3_u32 v27, v35, v27, s81
	v_bfe_u32 v28, v37, 16, 1
	v_lshrrev_b32_e32 v27, 16, v27
	v_add3_u32 v28, v37, v28, s81
	v_and_or_b32 v27, v28, s39, v27
	v_bfe_u32 v28, v39, 16, 1
	v_add3_u32 v28, v39, v28, s81
	v_bfe_u32 v29, v41, 16, 1
	v_lshrrev_b32_e32 v28, 16, v28
	v_add3_u32 v29, v41, v29, s81
	v_and_or_b32 v28, v29, s39, v28
	v_bfe_u32 v29, v43, 16, 1
	v_add3_u32 v29, v43, v29, s81
	v_lshrrev_b32_e32 v29, 16, v29
	v_add_u32_e32 v32, s0, v10
	v_and_or_b32 v29, v30, s39, v29
	v_lshrrev_b32_e32 v30, 8, v32
	v_mul_i32_i24_e32 v30, 0x58, v30
	v_ashrrev_i32_e32 v31, 31, v30
	v_lshl_add_u64 v[30:31], v[30:31], 0, s[72:73]
	v_lshlrev_b64 v[30:31], 15, v[30:31]
	v_lshlrev_b32_e32 v32, 7, v32
	v_lshl_add_u64 v[30:31], s[8:9], 0, v[30:31]
	v_and_b32_e32 v32, 0x7f80, v32
	v_mov_b32_e32 v33, v3
	v_lshl_add_u64 v[30:31], v[30:31], 0, v[32:33]
	ds_read2_b32 v[34:35], v9 offset0:16 offset1:24
	v_lshl_add_u64 v[30:31], v[30:31], 0, v[2:3]
	global_store_dwordx4 v[30:31], v[26:29], off sc0 sc1 nt
	ds_read2_b32 v[30:31], v9 offset0:81 offset1:89
	ds_read2_b32 v[32:33], v9 offset0:146 offset1:154
	ds_read2_b32 v[36:37], v9 offset0:211 offset1:219
	s_waitcnt lgkmcnt(3)
	v_bfe_u32 v26, v34, 16, 1
	v_add3_u32 v26, v34, v26, s81
	s_waitcnt lgkmcnt(2)
	v_bfe_u32 v27, v30, 16, 1
	ds_read2_b32 v[38:39], v25 offset0:20 offset1:28
	v_lshrrev_b32_e32 v26, 16, v26
	v_add3_u32 v27, v30, v27, s81
	ds_read2_b32 v[40:41], v25 offset0:85 offset1:93
	v_and_or_b32 v26, v27, s39, v26
	s_waitcnt lgkmcnt(3)
	v_bfe_u32 v27, v32, 16, 1
	v_add3_u32 v27, v32, v27, s81
	s_waitcnt lgkmcnt(2)
	v_bfe_u32 v28, v36, 16, 1
	ds_read2_b32 v[42:43], v25 offset0:150 offset1:158
	v_lshrrev_b32_e32 v27, 16, v27
	v_add3_u32 v28, v36, v28, s81
	ds_read2_b32 v[44:45], v25 offset0:215 offset1:223
	v_and_or_b32 v27, v28, s39, v27
	s_waitcnt lgkmcnt(3)
	v_bfe_u32 v28, v38, 16, 1
	v_add3_u32 v28, v38, v28, s81
	s_waitcnt lgkmcnt(2)
	v_bfe_u32 v29, v40, 16, 1
	v_lshrrev_b32_e32 v28, 16, v28
	v_add3_u32 v29, v40, v29, s81
	v_and_or_b32 v28, v29, s39, v28
	s_waitcnt lgkmcnt(1)
	v_bfe_u32 v29, v42, 16, 1
	v_add3_u32 v29, v42, v29, s81
	s_waitcnt lgkmcnt(0)
	v_bfe_u32 v30, v44, 16, 1
	v_lshrrev_b32_e32 v29, 16, v29
	v_add3_u32 v30, v44, v30, s81
	v_and_or_b32 v29, v30, s39, v29
	v_add_u32_e32 v30, s0, v11
	v_lshrrev_b32_e32 v32, 8, v30
	v_mul_i32_i24_e32 v46, 0x58, v32
	v_ashrrev_i32_e32 v47, 31, v46
	v_lshl_add_u64 v[46:47], v[46:47], 0, s[72:73]
	v_lshlrev_b64 v[46:47], 15, v[46:47]
	v_lshlrev_b32_e32 v30, 7, v30
	v_lshl_add_u64 v[46:47], s[8:9], 0, v[46:47]
	v_and_b32_e32 v48, 0x7f80, v30
	v_lshl_add_u64 v[46:47], v[46:47], 0, v[48:49]
	v_lshl_add_u64 v[46:47], v[46:47], 0, v[2:3]
	global_store_dwordx4 v[46:47], v[26:29], off sc0 sc1 nt
	v_bfe_u32 v30, v45, 16, 1
	v_add3_u32 v30, v45, v30, s81
	v_bfe_u32 v26, v35, 16, 1
	v_add3_u32 v26, v35, v26, s81
	v_bfe_u32 v27, v31, 16, 1
	v_lshrrev_b32_e32 v26, 16, v26
	v_add3_u32 v27, v31, v27, s81
	v_and_or_b32 v26, v27, s39, v26
	v_bfe_u32 v27, v33, 16, 1
	v_add3_u32 v27, v33, v27, s81
	v_bfe_u32 v28, v37, 16, 1
	v_lshrrev_b32_e32 v27, 16, v27
	v_add3_u32 v28, v37, v28, s81
	v_and_or_b32 v27, v28, s39, v27
	v_bfe_u32 v28, v39, 16, 1
	v_add3_u32 v28, v39, v28, s81
	v_bfe_u32 v29, v41, 16, 1
	v_lshrrev_b32_e32 v28, 16, v28
	v_add3_u32 v29, v41, v29, s81
	v_and_or_b32 v28, v29, s39, v28
	v_bfe_u32 v29, v43, 16, 1
	v_add3_u32 v29, v43, v29, s81
	v_lshrrev_b32_e32 v29, 16, v29
	v_add_u32_e32 v32, s0, v12
	v_and_or_b32 v29, v30, s39, v29
	v_lshrrev_b32_e32 v30, 8, v32
	v_mul_i32_i24_e32 v30, 0x58, v30
	v_ashrrev_i32_e32 v31, 31, v30
	v_lshl_add_u64 v[30:31], v[30:31], 0, s[72:73]
	v_lshlrev_b64 v[30:31], 15, v[30:31]
	v_lshlrev_b32_e32 v32, 7, v32
	v_lshl_add_u64 v[30:31], s[8:9], 0, v[30:31]
	v_and_b32_e32 v32, 0x7f80, v32
	v_mov_b32_e32 v33, v3
	v_lshl_add_u64 v[30:31], v[30:31], 0, v[32:33]
	ds_read2_b32 v[34:35], v9 offset0:32 offset1:40
	v_lshl_add_u64 v[30:31], v[30:31], 0, v[2:3]
	global_store_dwordx4 v[30:31], v[26:29], off sc0 sc1 nt
	ds_read2_b32 v[30:31], v9 offset0:97 offset1:105
	ds_read2_b32 v[32:33], v9 offset0:162 offset1:170
	ds_read2_b32 v[36:37], v9 offset0:227 offset1:235
	s_waitcnt lgkmcnt(3)
	v_bfe_u32 v26, v34, 16, 1
	v_add3_u32 v26, v34, v26, s81
	s_waitcnt lgkmcnt(2)
	v_bfe_u32 v27, v30, 16, 1
	ds_read2_b32 v[38:39], v25 offset0:36 offset1:44
	v_lshrrev_b32_e32 v26, 16, v26
	v_add3_u32 v27, v30, v27, s81
	ds_read2_b32 v[40:41], v25 offset0:101 offset1:109
	v_and_or_b32 v26, v27, s39, v26
	s_waitcnt lgkmcnt(3)
	v_bfe_u32 v27, v32, 16, 1
	v_add3_u32 v27, v32, v27, s81
	s_waitcnt lgkmcnt(2)
	v_bfe_u32 v28, v36, 16, 1
	ds_read2_b32 v[42:43], v25 offset0:166 offset1:174
	v_lshrrev_b32_e32 v27, 16, v27
	v_add3_u32 v28, v36, v28, s81
	ds_read2_b32 v[44:45], v25 offset0:231 offset1:239
	v_and_or_b32 v27, v28, s39, v27
	s_waitcnt lgkmcnt(3)
	v_bfe_u32 v28, v38, 16, 1
	v_add3_u32 v28, v38, v28, s81
	s_waitcnt lgkmcnt(2)
	v_bfe_u32 v29, v40, 16, 1
	v_lshrrev_b32_e32 v28, 16, v28
	v_add3_u32 v29, v40, v29, s81
	v_and_or_b32 v28, v29, s39, v28
	s_waitcnt lgkmcnt(1)
	v_bfe_u32 v29, v42, 16, 1
	v_add3_u32 v29, v42, v29, s81
	s_waitcnt lgkmcnt(0)
	v_bfe_u32 v30, v44, 16, 1
	v_lshrrev_b32_e32 v29, 16, v29
	v_add3_u32 v30, v44, v30, s81
	v_and_or_b32 v29, v30, s39, v29
	v_add_u32_e32 v30, s0, v13
	v_lshrrev_b32_e32 v32, 8, v30
	v_mul_i32_i24_e32 v46, 0x58, v32
	v_ashrrev_i32_e32 v47, 31, v46
	v_lshl_add_u64 v[46:47], v[46:47], 0, s[72:73]
	v_lshlrev_b64 v[46:47], 15, v[46:47]
	v_lshlrev_b32_e32 v30, 7, v30
	v_lshl_add_u64 v[46:47], s[8:9], 0, v[46:47]
	v_and_b32_e32 v48, 0x7f80, v30
	v_lshl_add_u64 v[46:47], v[46:47], 0, v[48:49]
	v_lshl_add_u64 v[46:47], v[46:47], 0, v[2:3]
	global_store_dwordx4 v[46:47], v[26:29], off sc0 sc1 nt
	v_bfe_u32 v30, v45, 16, 1
	v_add3_u32 v30, v45, v30, s81
	v_bfe_u32 v26, v35, 16, 1
	v_add3_u32 v26, v35, v26, s81
	v_bfe_u32 v27, v31, 16, 1
	v_lshrrev_b32_e32 v26, 16, v26
	v_add3_u32 v27, v31, v27, s81
	v_and_or_b32 v26, v27, s39, v26
	v_bfe_u32 v27, v33, 16, 1
	v_add3_u32 v27, v33, v27, s81
	v_bfe_u32 v28, v37, 16, 1
	v_lshrrev_b32_e32 v27, 16, v27
	v_add3_u32 v28, v37, v28, s81
	v_and_or_b32 v27, v28, s39, v27
	v_bfe_u32 v28, v39, 16, 1
	v_add3_u32 v28, v39, v28, s81
	v_bfe_u32 v29, v41, 16, 1
	v_lshrrev_b32_e32 v28, 16, v28
	v_add3_u32 v29, v41, v29, s81
	v_and_or_b32 v28, v29, s39, v28
	v_bfe_u32 v29, v43, 16, 1
	v_add3_u32 v29, v43, v29, s81
	v_lshrrev_b32_e32 v29, 16, v29
	v_add_u32_e32 v32, s0, v14
	v_and_or_b32 v29, v30, s39, v29
	v_lshrrev_b32_e32 v30, 8, v32
	v_mul_i32_i24_e32 v30, 0x58, v30
	v_ashrrev_i32_e32 v31, 31, v30
	v_lshl_add_u64 v[30:31], v[30:31], 0, s[72:73]
	v_lshlrev_b64 v[30:31], 15, v[30:31]
	v_lshlrev_b32_e32 v32, 7, v32
	v_lshl_add_u64 v[30:31], s[8:9], 0, v[30:31]
	v_and_b32_e32 v32, 0x7f80, v32
	v_mov_b32_e32 v33, v3
	v_lshl_add_u64 v[30:31], v[30:31], 0, v[32:33]
	ds_read2_b32 v[34:35], v9 offset0:48 offset1:56
	v_lshl_add_u64 v[30:31], v[30:31], 0, v[2:3]
	global_store_dwordx4 v[30:31], v[26:29], off sc0 sc1 nt
	ds_read2_b32 v[30:31], v9 offset0:113 offset1:121
	ds_read2_b32 v[32:33], v9 offset0:178 offset1:186
	ds_read2_b32 v[36:37], v9 offset0:243 offset1:251
	s_waitcnt lgkmcnt(3)
	v_bfe_u32 v26, v34, 16, 1
	v_add3_u32 v26, v34, v26, s81
	s_waitcnt lgkmcnt(2)
	v_bfe_u32 v27, v30, 16, 1
	ds_read2_b32 v[38:39], v25 offset0:52 offset1:60
	v_lshrrev_b32_e32 v26, 16, v26
	v_add3_u32 v27, v30, v27, s81
	ds_read2_b32 v[40:41], v25 offset0:117 offset1:125
	v_and_or_b32 v26, v27, s39, v26
	s_waitcnt lgkmcnt(3)
	v_bfe_u32 v27, v32, 16, 1
	ds_read2_b32 v[42:43], v25 offset0:182 offset1:190
	v_add3_u32 v27, v32, v27, s81
	s_waitcnt lgkmcnt(3)
	v_bfe_u32 v28, v36, 16, 1
	ds_read2_b32 v[44:45], v25 offset0:247 offset1:255
	v_lshrrev_b32_e32 v27, 16, v27
	v_add3_u32 v28, v36, v28, s81
	v_and_or_b32 v27, v28, s39, v27
	s_waitcnt lgkmcnt(3)
	v_bfe_u32 v28, v38, 16, 1
	v_add3_u32 v28, v38, v28, s81
	s_waitcnt lgkmcnt(2)
	v_bfe_u32 v29, v40, 16, 1
	v_lshrrev_b32_e32 v28, 16, v28
	v_add3_u32 v29, v40, v29, s81
	s_waitcnt lgkmcnt(1)
	v_bfe_u32 v25, v42, 16, 1
	v_and_or_b32 v28, v29, s39, v28
	v_add3_u32 v25, v42, v25, s81
	s_waitcnt lgkmcnt(0)
	v_bfe_u32 v29, v44, 16, 1
	v_lshrrev_b32_e32 v25, 16, v25
	v_add3_u32 v29, v44, v29, s81
	v_and_or_b32 v29, v29, s39, v25
	v_add_u32_e32 v25, s0, v15
	v_lshrrev_b32_e32 v30, 8, v25
	v_mul_i32_i24_e32 v46, 0x58, v30
	v_ashrrev_i32_e32 v47, 31, v46
	v_lshl_add_u64 v[46:47], v[46:47], 0, s[72:73]
	v_lshlrev_b64 v[46:47], 15, v[46:47]
	v_lshlrev_b32_e32 v25, 7, v25
	v_lshl_add_u64 v[46:47], s[8:9], 0, v[46:47]
	v_and_b32_e32 v48, 0x7f80, v25
	v_lshl_add_u64 v[46:47], v[46:47], 0, v[48:49]
	v_lshl_add_u64 v[46:47], v[46:47], 0, v[2:3]
	v_bfe_u32 v25, v35, 16, 1
	global_store_dwordx4 v[46:47], v[26:29], off sc0 sc1 nt
	v_add3_u32 v25, v35, v25, s81
	v_lshrrev_b32_e32 v25, 16, v25
	v_bfe_u32 v26, v31, 16, 1
	v_add3_u32 v26, v31, v26, s81
	v_and_or_b32 v26, v26, s39, v25
	v_bfe_u32 v25, v33, 16, 1
	v_add3_u32 v25, v33, v25, s81
	v_bfe_u32 v27, v37, 16, 1
	v_lshrrev_b32_e32 v25, 16, v25
	v_add3_u32 v27, v37, v27, s81
	v_and_or_b32 v27, v27, s39, v25
	v_bfe_u32 v25, v39, 16, 1
	v_add3_u32 v25, v39, v25, s81
	v_bfe_u32 v28, v41, 16, 1
	v_lshrrev_b32_e32 v25, 16, v25
	v_add3_u32 v28, v41, v28, s81
	v_and_or_b32 v28, v28, s39, v25
	v_bfe_u32 v25, v43, 16, 1
	v_add3_u32 v25, v43, v25, s81
	v_bfe_u32 v29, v45, 16, 1
	v_lshrrev_b32_e32 v25, 16, v25
	v_add3_u32 v29, v45, v29, s81
	v_and_or_b32 v29, v29, s39, v25
	v_add_u32_e32 v25, s0, v16
	v_lshrrev_b32_e32 v30, 8, v25
	v_mul_i32_i24_e32 v30, 0x58, v30
	v_ashrrev_i32_e32 v31, 31, v30
	v_lshl_add_u64 v[30:31], v[30:31], 0, s[72:73]
	v_lshlrev_b64 v[30:31], 15, v[30:31]
	v_lshlrev_b32_e32 v25, 7, v25
	v_lshl_add_u64 v[30:31], s[8:9], 0, v[30:31]
	v_and_b32_e32 v32, 0x7f80, v25
	v_mov_b32_e32 v33, v3
	v_lshl_add_u64 v[30:31], v[30:31], 0, v[32:33]
	v_lshl_add_u64 v[30:31], v[30:31], 0, v[2:3]
	global_store_dwordx4 v[30:31], v[26:29], off sc0 sc1 nt
	s_waitcnt lgkmcnt(0)
	s_mov_b64 s[0:1], 0
.LBB0_951:
	s_andn2_b64 vcc, exec, s[0:1]
	s_cbranch_vccnz .LBB0_953
	s_add_i32 s1, s22, 0xcf00
	s_and_b32 s0, s1, 0xffff
	s_mul_i32 s0, s0, 0xba2f
	s_lshr_b32 s0, s0, 23
	s_load_dwordx2 s[24:25], s[6:7], 0x90
	s_mul_i32 s2, s0, 0xb0
	s_sub_i32 s1, s1, s2
	s_lshl_b32 s1, s1, 6
	s_and_b32 s2, s1, 0xffc0
	s_lshl_b32 s1, s2, 2
	s_waitcnt lgkmcnt(0)
	s_add_u32 s24, s24, s1
	s_addc_u32 s25, s25, 0
	v_lshlrev_b32_e32 v2, 2, v4
	v_lshl_add_u32 v25, s0, 6, v5
	v_lshl_add_u64 v[26:27], s[24:25], 0, v[2:3]
	s_mov_b64 s[24:25], 0x5800000
	v_lshl_add_u64 v[86:87], v[26:27], 0, s[24:25]
	v_add_u32_e32 v2, 4, v25
	v_mad_i64_i32 v[26:27], s[24:25], v25, s59, v[86:87]
	v_mad_i64_i32 v[30:31], s[24:25], v2, s59, v[86:87]
	global_load_dwordx4 v[26:29], v[26:27], off nt
	v_add_u32_e32 v2, 8, v25
	global_load_dwordx4 v[30:33], v[30:31], off nt
	v_mad_i64_i32 v[34:35], s[24:25], v2, s59, v[86:87]
	global_load_dwordx4 v[34:37], v[34:35], off nt
	v_add_u32_e32 v2, 12, v25
	v_mad_i64_i32 v[38:39], s[24:25], v2, s59, v[86:87]
	global_load_dwordx4 v[38:41], v[38:39], off nt
	v_add_u32_e32 v2, 16, v25
	v_mad_i64_i32 v[42:43], s[24:25], v2, s59, v[86:87]
	global_load_dwordx4 v[42:45], v[42:43], off nt
	v_add_u32_e32 v2, 20, v25
	v_mad_i64_i32 v[46:47], s[24:25], v2, s59, v[86:87]
	global_load_dwordx4 v[46:49], v[46:47], off nt
	v_add_u32_e32 v2, 24, v25
	v_mad_i64_i32 v[50:51], s[24:25], v2, s59, v[86:87]
	global_load_dwordx4 v[50:53], v[50:51], off nt
	v_add_u32_e32 v2, 28, v25
	v_mad_i64_i32 v[54:55], s[24:25], v2, s59, v[86:87]
	global_load_dwordx4 v[54:57], v[54:55], off nt
	v_add_u32_e32 v2, 32, v25
	v_mad_i64_i32 v[58:59], s[24:25], v2, s59, v[86:87]
	global_load_dwordx4 v[58:61], v[58:59], off nt
	v_add_u32_e32 v2, 36, v25
	v_mad_i64_i32 v[62:63], s[24:25], v2, s59, v[86:87]
	global_load_dwordx4 v[62:65], v[62:63], off nt
	v_add_u32_e32 v2, 40, v25
	v_mad_i64_i32 v[66:67], s[24:25], v2, s59, v[86:87]
	global_load_dwordx4 v[66:69], v[66:67], off nt
	v_add_u32_e32 v2, 44, v25
	v_mad_i64_i32 v[70:71], s[24:25], v2, s59, v[86:87]
	global_load_dwordx4 v[70:73], v[70:71], off nt
	v_add_u32_e32 v2, 48, v25
	v_mad_i64_i32 v[74:75], s[24:25], v2, s59, v[86:87]
	global_load_dwordx4 v[74:77], v[74:75], off nt
	v_add_u32_e32 v2, 52, v25
	v_mad_i64_i32 v[78:79], s[24:25], v2, s59, v[86:87]
	global_load_dwordx4 v[78:81], v[78:79], off nt
	v_add_u32_e32 v2, 56, v25
	v_mad_i64_i32 v[82:83], s[24:25], v2, s59, v[86:87]
	global_load_dwordx4 v[82:85], v[82:83], off nt
	v_add_u32_e32 v2, 60, v25
	v_mad_i64_i32 v[86:87], s[24:25], v2, s59, v[86:87]
	global_load_dwordx4 v[86:89], v[86:87], off nt
	v_add_u32_e32 v2, 0x410, v7
	s_lshl_b32 s0, s0, 15
	s_add_u32 s0, s14, s0
	s_addc_u32 s1, s15, 0
	s_waitcnt vmcnt(0)
	ds_write2_b32 v7, v26, v27 offset1:1
	ds_write2_b32 v7, v28, v29 offset0:2 offset1:3
	ds_write2_b32 v2, v30, v31 offset1:1
	v_add_u32_e32 v2, 0x418, v7
	ds_write2_b32 v2, v32, v33 offset1:1
	v_add_u32_e32 v2, 0x820, v7
	ds_write2_b32 v2, v34, v35 offset1:1
	v_add_u32_e32 v2, 0x828, v7
	ds_write2_b32 v2, v36, v37 offset1:1
	v_add_u32_e32 v2, 0xc30, v7
	ds_write2_b32 v2, v38, v39 offset1:1
	v_add_u32_e32 v2, 0xc38, v7
	ds_write2_b32 v2, v40, v41 offset1:1
	v_add_u32_e32 v2, 0x1040, v7
	ds_write2_b32 v2, v42, v43 offset1:1
	v_add_u32_e32 v2, 0x1048, v7
	ds_write2_b32 v2, v44, v45 offset1:1
	v_add_u32_e32 v2, 0x1450, v7
	ds_write2_b32 v2, v46, v47 offset1:1
	v_add_u32_e32 v2, 0x1458, v7
	ds_write2_b32 v2, v48, v49 offset1:1
	v_add_u32_e32 v2, 0x1860, v7
	ds_write2_b32 v2, v50, v51 offset1:1
	v_add_u32_e32 v2, 0x1868, v7
	ds_write2_b32 v2, v52, v53 offset1:1
	v_add_u32_e32 v2, 0x1c70, v7
	ds_write2_b32 v2, v54, v55 offset1:1
	v_add_u32_e32 v2, 0x1c78, v7
	ds_write2_b32 v2, v56, v57 offset1:1
	v_add_u32_e32 v2, 0x2080, v7
	ds_write2_b32 v2, v58, v59 offset1:1
	v_add_u32_e32 v2, 0x2088, v7
	ds_write2_b32 v2, v60, v61 offset1:1
	v_add_u32_e32 v2, 0x2490, v7
	ds_write2_b32 v2, v62, v63 offset1:1
	v_add_u32_e32 v2, 0x2498, v7
	ds_write2_b32 v2, v64, v65 offset1:1
	v_add_u32_e32 v2, 0x28a0, v7
	ds_write2_b32 v2, v66, v67 offset1:1
	v_add_u32_e32 v2, 0x28a8, v7
	ds_write2_b32 v2, v68, v69 offset1:1
	v_add_u32_e32 v2, 0x2cb0, v7
	ds_write2_b32 v2, v70, v71 offset1:1
	v_add_u32_e32 v2, 0x2cb8, v7
	ds_write2_b32 v2, v72, v73 offset1:1
	v_add_u32_e32 v2, 0x30c0, v7
	ds_write2_b32 v2, v74, v75 offset1:1
	v_add_u32_e32 v2, 0x30c8, v7
	ds_write2_b32 v2, v76, v77 offset1:1
	v_add_u32_e32 v2, 0x34d0, v7
	ds_write2_b32 v2, v78, v79 offset1:1
	v_add_u32_e32 v2, 0x34d8, v7
	ds_write2_b32 v2, v80, v81 offset1:1
	v_add_u32_e32 v2, 0x38e0, v7
	ds_write2_b32 v2, v82, v83 offset1:1
	v_add_u32_e32 v2, 0x38e8, v7
	ds_write2_b32 v2, v84, v85 offset1:1
	v_add_u32_e32 v2, 0x3cf0, v7
	ds_write2_b32 v2, v86, v87 offset1:1
	v_add_u32_e32 v2, 0x3cf8, v7
	ds_write2_b32 v2, v88, v89 offset1:1
	s_waitcnt lgkmcnt(0)
	ds_read2_b32 v[30:31], v9 offset0:65 offset1:73
	ds_read2_b32 v[32:33], v9 offset1:8
	ds_read2_b32 v[34:35], v9 offset0:130 offset1:138
	ds_read2_b32 v[36:37], v9 offset0:195 offset1:203
	v_mov_b32_e32 v49, v3
	s_waitcnt lgkmcnt(3)
	v_bfe_u32 v25, v30, 16, 1
	s_waitcnt lgkmcnt(2)
	v_bfe_u32 v2, v32, 16, 1
	v_add3_u32 v2, v32, v2, s81
	v_lshrrev_b32_e32 v2, 16, v2
	v_add3_u32 v25, v30, v25, s81
	v_and_or_b32 v26, v25, s39, v2
	s_waitcnt lgkmcnt(1)
	v_bfe_u32 v2, v34, 16, 1
	v_add3_u32 v2, v34, v2, s81
	s_waitcnt lgkmcnt(0)
	v_bfe_u32 v25, v36, 16, 1
	v_lshrrev_b32_e32 v2, 16, v2
	v_add3_u32 v25, v36, v25, s81
	v_and_or_b32 v27, v25, s39, v2
	v_add_u32_e32 v25, 0x400, v9
	ds_read2_b32 v[38:39], v25 offset0:4 offset1:12
	ds_read2_b32 v[40:41], v25 offset0:69 offset1:77
	ds_read2_b32 v[42:43], v25 offset0:134 offset1:142
	ds_read2_b32 v[44:45], v25 offset0:199 offset1:207
	s_waitcnt lgkmcnt(3)
	v_bfe_u32 v2, v38, 16, 1
	v_add3_u32 v2, v38, v2, s81
	s_waitcnt lgkmcnt(2)
	v_bfe_u32 v28, v40, 16, 1
	v_lshrrev_b32_e32 v2, 16, v2
	v_add3_u32 v28, v40, v28, s81
	v_and_or_b32 v28, v28, s39, v2
	s_waitcnt lgkmcnt(1)
	v_bfe_u32 v2, v42, 16, 1
	v_add3_u32 v2, v42, v2, s81
	s_waitcnt lgkmcnt(0)
	v_bfe_u32 v29, v44, 16, 1
	v_lshrrev_b32_e32 v2, 16, v2
	v_add3_u32 v29, v44, v29, s81
	v_and_or_b32 v29, v29, s39, v2
	v_add_u32_e32 v2, s2, v8
	v_cmp_lt_i32_e32 vcc, s41, v2
	s_nop 1
	v_cndmask_b32_e32 v30, 0, v247, vcc
	v_add_u32_e32 v30, v30, v2
	v_ashrrev_i32_e32 v46, 7, v30
	v_cndmask_b32_e32 v32, 0, v248, vcc
	v_ashrrev_i32_e32 v47, 31, v46
	v_and_or_b32 v2, v2, s40, v32
	v_lshlrev_b64 v[46:47], 20, v[46:47]
	v_lshl_add_u64 v[46:47], s[0:1], 0, v[46:47]
	v_lshlrev_b32_e32 v2, 7, v2
	v_lshl_add_u64 v[46:47], v[46:47], 0, v[2:3]
	v_lshlrev_b32_e32 v2, 1, v6
	v_lshl_add_u64 v[46:47], v[46:47], 0, v[2:3]
	global_store_dwordx4 v[46:47], v[26:29], off sc0 sc1 nt
	v_bfe_u32 v30, v45, 16, 1
	v_add3_u32 v30, v45, v30, s81
	v_bfe_u32 v26, v33, 16, 1
	v_add3_u32 v26, v33, v26, s81
	v_bfe_u32 v27, v31, 16, 1
	v_lshrrev_b32_e32 v26, 16, v26
	v_add3_u32 v27, v31, v27, s81
	v_and_or_b32 v26, v27, s39, v26
	v_bfe_u32 v27, v35, 16, 1
	v_add3_u32 v27, v35, v27, s81
	v_bfe_u32 v28, v37, 16, 1
	v_lshrrev_b32_e32 v27, 16, v27
	v_add3_u32 v28, v37, v28, s81
	v_and_or_b32 v27, v28, s39, v27
	v_bfe_u32 v28, v39, 16, 1
	v_add3_u32 v28, v39, v28, s81
	v_bfe_u32 v29, v41, 16, 1
	v_lshrrev_b32_e32 v28, 16, v28
	v_add3_u32 v29, v41, v29, s81
	v_and_or_b32 v28, v29, s39, v28
	v_bfe_u32 v29, v43, 16, 1
	v_add3_u32 v29, v43, v29, s81
	v_lshrrev_b32_e32 v29, 16, v29
	v_and_or_b32 v29, v30, s39, v29
	v_add_u32_e32 v30, s2, v10
	v_cmp_lt_i32_e32 vcc, s41, v30
	v_mov_b32_e32 v33, v3
	s_nop 0
	v_cndmask_b32_e32 v31, 0, v247, vcc
	v_add_u32_e32 v31, v31, v30
	v_cndmask_b32_e32 v32, 0, v248, vcc
	v_and_or_b32 v32, v30, s40, v32
	v_ashrrev_i32_e32 v30, 7, v31
	v_ashrrev_i32_e32 v31, 31, v30
	v_lshlrev_b64 v[30:31], 20, v[30:31]
	v_lshl_add_u64 v[30:31], s[0:1], 0, v[30:31]
	v_lshlrev_b32_e32 v32, 7, v32
	v_lshl_add_u64 v[30:31], v[30:31], 0, v[32:33]
	v_lshl_add_u64 v[30:31], v[30:31], 0, v[2:3]
	global_store_dwordx4 v[30:31], v[26:29], off sc0 sc1 nt
	ds_read2_b32 v[30:31], v9 offset0:16 offset1:24
	ds_read2_b32 v[32:33], v9 offset0:81 offset1:89
	ds_read2_b32 v[34:35], v9 offset0:146 offset1:154
	ds_read2_b32 v[36:37], v9 offset0:211 offset1:219
	ds_read2_b32 v[38:39], v25 offset0:20 offset1:28
	ds_read2_b32 v[40:41], v25 offset0:85 offset1:93
	ds_read2_b32 v[42:43], v25 offset0:150 offset1:158
	ds_read2_b32 v[44:45], v25 offset0:215 offset1:223
	s_waitcnt lgkmcnt(7)
	v_bfe_u32 v26, v30, 16, 1
	v_add3_u32 v26, v30, v26, s81
	s_waitcnt lgkmcnt(6)
	v_bfe_u32 v27, v32, 16, 1
	v_lshrrev_b32_e32 v26, 16, v26
	v_add3_u32 v27, v32, v27, s81
	v_and_or_b32 v26, v27, s39, v26
	s_waitcnt lgkmcnt(5)
	v_bfe_u32 v27, v34, 16, 1
	v_add3_u32 v27, v34, v27, s81
	s_waitcnt lgkmcnt(4)
	v_bfe_u32 v28, v36, 16, 1
	v_lshrrev_b32_e32 v27, 16, v27
	v_add3_u32 v28, v36, v28, s81
	v_and_or_b32 v27, v28, s39, v27
	s_waitcnt lgkmcnt(3)
	v_bfe_u32 v28, v38, 16, 1
	v_add3_u32 v28, v38, v28, s81
	s_waitcnt lgkmcnt(2)
	v_bfe_u32 v29, v40, 16, 1
	v_lshrrev_b32_e32 v28, 16, v28
	v_add3_u32 v29, v40, v29, s81
	v_and_or_b32 v28, v29, s39, v28
	s_waitcnt lgkmcnt(1)
	v_bfe_u32 v29, v42, 16, 1
	v_add3_u32 v29, v42, v29, s81
	s_waitcnt lgkmcnt(0)
	v_bfe_u32 v30, v44, 16, 1
	v_lshrrev_b32_e32 v29, 16, v29
	v_add3_u32 v30, v44, v30, s81
	v_and_or_b32 v29, v30, s39, v29
	v_add_u32_e32 v30, s2, v11
	v_cmp_lt_i32_e32 vcc, s41, v30
	s_nop 1
	v_cndmask_b32_e32 v32, 0, v247, vcc
	v_add_u32_e32 v32, v32, v30
	v_ashrrev_i32_e32 v46, 7, v32
	v_cndmask_b32_e32 v34, 0, v248, vcc
	v_ashrrev_i32_e32 v47, 31, v46
	v_and_or_b32 v30, v30, s40, v34
	v_lshlrev_b64 v[46:47], 20, v[46:47]
	v_lshl_add_u64 v[46:47], s[0:1], 0, v[46:47]
	v_lshlrev_b32_e32 v48, 7, v30
	v_lshl_add_u64 v[46:47], v[46:47], 0, v[48:49]
	v_lshl_add_u64 v[46:47], v[46:47], 0, v[2:3]
	global_store_dwordx4 v[46:47], v[26:29], off sc0 sc1 nt
	v_bfe_u32 v30, v45, 16, 1
	v_add3_u32 v30, v45, v30, s81
	v_bfe_u32 v26, v31, 16, 1
	v_add3_u32 v26, v31, v26, s81
	v_bfe_u32 v27, v33, 16, 1
	v_lshrrev_b32_e32 v26, 16, v26
	v_add3_u32 v27, v33, v27, s81
	v_and_or_b32 v26, v27, s39, v26
	v_bfe_u32 v27, v35, 16, 1
	v_add3_u32 v27, v35, v27, s81
	v_bfe_u32 v28, v37, 16, 1
	v_lshrrev_b32_e32 v27, 16, v27
	v_add3_u32 v28, v37, v28, s81
	v_and_or_b32 v27, v28, s39, v27
	v_bfe_u32 v28, v39, 16, 1
	v_add3_u32 v28, v39, v28, s81
	v_bfe_u32 v29, v41, 16, 1
	v_lshrrev_b32_e32 v28, 16, v28
	v_add3_u32 v29, v41, v29, s81
	v_and_or_b32 v28, v29, s39, v28
	v_bfe_u32 v29, v43, 16, 1
	v_add3_u32 v29, v43, v29, s81
	v_lshrrev_b32_e32 v29, 16, v29
	v_and_or_b32 v29, v30, s39, v29
	v_add_u32_e32 v30, s2, v12
	v_cmp_lt_i32_e32 vcc, s41, v30
	v_mov_b32_e32 v33, v3
	s_nop 0
	v_cndmask_b32_e32 v31, 0, v247, vcc
	v_add_u32_e32 v31, v31, v30
	v_cndmask_b32_e32 v32, 0, v248, vcc
	v_and_or_b32 v32, v30, s40, v32
	v_ashrrev_i32_e32 v30, 7, v31
	v_ashrrev_i32_e32 v31, 31, v30
	v_lshlrev_b64 v[30:31], 20, v[30:31]
	v_lshl_add_u64 v[30:31], s[0:1], 0, v[30:31]
	v_lshlrev_b32_e32 v32, 7, v32
	v_lshl_add_u64 v[30:31], v[30:31], 0, v[32:33]
	v_lshl_add_u64 v[30:31], v[30:31], 0, v[2:3]
	global_store_dwordx4 v[30:31], v[26:29], off sc0 sc1 nt
	ds_read2_b32 v[30:31], v9 offset0:32 offset1:40
	ds_read2_b32 v[32:33], v9 offset0:97 offset1:105
	ds_read2_b32 v[34:35], v9 offset0:162 offset1:170
	ds_read2_b32 v[36:37], v9 offset0:227 offset1:235
	ds_read2_b32 v[38:39], v25 offset0:36 offset1:44
	ds_read2_b32 v[40:41], v25 offset0:101 offset1:109
	ds_read2_b32 v[42:43], v25 offset0:166 offset1:174
	ds_read2_b32 v[44:45], v25 offset0:231 offset1:239
	s_waitcnt lgkmcnt(7)
	v_bfe_u32 v26, v30, 16, 1
	v_add3_u32 v26, v30, v26, s81
	s_waitcnt lgkmcnt(6)
	v_bfe_u32 v27, v32, 16, 1
	v_lshrrev_b32_e32 v26, 16, v26
	v_add3_u32 v27, v32, v27, s81
	v_and_or_b32 v26, v27, s39, v26
	s_waitcnt lgkmcnt(5)
	v_bfe_u32 v27, v34, 16, 1
	v_add3_u32 v27, v34, v27, s81
	s_waitcnt lgkmcnt(4)
	v_bfe_u32 v28, v36, 16, 1
	v_lshrrev_b32_e32 v27, 16, v27
	v_add3_u32 v28, v36, v28, s81
	v_and_or_b32 v27, v28, s39, v27
	s_waitcnt lgkmcnt(3)
	v_bfe_u32 v28, v38, 16, 1
	v_add3_u32 v28, v38, v28, s81
	s_waitcnt lgkmcnt(2)
	v_bfe_u32 v29, v40, 16, 1
	v_lshrrev_b32_e32 v28, 16, v28
	v_add3_u32 v29, v40, v29, s81
	v_and_or_b32 v28, v29, s39, v28
	s_waitcnt lgkmcnt(1)
	v_bfe_u32 v29, v42, 16, 1
	v_add3_u32 v29, v42, v29, s81
	s_waitcnt lgkmcnt(0)
	v_bfe_u32 v30, v44, 16, 1
	v_lshrrev_b32_e32 v29, 16, v29
	v_add3_u32 v30, v44, v30, s81
	v_and_or_b32 v29, v30, s39, v29
	v_add_u32_e32 v30, s2, v13
	v_cmp_lt_i32_e32 vcc, s41, v30
	s_nop 1
	v_cndmask_b32_e32 v32, 0, v247, vcc
	v_add_u32_e32 v32, v32, v30
	v_ashrrev_i32_e32 v46, 7, v32
	v_cndmask_b32_e32 v34, 0, v248, vcc
	v_ashrrev_i32_e32 v47, 31, v46
	v_and_or_b32 v30, v30, s40, v34
	v_lshlrev_b64 v[46:47], 20, v[46:47]
	v_lshl_add_u64 v[46:47], s[0:1], 0, v[46:47]
	v_lshlrev_b32_e32 v48, 7, v30
	v_lshl_add_u64 v[46:47], v[46:47], 0, v[48:49]
	v_lshl_add_u64 v[46:47], v[46:47], 0, v[2:3]
	global_store_dwordx4 v[46:47], v[26:29], off sc0 sc1 nt
	v_bfe_u32 v30, v45, 16, 1
	v_add3_u32 v30, v45, v30, s81
	v_bfe_u32 v26, v31, 16, 1
	v_add3_u32 v26, v31, v26, s81
	v_bfe_u32 v27, v33, 16, 1
	v_lshrrev_b32_e32 v26, 16, v26
	v_add3_u32 v27, v33, v27, s81
	v_and_or_b32 v26, v27, s39, v26
	v_bfe_u32 v27, v35, 16, 1
	v_add3_u32 v27, v35, v27, s81
	v_bfe_u32 v28, v37, 16, 1
	v_lshrrev_b32_e32 v27, 16, v27
	v_add3_u32 v28, v37, v28, s81
	v_and_or_b32 v27, v28, s39, v27
	v_bfe_u32 v28, v39, 16, 1
	v_add3_u32 v28, v39, v28, s81
	v_bfe_u32 v29, v41, 16, 1
	v_lshrrev_b32_e32 v28, 16, v28
	v_add3_u32 v29, v41, v29, s81
	v_and_or_b32 v28, v29, s39, v28
	v_bfe_u32 v29, v43, 16, 1
	v_add3_u32 v29, v43, v29, s81
	v_lshrrev_b32_e32 v29, 16, v29
	v_and_or_b32 v29, v30, s39, v29
	v_add_u32_e32 v30, s2, v14
	v_cmp_lt_i32_e32 vcc, s41, v30
	v_mov_b32_e32 v33, v3
	s_nop 0
	v_cndmask_b32_e32 v31, 0, v247, vcc
	v_add_u32_e32 v31, v31, v30
	v_cndmask_b32_e32 v32, 0, v248, vcc
	v_and_or_b32 v32, v30, s40, v32
	v_ashrrev_i32_e32 v30, 7, v31
	v_ashrrev_i32_e32 v31, 31, v30
	v_lshlrev_b64 v[30:31], 20, v[30:31]
	v_lshl_add_u64 v[30:31], s[0:1], 0, v[30:31]
	v_lshlrev_b32_e32 v32, 7, v32
	v_lshl_add_u64 v[30:31], v[30:31], 0, v[32:33]
	v_lshl_add_u64 v[30:31], v[30:31], 0, v[2:3]
	global_store_dwordx4 v[30:31], v[26:29], off sc0 sc1 nt
	ds_read2_b32 v[30:31], v9 offset0:48 offset1:56
	ds_read2_b32 v[32:33], v9 offset0:113 offset1:121
	ds_read2_b32 v[34:35], v9 offset0:178 offset1:186
	ds_read2_b32 v[36:37], v9 offset0:243 offset1:251
	ds_read2_b32 v[38:39], v25 offset0:52 offset1:60
	ds_read2_b32 v[40:41], v25 offset0:117 offset1:125
	ds_read2_b32 v[42:43], v25 offset0:182 offset1:190
	ds_read2_b32 v[44:45], v25 offset0:247 offset1:255
	s_waitcnt lgkmcnt(7)
	v_bfe_u32 v26, v30, 16, 1
	v_add3_u32 v26, v30, v26, s81
	s_waitcnt lgkmcnt(6)
	v_bfe_u32 v27, v32, 16, 1
	v_lshrrev_b32_e32 v26, 16, v26
	v_add3_u32 v27, v32, v27, s81
	v_and_or_b32 v26, v27, s39, v26
	s_waitcnt lgkmcnt(5)
	v_bfe_u32 v27, v34, 16, 1
	v_add3_u32 v27, v34, v27, s81
	s_waitcnt lgkmcnt(4)
	v_bfe_u32 v28, v36, 16, 1
	v_lshrrev_b32_e32 v27, 16, v27
	v_add3_u32 v28, v36, v28, s81
	v_and_or_b32 v27, v28, s39, v27
	s_waitcnt lgkmcnt(3)
	v_bfe_u32 v28, v38, 16, 1
	v_add3_u32 v28, v38, v28, s81
	s_waitcnt lgkmcnt(2)
	v_bfe_u32 v29, v40, 16, 1
	v_lshrrev_b32_e32 v28, 16, v28
	v_add3_u32 v29, v40, v29, s81
	s_waitcnt lgkmcnt(1)
	v_bfe_u32 v25, v42, 16, 1
	v_and_or_b32 v28, v29, s39, v28
	v_add3_u32 v25, v42, v25, s81
	s_waitcnt lgkmcnt(0)
	v_bfe_u32 v29, v44, 16, 1
	v_lshrrev_b32_e32 v25, 16, v25
	v_add3_u32 v29, v44, v29, s81
	v_and_or_b32 v29, v29, s39, v25
	v_add_u32_e32 v25, s2, v15
	v_cmp_lt_i32_e32 vcc, s41, v25
	s_nop 1
	v_cndmask_b32_e32 v30, 0, v247, vcc
	v_add_u32_e32 v30, v30, v25
	v_ashrrev_i32_e32 v46, 7, v30
	v_cndmask_b32_e32 v32, 0, v248, vcc
	v_ashrrev_i32_e32 v47, 31, v46
	v_and_or_b32 v25, v25, s40, v32
	v_lshlrev_b64 v[46:47], 20, v[46:47]
	v_lshl_add_u64 v[46:47], s[0:1], 0, v[46:47]
	v_lshlrev_b32_e32 v48, 7, v25
	v_lshl_add_u64 v[46:47], v[46:47], 0, v[48:49]
	v_lshl_add_u64 v[46:47], v[46:47], 0, v[2:3]
	v_bfe_u32 v25, v31, 16, 1
	global_store_dwordx4 v[46:47], v[26:29], off sc0 sc1 nt
	v_add3_u32 v25, v31, v25, s81
	v_lshrrev_b32_e32 v25, 16, v25
	v_bfe_u32 v26, v33, 16, 1
	v_add3_u32 v26, v33, v26, s81
	v_and_or_b32 v26, v26, s39, v25
	v_bfe_u32 v25, v35, 16, 1
	v_add3_u32 v25, v35, v25, s81
	v_bfe_u32 v27, v37, 16, 1
	v_lshrrev_b32_e32 v25, 16, v25
	v_add3_u32 v27, v37, v27, s81
	v_and_or_b32 v27, v27, s39, v25
	v_bfe_u32 v25, v39, 16, 1
	v_add3_u32 v25, v39, v25, s81
	v_bfe_u32 v28, v41, 16, 1
	v_lshrrev_b32_e32 v25, 16, v25
	v_add3_u32 v28, v41, v28, s81
	v_and_or_b32 v28, v28, s39, v25
	v_bfe_u32 v25, v43, 16, 1
	v_add3_u32 v25, v43, v25, s81
	v_bfe_u32 v29, v45, 16, 1
	v_lshrrev_b32_e32 v25, 16, v25
	v_add3_u32 v29, v45, v29, s81
	v_and_or_b32 v29, v29, s39, v25
	v_add_u32_e32 v25, s2, v16
	v_cmp_lt_i32_e32 vcc, s41, v25
	v_mov_b32_e32 v33, v3
	s_nop 0
	v_cndmask_b32_e32 v30, 0, v247, vcc
	v_add_u32_e32 v30, v30, v25
	v_cndmask_b32_e32 v31, 0, v248, vcc
	v_ashrrev_i32_e32 v30, 7, v30
	v_and_or_b32 v25, v25, s40, v31
	v_ashrrev_i32_e32 v31, 31, v30
	v_lshlrev_b64 v[30:31], 20, v[30:31]
	v_lshl_add_u64 v[30:31], s[0:1], 0, v[30:31]
	v_lshlrev_b32_e32 v32, 7, v25
	v_lshl_add_u64 v[30:31], v[30:31], 0, v[32:33]
	v_lshl_add_u64 v[30:31], v[30:31], 0, v[2:3]
	global_store_dwordx4 v[30:31], v[26:29], off sc0 sc1 nt
	s_waitcnt lgkmcnt(0)

.LBB0_954:
	s_andn2_b64 vcc, exec, s[0:1]
	s_cbranch_vccnz .LBB0_956
	s_load_dwordx2 s[0:1], s[6:7], 0x58
	s_add_i32 s2, s20, 0x3400
	s_and_b32 s23, s2, 0x1fc0
	s_add_i32 s2, s18, 0xfff4c000
	s_and_b32 s2, s2, 0x7c0
	s_add_i32 s3, s22, 0xffffd300
	v_add_u32_e32 v26, s23, v5
	s_lshl_b32 s23, s2, 2
	s_waitcnt lgkmcnt(0)
	s_add_u32 s0, s0, s23
	s_addc_u32 s1, s1, 0
	v_lshlrev_b32_e32 v2, 2, v4
	v_ashrrev_i32_e32 v27, 31, v26
	v_lshl_add_u64 v[28:29], s[0:1], 0, v[2:3]
	v_lshlrev_b64 v[26:27], 13, v[26:27]
	v_lshl_add_u64 v[86:87], v[28:29], 0, v[26:27]
	s_mov_b32 s0, 0x1000000
	v_add_co_u32_e32 v26, vcc, s0, v86
	s_mov_b32 s0, 0x1008000
	s_nop 0
	v_addc_co_u32_e32 v27, vcc, 0, v87, vcc
	v_add_co_u32_e32 v30, vcc, s0, v86
	s_mov_b32 s0, 0x1010000
	s_nop 0
	v_addc_co_u32_e32 v31, vcc, 0, v87, vcc
	v_add_co_u32_e32 v34, vcc, s0, v86
	global_load_dwordx4 v[26:29], v[26:27], off nt
	s_nop 0
	global_load_dwordx4 v[30:33], v[30:31], off nt
	v_addc_co_u32_e32 v35, vcc, 0, v87, vcc
	s_mov_b32 s0, 0x1018000
	v_add_co_u32_e32 v38, vcc, s0, v86
	s_mov_b32 s0, 0x1020000
	s_nop 0
	v_addc_co_u32_e32 v39, vcc, 0, v87, vcc
	global_load_dwordx4 v[34:37], v[34:35], off nt
	s_nop 0
	global_load_dwordx4 v[38:41], v[38:39], off nt
	v_add_co_u32_e32 v42, vcc, s0, v86
	s_mov_b32 s0, 0x1028000
	s_nop 0
	v_addc_co_u32_e32 v43, vcc, 0, v87, vcc
	v_add_co_u32_e32 v46, vcc, s0, v86
	s_mov_b32 s0, 0x1030000
	s_nop 0
	v_addc_co_u32_e32 v47, vcc, 0, v87, vcc
	global_load_dwordx4 v[42:45], v[42:43], off nt
	s_nop 0
	global_load_dwordx4 v[46:49], v[46:47], off nt
	v_add_co_u32_e32 v50, vcc, s0, v86
	s_mov_b32 s0, 0x1038000
	s_nop 0
	v_addc_co_u32_e32 v51, vcc, 0, v87, vcc
	v_add_co_u32_e32 v54, vcc, s0, v86
	s_mov_b32 s0, 0x1040000
	s_nop 0
	v_addc_co_u32_e32 v55, vcc, 0, v87, vcc
	global_load_dwordx4 v[50:53], v[50:51], off nt
	s_nop 0
	global_load_dwordx4 v[54:57], v[54:55], off nt
	v_add_co_u32_e32 v58, vcc, s0, v86
	s_mov_b32 s0, 0x1048000
	s_nop 0
	v_addc_co_u32_e32 v59, vcc, 0, v87, vcc
	v_add_co_u32_e32 v62, vcc, s0, v86
	s_mov_b32 s0, 0x1050000
	s_nop 0
	v_addc_co_u32_e32 v63, vcc, 0, v87, vcc
	global_load_dwordx4 v[58:61], v[58:59], off nt
	s_nop 0
	global_load_dwordx4 v[62:65], v[62:63], off nt
	v_add_co_u32_e32 v66, vcc, s0, v86
	s_mov_b32 s0, 0x1058000
	s_nop 0
	v_addc_co_u32_e32 v67, vcc, 0, v87, vcc
	v_add_co_u32_e32 v70, vcc, s0, v86
	s_mov_b32 s0, 0x1060000
	s_nop 0
	v_addc_co_u32_e32 v71, vcc, 0, v87, vcc
	global_load_dwordx4 v[66:69], v[66:67], off nt
	s_nop 0
	global_load_dwordx4 v[70:73], v[70:71], off nt
	v_add_co_u32_e32 v74, vcc, s0, v86
	s_mov_b32 s0, 0x1068000
	s_nop 0
	v_addc_co_u32_e32 v75, vcc, 0, v87, vcc
	global_load_dwordx4 v[74:77], v[74:75], off nt
	v_add_co_u32_e32 v78, vcc, s0, v86
	s_mov_b32 s0, 0x1070000
	s_nop 0
	v_addc_co_u32_e32 v79, vcc, 0, v87, vcc
	global_load_dwordx4 v[78:81], v[78:79], off nt
	v_add_co_u32_e32 v82, vcc, s0, v86
	s_mov_b32 s0, 0x1078000
	s_nop 0
	v_addc_co_u32_e32 v83, vcc, 0, v87, vcc
	global_load_dwordx4 v[82:85], v[82:83], off nt
	v_add_co_u32_e32 v86, vcc, s0, v86
	v_add_u32_e32 v2, 0x410, v7
	s_nop 0
	v_addc_co_u32_e32 v87, vcc, 0, v87, vcc
	global_load_dwordx4 v[86:89], v[86:87], off nt
	s_waitcnt vmcnt(0)
	ds_write2_b32 v7, v26, v27 offset1:1
	ds_write2_b32 v7, v28, v29 offset0:2 offset1:3
	ds_write2_b32 v2, v30, v31 offset1:1
	v_add_u32_e32 v2, 0x418, v7
	ds_write2_b32 v2, v32, v33 offset1:1
	v_add_u32_e32 v2, 0x820, v7
	s_lshr_b32 s72, s3, 5
	s_lshl_b64 s[0:1], s[72:73], 15
	ds_write2_b32 v2, v34, v35 offset1:1
	v_add_u32_e32 v2, 0x828, v7
	ds_write2_b32 v2, v36, v37 offset1:1
	v_add_u32_e32 v2, 0xc30, v7
	ds_write2_b32 v2, v38, v39 offset1:1
	v_add_u32_e32 v2, 0xc38, v7
	ds_write2_b32 v2, v40, v41 offset1:1
	v_add_u32_e32 v2, 0x1040, v7
	ds_write2_b32 v2, v42, v43 offset1:1
	v_add_u32_e32 v2, 0x1048, v7
	ds_write2_b32 v2, v44, v45 offset1:1
	v_add_u32_e32 v2, 0x1450, v7
	ds_write2_b32 v2, v46, v47 offset1:1
	v_add_u32_e32 v2, 0x1458, v7
	ds_write2_b32 v2, v48, v49 offset1:1
	v_add_u32_e32 v2, 0x1860, v7
	v_mov_b32_e32 v49, v3
	ds_write2_b32 v2, v50, v51 offset1:1
	v_add_u32_e32 v2, 0x1868, v7
	ds_write2_b32 v2, v52, v53 offset1:1
	v_add_u32_e32 v2, 0x1c70, v7
	ds_write2_b32 v2, v54, v55 offset1:1
	v_add_u32_e32 v2, 0x1c78, v7
	ds_write2_b32 v2, v56, v57 offset1:1
	v_add_u32_e32 v2, 0x2080, v7
	ds_write2_b32 v2, v58, v59 offset1:1
	v_add_u32_e32 v2, 0x2088, v7
	ds_write2_b32 v2, v60, v61 offset1:1
	v_add_u32_e32 v2, 0x2490, v7
	ds_write2_b32 v2, v62, v63 offset1:1
	v_add_u32_e32 v2, 0x2498, v7
	ds_write2_b32 v2, v64, v65 offset1:1
	v_add_u32_e32 v2, 0x28a0, v7
	ds_write2_b32 v2, v66, v67 offset1:1
	v_add_u32_e32 v2, 0x28a8, v7
	ds_write2_b32 v2, v68, v69 offset1:1
	v_add_u32_e32 v2, 0x2cb0, v7
	ds_write2_b32 v2, v70, v71 offset1:1
	v_add_u32_e32 v2, 0x2cb8, v7
	ds_write2_b32 v2, v72, v73 offset1:1
	v_add_u32_e32 v2, 0x30c0, v7
	ds_write2_b32 v2, v74, v75 offset1:1
	v_add_u32_e32 v2, 0x30c8, v7
	ds_write2_b32 v2, v76, v77 offset1:1
	v_add_u32_e32 v2, 0x34d0, v7
	ds_write2_b32 v2, v78, v79 offset1:1
	v_add_u32_e32 v2, 0x34d8, v7
	ds_write2_b32 v2, v80, v81 offset1:1
	v_add_u32_e32 v2, 0x38e0, v7
	ds_write2_b32 v2, v82, v83 offset1:1
	v_add_u32_e32 v2, 0x38e8, v7
	ds_write2_b32 v2, v84, v85 offset1:1
	v_add_u32_e32 v2, 0x3cf0, v7
	ds_write2_b32 v2, v86, v87 offset1:1
	v_add_u32_e32 v2, 0x3cf8, v7
	ds_write2_b32 v2, v88, v89 offset1:1
	s_waitcnt lgkmcnt(0)
	ds_read2_b32 v[30:31], v9 offset1:8
	ds_read2_b32 v[32:33], v9 offset0:65 offset1:73
	ds_read2_b32 v[34:35], v9 offset0:130 offset1:138
	ds_read2_b32 v[36:37], v9 offset0:195 offset1:203
	s_waitcnt lgkmcnt(3)
	v_bfe_u32 v2, v30, 16, 1
	v_add3_u32 v2, v30, v2, s81
	s_waitcnt lgkmcnt(2)
	v_bfe_u32 v25, v32, 16, 1
	v_lshrrev_b32_e32 v2, 16, v2
	v_add3_u32 v25, v32, v25, s81
	v_and_or_b32 v26, v25, s39, v2
	v_add_u32_e32 v25, 0x400, v9
	ds_read2_b32 v[38:39], v25 offset0:4 offset1:12
	ds_read2_b32 v[40:41], v25 offset0:69 offset1:77
	s_waitcnt lgkmcnt(3)
	v_bfe_u32 v2, v34, 16, 1
	v_add3_u32 v2, v34, v2, s81
	s_waitcnt lgkmcnt(2)
	v_bfe_u32 v27, v36, 16, 1
	ds_read2_b32 v[42:43], v25 offset0:134 offset1:142
	v_lshrrev_b32_e32 v2, 16, v2
	v_add3_u32 v27, v36, v27, s81
	ds_read2_b32 v[44:45], v25 offset0:199 offset1:207
	v_and_or_b32 v27, v27, s39, v2
	s_waitcnt lgkmcnt(3)
	v_bfe_u32 v2, v38, 16, 1
	v_add3_u32 v2, v38, v2, s81
	s_waitcnt lgkmcnt(2)
	v_bfe_u32 v28, v40, 16, 1
	v_lshrrev_b32_e32 v2, 16, v2
	v_add3_u32 v28, v40, v28, s81
	v_and_or_b32 v28, v28, s39, v2
	s_waitcnt lgkmcnt(1)
	v_bfe_u32 v2, v42, 16, 1
	v_add3_u32 v2, v42, v2, s81
	s_waitcnt lgkmcnt(0)
	v_bfe_u32 v29, v44, 16, 1
	v_lshrrev_b32_e32 v2, 16, v2
	v_add3_u32 v29, v44, v29, s81
	v_and_or_b32 v29, v29, s39, v2
	v_add_u32_e32 v2, s2, v8
	v_ashrrev_i32_e32 v46, 8, v2
	v_ashrrev_i32_e32 v47, 31, v46
	v_lshlrev_b64 v[46:47], 20, v[46:47]
	v_lshl_add_u64 v[46:47], s[10:11], 0, v[46:47]
	v_lshlrev_b32_e32 v2, 7, v2
	v_lshl_add_u64 v[46:47], v[46:47], 0, s[0:1]
	v_and_b32_e32 v2, 0x7f80, v2
	v_lshl_add_u64 v[46:47], v[46:47], 0, v[2:3]
	v_lshlrev_b32_e32 v2, 1, v6
	v_lshl_add_u64 v[46:47], v[46:47], 0, v[2:3]
	global_store_dwordx4 v[46:47], v[26:29], off sc0 sc1 nt
	v_bfe_u32 v30, v45, 16, 1
	v_add3_u32 v30, v45, v30, s81
	v_bfe_u32 v26, v31, 16, 1
	v_add3_u32 v26, v31, v26, s81
	v_bfe_u32 v27, v33, 16, 1
	v_lshrrev_b32_e32 v26, 16, v26
	v_add3_u32 v27, v33, v27, s81
	v_and_or_b32 v26, v27, s39, v26
	v_bfe_u32 v27, v35, 16, 1
	v_add3_u32 v27, v35, v27, s81
	v_bfe_u32 v28, v37, 16, 1
	v_lshrrev_b32_e32 v27, 16, v27
	v_add3_u32 v28, v37, v28, s81
	v_and_or_b32 v27, v28, s39, v27
	v_bfe_u32 v28, v39, 16, 1
	v_add3_u32 v28, v39, v28, s81
	v_bfe_u32 v29, v41, 16, 1
	v_lshrrev_b32_e32 v28, 16, v28
	v_add3_u32 v29, v41, v29, s81
	v_and_or_b32 v28, v29, s39, v28
	v_bfe_u32 v29, v43, 16, 1
	v_add3_u32 v29, v43, v29, s81
	v_lshrrev_b32_e32 v29, 16, v29
	v_add_u32_e32 v32, s2, v10
	v_and_or_b32 v29, v30, s39, v29
	v_ashrrev_i32_e32 v30, 8, v32
	v_ashrrev_i32_e32 v31, 31, v30
	v_lshlrev_b64 v[30:31], 20, v[30:31]
	v_lshl_add_u64 v[30:31], s[10:11], 0, v[30:31]
	v_lshlrev_b32_e32 v32, 7, v32
	v_lshl_add_u64 v[30:31], v[30:31], 0, s[0:1]
	v_and_b32_e32 v32, 0x7f80, v32
	v_mov_b32_e32 v33, v3
	v_lshl_add_u64 v[30:31], v[30:31], 0, v[32:33]
	ds_read2_b32 v[34:35], v9 offset0:16 offset1:24
	v_lshl_add_u64 v[30:31], v[30:31], 0, v[2:3]
	global_store_dwordx4 v[30:31], v[26:29], off sc0 sc1 nt
	ds_read2_b32 v[30:31], v9 offset0:81 offset1:89
	ds_read2_b32 v[32:33], v9 offset0:146 offset1:154
	ds_read2_b32 v[36:37], v9 offset0:211 offset1:219
	s_waitcnt lgkmcnt(3)
	v_bfe_u32 v26, v34, 16, 1
	v_add3_u32 v26, v34, v26, s81
	s_waitcnt lgkmcnt(2)
	v_bfe_u32 v27, v30, 16, 1
	ds_read2_b32 v[38:39], v25 offset0:20 offset1:28
	v_lshrrev_b32_e32 v26, 16, v26
	v_add3_u32 v27, v30, v27, s81
	ds_read2_b32 v[40:41], v25 offset0:85 offset1:93
	v_and_or_b32 v26, v27, s39, v26
	s_waitcnt lgkmcnt(3)
	v_bfe_u32 v27, v32, 16, 1
	v_add3_u32 v27, v32, v27, s81
	s_waitcnt lgkmcnt(2)
	v_bfe_u32 v28, v36, 16, 1
	ds_read2_b32 v[42:43], v25 offset0:150 offset1:158
	v_lshrrev_b32_e32 v27, 16, v27
	v_add3_u32 v28, v36, v28, s81
	ds_read2_b32 v[44:45], v25 offset0:215 offset1:223
	v_and_or_b32 v27, v28, s39, v27
	s_waitcnt lgkmcnt(3)
	v_bfe_u32 v28, v38, 16, 1
	v_add3_u32 v28, v38, v28, s81
	s_waitcnt lgkmcnt(2)
	v_bfe_u32 v29, v40, 16, 1
	v_lshrrev_b32_e32 v28, 16, v28
	v_add3_u32 v29, v40, v29, s81
	v_and_or_b32 v28, v29, s39, v28
	s_waitcnt lgkmcnt(1)
	v_bfe_u32 v29, v42, 16, 1
	v_add3_u32 v29, v42, v29, s81
	s_waitcnt lgkmcnt(0)
	v_bfe_u32 v30, v44, 16, 1
	v_lshrrev_b32_e32 v29, 16, v29
	v_add3_u32 v30, v44, v30, s81
	v_and_or_b32 v29, v30, s39, v29
	v_add_u32_e32 v30, s2, v11
	v_ashrrev_i32_e32 v46, 8, v30
	v_ashrrev_i32_e32 v47, 31, v46
	v_lshlrev_b64 v[46:47], 20, v[46:47]
	v_lshl_add_u64 v[46:47], s[10:11], 0, v[46:47]
	v_lshlrev_b32_e32 v30, 7, v30
	v_lshl_add_u64 v[46:47], v[46:47], 0, s[0:1]
	v_and_b32_e32 v48, 0x7f80, v30
	v_lshl_add_u64 v[46:47], v[46:47], 0, v[48:49]
	v_lshl_add_u64 v[46:47], v[46:47], 0, v[2:3]
	global_store_dwordx4 v[46:47], v[26:29], off sc0 sc1 nt
	v_bfe_u32 v30, v45, 16, 1
	v_add3_u32 v30, v45, v30, s81
	v_bfe_u32 v26, v35, 16, 1
	v_add3_u32 v26, v35, v26, s81
	v_bfe_u32 v27, v31, 16, 1
	v_lshrrev_b32_e32 v26, 16, v26
	v_add3_u32 v27, v31, v27, s81
	v_and_or_b32 v26, v27, s39, v26
	v_bfe_u32 v27, v33, 16, 1
	v_add3_u32 v27, v33, v27, s81
	v_bfe_u32 v28, v37, 16, 1
	v_lshrrev_b32_e32 v27, 16, v27
	v_add3_u32 v28, v37, v28, s81
	v_and_or_b32 v27, v28, s39, v27
	v_bfe_u32 v28, v39, 16, 1
	v_add3_u32 v28, v39, v28, s81
	v_bfe_u32 v29, v41, 16, 1
	v_lshrrev_b32_e32 v28, 16, v28
	v_add3_u32 v29, v41, v29, s81
	v_and_or_b32 v28, v29, s39, v28
	v_bfe_u32 v29, v43, 16, 1
	v_add3_u32 v29, v43, v29, s81
	v_lshrrev_b32_e32 v29, 16, v29
	v_add_u32_e32 v32, s2, v12
	v_and_or_b32 v29, v30, s39, v29
	v_ashrrev_i32_e32 v30, 8, v32
	v_ashrrev_i32_e32 v31, 31, v30
	v_lshlrev_b64 v[30:31], 20, v[30:31]
	v_lshl_add_u64 v[30:31], s[10:11], 0, v[30:31]
	v_lshlrev_b32_e32 v32, 7, v32
	v_lshl_add_u64 v[30:31], v[30:31], 0, s[0:1]
	v_and_b32_e32 v32, 0x7f80, v32
	v_mov_b32_e32 v33, v3
	v_lshl_add_u64 v[30:31], v[30:31], 0, v[32:33]
	ds_read2_b32 v[34:35], v9 offset0:32 offset1:40
	v_lshl_add_u64 v[30:31], v[30:31], 0, v[2:3]
	global_store_dwordx4 v[30:31], v[26:29], off sc0 sc1 nt
	ds_read2_b32 v[30:31], v9 offset0:97 offset1:105
	ds_read2_b32 v[32:33], v9 offset0:162 offset1:170
	ds_read2_b32 v[36:37], v9 offset0:227 offset1:235
	s_waitcnt lgkmcnt(3)
	v_bfe_u32 v26, v34, 16, 1
	v_add3_u32 v26, v34, v26, s81
	s_waitcnt lgkmcnt(2)
	v_bfe_u32 v27, v30, 16, 1
	ds_read2_b32 v[38:39], v25 offset0:36 offset1:44
	v_lshrrev_b32_e32 v26, 16, v26
	v_add3_u32 v27, v30, v27, s81
	ds_read2_b32 v[40:41], v25 offset0:101 offset1:109
	v_and_or_b32 v26, v27, s39, v26
	s_waitcnt lgkmcnt(3)
	v_bfe_u32 v27, v32, 16, 1
	v_add3_u32 v27, v32, v27, s81
	s_waitcnt lgkmcnt(2)
	v_bfe_u32 v28, v36, 16, 1
	ds_read2_b32 v[42:43], v25 offset0:166 offset1:174
	v_lshrrev_b32_e32 v27, 16, v27
	v_add3_u32 v28, v36, v28, s81
	ds_read2_b32 v[44:45], v25 offset0:231 offset1:239
	v_and_or_b32 v27, v28, s39, v27
	s_waitcnt lgkmcnt(3)
	v_bfe_u32 v28, v38, 16, 1
	v_add3_u32 v28, v38, v28, s81
	s_waitcnt lgkmcnt(2)
	v_bfe_u32 v29, v40, 16, 1
	v_lshrrev_b32_e32 v28, 16, v28
	v_add3_u32 v29, v40, v29, s81
	v_and_or_b32 v28, v29, s39, v28
	s_waitcnt lgkmcnt(1)
	v_bfe_u32 v29, v42, 16, 1
	v_add3_u32 v29, v42, v29, s81
	s_waitcnt lgkmcnt(0)
	v_bfe_u32 v30, v44, 16, 1
	v_lshrrev_b32_e32 v29, 16, v29
	v_add3_u32 v30, v44, v30, s81
	v_and_or_b32 v29, v30, s39, v29
	v_add_u32_e32 v30, s2, v13
	v_ashrrev_i32_e32 v46, 8, v30
	v_ashrrev_i32_e32 v47, 31, v46
	v_lshlrev_b64 v[46:47], 20, v[46:47]
	v_lshl_add_u64 v[46:47], s[10:11], 0, v[46:47]
	v_lshlrev_b32_e32 v30, 7, v30
	v_lshl_add_u64 v[46:47], v[46:47], 0, s[0:1]
	v_and_b32_e32 v48, 0x7f80, v30
	v_lshl_add_u64 v[46:47], v[46:47], 0, v[48:49]
	v_lshl_add_u64 v[46:47], v[46:47], 0, v[2:3]
	global_store_dwordx4 v[46:47], v[26:29], off sc0 sc1 nt
	v_bfe_u32 v30, v45, 16, 1
	v_add3_u32 v30, v45, v30, s81
	v_bfe_u32 v26, v35, 16, 1
	v_add3_u32 v26, v35, v26, s81
	v_bfe_u32 v27, v31, 16, 1
	v_lshrrev_b32_e32 v26, 16, v26
	v_add3_u32 v27, v31, v27, s81
	v_and_or_b32 v26, v27, s39, v26
	v_bfe_u32 v27, v33, 16, 1
	v_add3_u32 v27, v33, v27, s81
	v_bfe_u32 v28, v37, 16, 1
	v_lshrrev_b32_e32 v27, 16, v27
	v_add3_u32 v28, v37, v28, s81
	v_and_or_b32 v27, v28, s39, v27
	v_bfe_u32 v28, v39, 16, 1
	v_add3_u32 v28, v39, v28, s81
	v_bfe_u32 v29, v41, 16, 1
	v_lshrrev_b32_e32 v28, 16, v28
	v_add3_u32 v29, v41, v29, s81
	v_and_or_b32 v28, v29, s39, v28
	v_bfe_u32 v29, v43, 16, 1
	v_add3_u32 v29, v43, v29, s81
	v_lshrrev_b32_e32 v29, 16, v29
	v_add_u32_e32 v32, s2, v14
	v_and_or_b32 v29, v30, s39, v29
	v_ashrrev_i32_e32 v30, 8, v32
	v_ashrrev_i32_e32 v31, 31, v30
	v_lshlrev_b64 v[30:31], 20, v[30:31]
	v_lshl_add_u64 v[30:31], s[10:11], 0, v[30:31]
	v_lshlrev_b32_e32 v32, 7, v32
	v_lshl_add_u64 v[30:31], v[30:31], 0, s[0:1]
	v_and_b32_e32 v32, 0x7f80, v32
	v_mov_b32_e32 v33, v3
	v_lshl_add_u64 v[30:31], v[30:31], 0, v[32:33]
	ds_read2_b32 v[34:35], v9 offset0:48 offset1:56
	v_lshl_add_u64 v[30:31], v[30:31], 0, v[2:3]
	global_store_dwordx4 v[30:31], v[26:29], off sc0 sc1 nt
	ds_read2_b32 v[30:31], v9 offset0:113 offset1:121
	ds_read2_b32 v[32:33], v9 offset0:178 offset1:186
	ds_read2_b32 v[36:37], v9 offset0:243 offset1:251
	s_waitcnt lgkmcnt(3)
	v_bfe_u32 v26, v34, 16, 1
	v_add3_u32 v26, v34, v26, s81
	s_waitcnt lgkmcnt(2)
	v_bfe_u32 v27, v30, 16, 1
	ds_read2_b32 v[38:39], v25 offset0:52 offset1:60
	v_lshrrev_b32_e32 v26, 16, v26
	v_add3_u32 v27, v30, v27, s81
	ds_read2_b32 v[40:41], v25 offset0:117 offset1:125
	v_and_or_b32 v26, v27, s39, v26
	s_waitcnt lgkmcnt(3)
	v_bfe_u32 v27, v32, 16, 1
	ds_read2_b32 v[42:43], v25 offset0:182 offset1:190
	v_add3_u32 v27, v32, v27, s81
	s_waitcnt lgkmcnt(3)
	v_bfe_u32 v28, v36, 16, 1
	ds_read2_b32 v[44:45], v25 offset0:247 offset1:255
	v_lshrrev_b32_e32 v27, 16, v27
	v_add3_u32 v28, v36, v28, s81
	v_and_or_b32 v27, v28, s39, v27
	s_waitcnt lgkmcnt(3)
	v_bfe_u32 v28, v38, 16, 1
	v_add3_u32 v28, v38, v28, s81
	s_waitcnt lgkmcnt(2)
	v_bfe_u32 v29, v40, 16, 1
	v_lshrrev_b32_e32 v28, 16, v28
	v_add3_u32 v29, v40, v29, s81
	s_waitcnt lgkmcnt(1)
	v_bfe_u32 v25, v42, 16, 1
	v_and_or_b32 v28, v29, s39, v28
	v_add3_u32 v25, v42, v25, s81
	s_waitcnt lgkmcnt(0)
	v_bfe_u32 v29, v44, 16, 1
	v_lshrrev_b32_e32 v25, 16, v25
	v_add3_u32 v29, v44, v29, s81
	v_and_or_b32 v29, v29, s39, v25
	v_add_u32_e32 v25, s2, v15
	v_ashrrev_i32_e32 v46, 8, v25
	v_ashrrev_i32_e32 v47, 31, v46
	v_lshlrev_b64 v[46:47], 20, v[46:47]
	v_lshl_add_u64 v[46:47], s[10:11], 0, v[46:47]
	v_lshlrev_b32_e32 v25, 7, v25
	v_lshl_add_u64 v[46:47], v[46:47], 0, s[0:1]
	v_and_b32_e32 v48, 0x7f80, v25
	v_lshl_add_u64 v[46:47], v[46:47], 0, v[48:49]
	v_lshl_add_u64 v[46:47], v[46:47], 0, v[2:3]
	v_bfe_u32 v25, v35, 16, 1
	global_store_dwordx4 v[46:47], v[26:29], off sc0 sc1 nt
	v_add3_u32 v25, v35, v25, s81
	v_lshrrev_b32_e32 v25, 16, v25
	v_bfe_u32 v26, v31, 16, 1
	v_add3_u32 v26, v31, v26, s81
	v_and_or_b32 v26, v26, s39, v25
	v_bfe_u32 v25, v33, 16, 1
	v_add3_u32 v25, v33, v25, s81
	v_bfe_u32 v27, v37, 16, 1
	v_lshrrev_b32_e32 v25, 16, v25
	v_add3_u32 v27, v37, v27, s81
	v_and_or_b32 v27, v27, s39, v25
	v_bfe_u32 v25, v39, 16, 1
	v_add3_u32 v25, v39, v25, s81
	v_bfe_u32 v28, v41, 16, 1
	v_lshrrev_b32_e32 v25, 16, v25
	v_add3_u32 v28, v41, v28, s81
	v_and_or_b32 v28, v28, s39, v25
	v_bfe_u32 v25, v43, 16, 1
	v_add3_u32 v25, v43, v25, s81
	v_bfe_u32 v29, v45, 16, 1
	v_lshrrev_b32_e32 v25, 16, v25
	v_add3_u32 v29, v45, v29, s81
	v_and_or_b32 v29, v29, s39, v25
	v_add_u32_e32 v25, s2, v16
	v_ashrrev_i32_e32 v30, 8, v25
	v_ashrrev_i32_e32 v31, 31, v30
	v_lshlrev_b64 v[30:31], 20, v[30:31]
	v_lshl_add_u64 v[30:31], s[10:11], 0, v[30:31]
	v_lshlrev_b32_e32 v25, 7, v25
	v_lshl_add_u64 v[30:31], v[30:31], 0, s[0:1]
	v_and_b32_e32 v32, 0x7f80, v25
	v_mov_b32_e32 v33, v3
	v_lshl_add_u64 v[30:31], v[30:31], 0, v[32:33]
	v_lshl_add_u64 v[30:31], v[30:31], 0, v[2:3]
	global_store_dwordx4 v[30:31], v[26:29], off sc0 sc1 nt
	s_waitcnt lgkmcnt(0)

.LBB0_957:
	s_andn2_b64 vcc, exec, s[0:1]
	s_cbranch_vccnz .LBB0_959
	s_add_i32 s1, s22, 0xdf00
	s_and_b32 s0, s1, 0xffff
	s_mul_i32 s0, s0, 0xaaab
	s_lshr_b32 s0, s0, 22
	s_load_dwordx2 s[24:25], s[6:7], 0x50
	s_mul_i32 s2, s0, 0x60
	s_sub_i32 s1, s1, s2
	s_lshl_b32 s1, s1, 6
	s_and_b32 s2, s1, 0xffc0
	s_lshl_b32 s1, s2, 2
	s_waitcnt lgkmcnt(0)
	s_add_u32 s24, s24, s1
	s_addc_u32 s25, s25, 0
	v_lshlrev_b32_e32 v2, 2, v4
	v_lshl_add_u32 v25, s0, 6, v5
	v_lshl_add_u64 v[26:27], s[24:25], 0, v[2:3]
	s_mov_b64 s[24:25], 0x3000000
	v_lshl_add_u64 v[86:87], v[26:27], 0, s[24:25]
	s_movk_i32 s1, 0x6000
	v_add_u32_e32 v2, 4, v25
	v_mad_i64_i32 v[26:27], s[24:25], v25, s1, v[86:87]
	v_mad_i64_i32 v[30:31], s[24:25], v2, s1, v[86:87]
	global_load_dwordx4 v[26:29], v[26:27], off nt
	v_add_u32_e32 v2, 8, v25
	global_load_dwordx4 v[30:33], v[30:31], off nt
	v_mad_i64_i32 v[34:35], s[24:25], v2, s1, v[86:87]
	global_load_dwordx4 v[34:37], v[34:35], off nt
	v_add_u32_e32 v2, 12, v25
	v_mad_i64_i32 v[38:39], s[24:25], v2, s1, v[86:87]
	global_load_dwordx4 v[38:41], v[38:39], off nt
	v_add_u32_e32 v2, 16, v25
	v_mad_i64_i32 v[42:43], s[24:25], v2, s1, v[86:87]
	global_load_dwordx4 v[42:45], v[42:43], off nt
	v_add_u32_e32 v2, 20, v25
	v_mad_i64_i32 v[46:47], s[24:25], v2, s1, v[86:87]
	global_load_dwordx4 v[46:49], v[46:47], off nt
	v_add_u32_e32 v2, 24, v25
	v_mad_i64_i32 v[50:51], s[24:25], v2, s1, v[86:87]
	global_load_dwordx4 v[50:53], v[50:51], off nt
	v_add_u32_e32 v2, 28, v25
	v_mad_i64_i32 v[54:55], s[24:25], v2, s1, v[86:87]
	global_load_dwordx4 v[54:57], v[54:55], off nt
	v_add_u32_e32 v2, 32, v25
	v_mad_i64_i32 v[58:59], s[24:25], v2, s1, v[86:87]
	global_load_dwordx4 v[58:61], v[58:59], off nt
	v_add_u32_e32 v2, 36, v25
	v_mad_i64_i32 v[62:63], s[24:25], v2, s1, v[86:87]
	global_load_dwordx4 v[62:65], v[62:63], off nt
	v_add_u32_e32 v2, 40, v25
	v_mad_i64_i32 v[66:67], s[24:25], v2, s1, v[86:87]
	global_load_dwordx4 v[66:69], v[66:67], off nt
	v_add_u32_e32 v2, 44, v25
	v_mad_i64_i32 v[70:71], s[24:25], v2, s1, v[86:87]
	global_load_dwordx4 v[70:73], v[70:71], off nt
	v_add_u32_e32 v2, 48, v25
	v_mad_i64_i32 v[74:75], s[24:25], v2, s1, v[86:87]
	global_load_dwordx4 v[74:77], v[74:75], off nt
	v_add_u32_e32 v2, 52, v25
	v_mad_i64_i32 v[78:79], s[24:25], v2, s1, v[86:87]
	global_load_dwordx4 v[78:81], v[78:79], off nt
	v_add_u32_e32 v2, 56, v25
	v_mad_i64_i32 v[82:83], s[24:25], v2, s1, v[86:87]
	global_load_dwordx4 v[82:85], v[82:83], off nt
	v_add_u32_e32 v2, 60, v25
	v_mad_i64_i32 v[86:87], s[24:25], v2, s1, v[86:87]
	global_load_dwordx4 v[86:89], v[86:87], off nt
	v_add_u32_e32 v2, 0x410, v7
	s_movk_i32 s3, 0x800
	s_lshl_b32 s0, s0, 15
	s_add_u32 s0, s16, s0
	s_addc_u32 s1, s17, 0
	s_waitcnt vmcnt(0)
	ds_write2_b32 v7, v26, v27 offset1:1
	ds_write2_b32 v7, v28, v29 offset0:2 offset1:3
	ds_write2_b32 v2, v30, v31 offset1:1
	v_add_u32_e32 v2, 0x418, v7
	ds_write2_b32 v2, v32, v33 offset1:1
	v_add_u32_e32 v2, 0x820, v7
	ds_write2_b32 v2, v34, v35 offset1:1
	v_add_u32_e32 v2, 0x828, v7
	ds_write2_b32 v2, v36, v37 offset1:1
	v_add_u32_e32 v2, 0xc30, v7
	ds_write2_b32 v2, v38, v39 offset1:1
	v_add_u32_e32 v2, 0xc38, v7
	ds_write2_b32 v2, v40, v41 offset1:1
	v_add_u32_e32 v2, 0x1040, v7
	ds_write2_b32 v2, v42, v43 offset1:1
	v_add_u32_e32 v2, 0x1048, v7
	ds_write2_b32 v2, v44, v45 offset1:1
	v_add_u32_e32 v2, 0x1450, v7
	ds_write2_b32 v2, v46, v47 offset1:1
	v_add_u32_e32 v2, 0x1458, v7
	ds_write2_b32 v2, v48, v49 offset1:1
	v_add_u32_e32 v2, 0x1860, v7
	ds_write2_b32 v2, v50, v51 offset1:1
	v_add_u32_e32 v2, 0x1868, v7
	ds_write2_b32 v2, v52, v53 offset1:1
	v_add_u32_e32 v2, 0x1c70, v7
	ds_write2_b32 v2, v54, v55 offset1:1
	v_add_u32_e32 v2, 0x1c78, v7
	ds_write2_b32 v2, v56, v57 offset1:1
	v_add_u32_e32 v2, 0x2080, v7
	ds_write2_b32 v2, v58, v59 offset1:1
	v_add_u32_e32 v2, 0x2088, v7
	ds_write2_b32 v2, v60, v61 offset1:1
	v_add_u32_e32 v2, 0x2490, v7
	ds_write2_b32 v2, v62, v63 offset1:1
	v_add_u32_e32 v2, 0x2498, v7
	ds_write2_b32 v2, v64, v65 offset1:1
	v_add_u32_e32 v2, 0x28a0, v7
	ds_write2_b32 v2, v66, v67 offset1:1
	v_add_u32_e32 v2, 0x28a8, v7
	ds_write2_b32 v2, v68, v69 offset1:1
	v_add_u32_e32 v2, 0x2cb0, v7
	ds_write2_b32 v2, v70, v71 offset1:1
	v_add_u32_e32 v2, 0x2cb8, v7
	ds_write2_b32 v2, v72, v73 offset1:1
	v_add_u32_e32 v2, 0x30c0, v7
	ds_write2_b32 v2, v74, v75 offset1:1
	v_add_u32_e32 v2, 0x30c8, v7
	ds_write2_b32 v2, v76, v77 offset1:1
	v_add_u32_e32 v2, 0x34d0, v7
	ds_write2_b32 v2, v78, v79 offset1:1
	v_add_u32_e32 v2, 0x34d8, v7
	ds_write2_b32 v2, v80, v81 offset1:1
	v_add_u32_e32 v2, 0x38e0, v7
	ds_write2_b32 v2, v82, v83 offset1:1
	v_add_u32_e32 v2, 0x38e8, v7
	ds_write2_b32 v2, v84, v85 offset1:1
	v_add_u32_e32 v2, 0x3cf0, v7
	ds_write2_b32 v2, v86, v87 offset1:1
	v_add_u32_e32 v2, 0x3cf8, v7
	ds_write2_b32 v2, v88, v89 offset1:1
	s_waitcnt lgkmcnt(0)
	ds_read2_b32 v[30:31], v9 offset0:65 offset1:73
	ds_read2_b32 v[32:33], v9 offset1:8
	ds_read2_b32 v[34:35], v9 offset0:130 offset1:138
	ds_read2_b32 v[36:37], v9 offset0:195 offset1:203
	v_mov_b32_e32 v49, v3
	s_waitcnt lgkmcnt(3)
	v_bfe_u32 v25, v30, 16, 1
	s_waitcnt lgkmcnt(2)
	v_bfe_u32 v2, v32, 16, 1
	v_add3_u32 v2, v32, v2, s81
	v_lshrrev_b32_e32 v2, 16, v2
	v_add3_u32 v25, v30, v25, s81
	v_and_or_b32 v26, v25, s39, v2
	s_waitcnt lgkmcnt(1)
	v_bfe_u32 v2, v34, 16, 1
	v_add3_u32 v2, v34, v2, s81
	s_waitcnt lgkmcnt(0)
	v_bfe_u32 v25, v36, 16, 1
	v_lshrrev_b32_e32 v2, 16, v2
	v_add3_u32 v25, v36, v25, s81
	v_and_or_b32 v27, v25, s39, v2
	v_add_u32_e32 v25, 0x400, v9
	ds_read2_b32 v[38:39], v25 offset0:4 offset1:12
	ds_read2_b32 v[40:41], v25 offset0:69 offset1:77
	ds_read2_b32 v[42:43], v25 offset0:134 offset1:142
	ds_read2_b32 v[44:45], v25 offset0:199 offset1:207
	s_waitcnt lgkmcnt(3)
	v_bfe_u32 v2, v38, 16, 1
	v_add3_u32 v2, v38, v2, s81
	s_waitcnt lgkmcnt(2)
	v_bfe_u32 v28, v40, 16, 1
	v_lshrrev_b32_e32 v2, 16, v2
	v_add3_u32 v28, v40, v28, s81
	v_and_or_b32 v28, v28, s39, v2
	s_waitcnt lgkmcnt(1)
	v_bfe_u32 v2, v42, 16, 1
	v_add3_u32 v2, v42, v2, s81
	s_waitcnt lgkmcnt(0)
	v_bfe_u32 v29, v44, 16, 1
	v_lshrrev_b32_e32 v2, 16, v2
	v_add3_u32 v29, v44, v29, s81
	v_and_or_b32 v29, v29, s39, v2
	v_add_u32_e32 v2, s2, v8
	v_and_b32_e32 v30, 0xffffffc0, v2
	v_cmp_gt_i32_e32 vcc, s3, v2
	v_add_u32_e32 v30, v30, v17
	s_nop 0
	v_cndmask_b32_e32 v2, v2, v30, vcc
	v_ashrrev_i32_e32 v46, 8, v2
	v_ashrrev_i32_e32 v47, 31, v46
	v_lshlrev_b64 v[46:47], 20, v[46:47]
	v_lshlrev_b32_e32 v2, 7, v2
	v_lshl_add_u64 v[46:47], s[0:1], 0, v[46:47]
	v_and_b32_e32 v2, 0x7f80, v2
	v_lshl_add_u64 v[46:47], v[46:47], 0, v[2:3]
	v_lshlrev_b32_e32 v2, 1, v6
	v_lshl_add_u64 v[46:47], v[46:47], 0, v[2:3]
	global_store_dwordx4 v[46:47], v[26:29], off sc0 sc1 nt
	v_bfe_u32 v30, v45, 16, 1
	v_add3_u32 v30, v45, v30, s81
	v_bfe_u32 v26, v33, 16, 1
	v_add3_u32 v26, v33, v26, s81
	v_bfe_u32 v27, v31, 16, 1
	v_lshrrev_b32_e32 v26, 16, v26
	v_add3_u32 v27, v31, v27, s81
	v_and_or_b32 v26, v27, s39, v26
	v_bfe_u32 v27, v35, 16, 1
	v_add3_u32 v27, v35, v27, s81
	v_bfe_u32 v28, v37, 16, 1
	v_lshrrev_b32_e32 v27, 16, v27
	v_add3_u32 v28, v37, v28, s81
	v_and_or_b32 v27, v28, s39, v27
	v_bfe_u32 v28, v39, 16, 1
	v_add3_u32 v28, v39, v28, s81
	v_bfe_u32 v29, v41, 16, 1
	v_lshrrev_b32_e32 v28, 16, v28
	v_add3_u32 v29, v41, v29, s81
	v_and_or_b32 v28, v29, s39, v28
	v_bfe_u32 v29, v43, 16, 1
	v_add3_u32 v29, v43, v29, s81
	v_lshrrev_b32_e32 v29, 16, v29
	v_and_or_b32 v29, v30, s39, v29
	v_add_u32_e32 v30, s2, v10
	v_and_b32_e32 v31, 0xffffffc0, v30
	v_cmp_gt_i32_e32 vcc, s3, v30
	v_add_u32_e32 v31, v31, v18
	v_mov_b32_e32 v33, v3
	v_cndmask_b32_e32 v32, v30, v31, vcc
	v_ashrrev_i32_e32 v30, 8, v32
	v_ashrrev_i32_e32 v31, 31, v30
	v_lshlrev_b64 v[30:31], 20, v[30:31]
	v_lshlrev_b32_e32 v32, 7, v32
	v_lshl_add_u64 v[30:31], s[0:1], 0, v[30:31]
	v_and_b32_e32 v32, 0x7f80, v32
	v_lshl_add_u64 v[30:31], v[30:31], 0, v[32:33]
	v_lshl_add_u64 v[30:31], v[30:31], 0, v[2:3]
	global_store_dwordx4 v[30:31], v[26:29], off sc0 sc1 nt
	ds_read2_b32 v[30:31], v9 offset0:16 offset1:24
	ds_read2_b32 v[32:33], v9 offset0:81 offset1:89
	ds_read2_b32 v[34:35], v9 offset0:146 offset1:154
	ds_read2_b32 v[36:37], v9 offset0:211 offset1:219
	ds_read2_b32 v[38:39], v25 offset0:20 offset1:28
	ds_read2_b32 v[40:41], v25 offset0:85 offset1:93
	ds_read2_b32 v[42:43], v25 offset0:150 offset1:158
	ds_read2_b32 v[44:45], v25 offset0:215 offset1:223
	s_waitcnt lgkmcnt(7)
	v_bfe_u32 v26, v30, 16, 1
	v_add3_u32 v26, v30, v26, s81
	s_waitcnt lgkmcnt(6)
	v_bfe_u32 v27, v32, 16, 1
	v_lshrrev_b32_e32 v26, 16, v26
	v_add3_u32 v27, v32, v27, s81
	v_and_or_b32 v26, v27, s39, v26
	s_waitcnt lgkmcnt(5)
	v_bfe_u32 v27, v34, 16, 1
	v_add3_u32 v27, v34, v27, s81
	s_waitcnt lgkmcnt(4)
	v_bfe_u32 v28, v36, 16, 1
	v_lshrrev_b32_e32 v27, 16, v27
	v_add3_u32 v28, v36, v28, s81
	v_and_or_b32 v27, v28, s39, v27
	s_waitcnt lgkmcnt(3)
	v_bfe_u32 v28, v38, 16, 1
	v_add3_u32 v28, v38, v28, s81
	s_waitcnt lgkmcnt(2)
	v_bfe_u32 v29, v40, 16, 1
	v_lshrrev_b32_e32 v28, 16, v28
	v_add3_u32 v29, v40, v29, s81
	v_and_or_b32 v28, v29, s39, v28
	s_waitcnt lgkmcnt(1)
	v_bfe_u32 v29, v42, 16, 1
	v_add3_u32 v29, v42, v29, s81
	s_waitcnt lgkmcnt(0)
	v_bfe_u32 v30, v44, 16, 1
	v_lshrrev_b32_e32 v29, 16, v29
	v_add3_u32 v30, v44, v30, s81
	v_and_or_b32 v29, v30, s39, v29
	v_add_u32_e32 v30, s2, v11
	v_and_b32_e32 v32, 0xffffffc0, v30
	v_cmp_gt_i32_e32 vcc, s3, v30
	v_add_u32_e32 v32, v32, v19
	s_nop 0
	v_cndmask_b32_e32 v30, v30, v32, vcc
	v_ashrrev_i32_e32 v46, 8, v30
	v_ashrrev_i32_e32 v47, 31, v46
	v_lshlrev_b64 v[46:47], 20, v[46:47]
	v_lshlrev_b32_e32 v30, 7, v30
	v_lshl_add_u64 v[46:47], s[0:1], 0, v[46:47]
	v_and_b32_e32 v48, 0x7f80, v30
	v_lshl_add_u64 v[46:47], v[46:47], 0, v[48:49]
	v_lshl_add_u64 v[46:47], v[46:47], 0, v[2:3]
	global_store_dwordx4 v[46:47], v[26:29], off sc0 sc1 nt
	v_bfe_u32 v30, v45, 16, 1
	v_add3_u32 v30, v45, v30, s81
	v_bfe_u32 v26, v31, 16, 1
	v_add3_u32 v26, v31, v26, s81
	v_bfe_u32 v27, v33, 16, 1
	v_lshrrev_b32_e32 v26, 16, v26
	v_add3_u32 v27, v33, v27, s81
	v_and_or_b32 v26, v27, s39, v26
	v_bfe_u32 v27, v35, 16, 1
	v_add3_u32 v27, v35, v27, s81
	v_bfe_u32 v28, v37, 16, 1
	v_lshrrev_b32_e32 v27, 16, v27
	v_add3_u32 v28, v37, v28, s81
	v_and_or_b32 v27, v28, s39, v27
	v_bfe_u32 v28, v39, 16, 1
	v_add3_u32 v28, v39, v28, s81
	v_bfe_u32 v29, v41, 16, 1
	v_lshrrev_b32_e32 v28, 16, v28
	v_add3_u32 v29, v41, v29, s81
	v_and_or_b32 v28, v29, s39, v28
	v_bfe_u32 v29, v43, 16, 1
	v_add3_u32 v29, v43, v29, s81
	v_lshrrev_b32_e32 v29, 16, v29
	v_and_or_b32 v29, v30, s39, v29
	v_add_u32_e32 v30, s2, v12
	v_and_b32_e32 v31, 0xffffffc0, v30
	v_cmp_gt_i32_e32 vcc, s3, v30
	v_add_u32_e32 v31, v31, v20
	v_mov_b32_e32 v33, v3
	v_cndmask_b32_e32 v32, v30, v31, vcc
	v_ashrrev_i32_e32 v30, 8, v32
	v_ashrrev_i32_e32 v31, 31, v30
	v_lshlrev_b64 v[30:31], 20, v[30:31]
	v_lshlrev_b32_e32 v32, 7, v32
	v_lshl_add_u64 v[30:31], s[0:1], 0, v[30:31]
	v_and_b32_e32 v32, 0x7f80, v32
	v_lshl_add_u64 v[30:31], v[30:31], 0, v[32:33]
	v_lshl_add_u64 v[30:31], v[30:31], 0, v[2:3]
	global_store_dwordx4 v[30:31], v[26:29], off sc0 sc1 nt
	ds_read2_b32 v[30:31], v9 offset0:32 offset1:40
	ds_read2_b32 v[32:33], v9 offset0:97 offset1:105
	ds_read2_b32 v[34:35], v9 offset0:162 offset1:170
	ds_read2_b32 v[36:37], v9 offset0:227 offset1:235
	ds_read2_b32 v[38:39], v25 offset0:36 offset1:44
	ds_read2_b32 v[40:41], v25 offset0:101 offset1:109
	ds_read2_b32 v[42:43], v25 offset0:166 offset1:174
	ds_read2_b32 v[44:45], v25 offset0:231 offset1:239
	s_waitcnt lgkmcnt(7)
	v_bfe_u32 v26, v30, 16, 1
	v_add3_u32 v26, v30, v26, s81
	s_waitcnt lgkmcnt(6)
	v_bfe_u32 v27, v32, 16, 1
	v_lshrrev_b32_e32 v26, 16, v26
	v_add3_u32 v27, v32, v27, s81
	v_and_or_b32 v26, v27, s39, v26
	s_waitcnt lgkmcnt(5)
	v_bfe_u32 v27, v34, 16, 1
	v_add3_u32 v27, v34, v27, s81
	s_waitcnt lgkmcnt(4)
	v_bfe_u32 v28, v36, 16, 1
	v_lshrrev_b32_e32 v27, 16, v27
	v_add3_u32 v28, v36, v28, s81
	v_and_or_b32 v27, v28, s39, v27
	s_waitcnt lgkmcnt(3)
	v_bfe_u32 v28, v38, 16, 1
	v_add3_u32 v28, v38, v28, s81
	s_waitcnt lgkmcnt(2)
	v_bfe_u32 v29, v40, 16, 1
	v_lshrrev_b32_e32 v28, 16, v28
	v_add3_u32 v29, v40, v29, s81
	v_and_or_b32 v28, v29, s39, v28
	s_waitcnt lgkmcnt(1)
	v_bfe_u32 v29, v42, 16, 1
	v_add3_u32 v29, v42, v29, s81
	s_waitcnt lgkmcnt(0)
	v_bfe_u32 v30, v44, 16, 1
	v_lshrrev_b32_e32 v29, 16, v29
	v_add3_u32 v30, v44, v30, s81
	v_and_or_b32 v29, v30, s39, v29
	v_add_u32_e32 v30, s2, v13
	v_and_b32_e32 v32, 0xffffffc0, v30
	v_cmp_gt_i32_e32 vcc, s3, v30
	v_add_u32_e32 v32, v32, v21
	s_nop 0
	v_cndmask_b32_e32 v30, v30, v32, vcc
	v_ashrrev_i32_e32 v46, 8, v30
	v_ashrrev_i32_e32 v47, 31, v46
	v_lshlrev_b64 v[46:47], 20, v[46:47]
	v_lshlrev_b32_e32 v30, 7, v30
	v_lshl_add_u64 v[46:47], s[0:1], 0, v[46:47]
	v_and_b32_e32 v48, 0x7f80, v30
	v_lshl_add_u64 v[46:47], v[46:47], 0, v[48:49]
	v_lshl_add_u64 v[46:47], v[46:47], 0, v[2:3]
	global_store_dwordx4 v[46:47], v[26:29], off sc0 sc1 nt
	v_bfe_u32 v30, v45, 16, 1
	v_add3_u32 v30, v45, v30, s81
	v_bfe_u32 v26, v31, 16, 1
	v_add3_u32 v26, v31, v26, s81
	v_bfe_u32 v27, v33, 16, 1
	v_lshrrev_b32_e32 v26, 16, v26
	v_add3_u32 v27, v33, v27, s81
	v_and_or_b32 v26, v27, s39, v26
	v_bfe_u32 v27, v35, 16, 1
	v_add3_u32 v27, v35, v27, s81
	v_bfe_u32 v28, v37, 16, 1
	v_lshrrev_b32_e32 v27, 16, v27
	v_add3_u32 v28, v37, v28, s81
	v_and_or_b32 v27, v28, s39, v27
	v_bfe_u32 v28, v39, 16, 1
	v_add3_u32 v28, v39, v28, s81
	v_bfe_u32 v29, v41, 16, 1
	v_lshrrev_b32_e32 v28, 16, v28
	v_add3_u32 v29, v41, v29, s81
	v_and_or_b32 v28, v29, s39, v28
	v_bfe_u32 v29, v43, 16, 1
	v_add3_u32 v29, v43, v29, s81
	v_lshrrev_b32_e32 v29, 16, v29
	v_and_or_b32 v29, v30, s39, v29
	v_add_u32_e32 v30, s2, v14
	v_and_b32_e32 v31, 0xffffffc0, v30
	v_cmp_gt_i32_e32 vcc, s3, v30
	v_add_u32_e32 v31, v31, v22
	v_mov_b32_e32 v33, v3
	v_cndmask_b32_e32 v32, v30, v31, vcc
	v_ashrrev_i32_e32 v30, 8, v32
	v_ashrrev_i32_e32 v31, 31, v30
	v_lshlrev_b64 v[30:31], 20, v[30:31]
	v_lshlrev_b32_e32 v32, 7, v32
	v_lshl_add_u64 v[30:31], s[0:1], 0, v[30:31]
	v_and_b32_e32 v32, 0x7f80, v32
	v_lshl_add_u64 v[30:31], v[30:31], 0, v[32:33]
	v_lshl_add_u64 v[30:31], v[30:31], 0, v[2:3]
	global_store_dwordx4 v[30:31], v[26:29], off sc0 sc1 nt
	ds_read2_b32 v[30:31], v9 offset0:48 offset1:56
	ds_read2_b32 v[32:33], v9 offset0:113 offset1:121
	ds_read2_b32 v[34:35], v9 offset0:178 offset1:186
	ds_read2_b32 v[36:37], v9 offset0:243 offset1:251
	ds_read2_b32 v[38:39], v25 offset0:52 offset1:60
	ds_read2_b32 v[40:41], v25 offset0:117 offset1:125
	ds_read2_b32 v[42:43], v25 offset0:182 offset1:190
	ds_read2_b32 v[44:45], v25 offset0:247 offset1:255
	s_waitcnt lgkmcnt(7)
	v_bfe_u32 v26, v30, 16, 1
	v_add3_u32 v26, v30, v26, s81
	s_waitcnt lgkmcnt(6)
	v_bfe_u32 v27, v32, 16, 1
	v_lshrrev_b32_e32 v26, 16, v26
	v_add3_u32 v27, v32, v27, s81
	v_and_or_b32 v26, v27, s39, v26
	s_waitcnt lgkmcnt(5)
	v_bfe_u32 v27, v34, 16, 1
	v_add3_u32 v27, v34, v27, s81
	s_waitcnt lgkmcnt(4)
	v_bfe_u32 v28, v36, 16, 1
	v_lshrrev_b32_e32 v27, 16, v27
	v_add3_u32 v28, v36, v28, s81
	v_and_or_b32 v27, v28, s39, v27
	s_waitcnt lgkmcnt(3)
	v_bfe_u32 v28, v38, 16, 1
	v_add3_u32 v28, v38, v28, s81
	s_waitcnt lgkmcnt(2)
	v_bfe_u32 v29, v40, 16, 1
	v_lshrrev_b32_e32 v28, 16, v28
	v_add3_u32 v29, v40, v29, s81
	s_waitcnt lgkmcnt(1)
	v_bfe_u32 v25, v42, 16, 1
	v_and_or_b32 v28, v29, s39, v28
	v_add3_u32 v25, v42, v25, s81
	s_waitcnt lgkmcnt(0)
	v_bfe_u32 v29, v44, 16, 1
	v_lshrrev_b32_e32 v25, 16, v25
	v_add3_u32 v29, v44, v29, s81
	v_and_or_b32 v29, v29, s39, v25
	v_add_u32_e32 v25, s2, v15
	v_and_b32_e32 v30, 0xffffffc0, v25
	v_cmp_gt_i32_e32 vcc, s3, v25
	v_add_u32_e32 v30, v30, v23
	s_nop 0
	v_cndmask_b32_e32 v25, v25, v30, vcc
	v_ashrrev_i32_e32 v46, 8, v25
	v_ashrrev_i32_e32 v47, 31, v46
	v_lshlrev_b64 v[46:47], 20, v[46:47]
	v_lshlrev_b32_e32 v25, 7, v25
	v_lshl_add_u64 v[46:47], s[0:1], 0, v[46:47]
	v_and_b32_e32 v48, 0x7f80, v25
	v_lshl_add_u64 v[46:47], v[46:47], 0, v[48:49]
	v_lshl_add_u64 v[46:47], v[46:47], 0, v[2:3]
	v_bfe_u32 v25, v31, 16, 1
	global_store_dwordx4 v[46:47], v[26:29], off sc0 sc1 nt
	v_add3_u32 v25, v31, v25, s81
	v_lshrrev_b32_e32 v25, 16, v25
	v_bfe_u32 v26, v33, 16, 1
	v_add3_u32 v26, v33, v26, s81
	v_and_or_b32 v26, v26, s39, v25
	v_bfe_u32 v25, v35, 16, 1
	v_add3_u32 v25, v35, v25, s81
	v_bfe_u32 v27, v37, 16, 1
	v_lshrrev_b32_e32 v25, 16, v25
	v_add3_u32 v27, v37, v27, s81
	v_and_or_b32 v27, v27, s39, v25
	v_bfe_u32 v25, v39, 16, 1
	v_add3_u32 v25, v39, v25, s81
	v_bfe_u32 v28, v41, 16, 1
	v_lshrrev_b32_e32 v25, 16, v25
	v_add3_u32 v28, v41, v28, s81
	v_and_or_b32 v28, v28, s39, v25
	v_bfe_u32 v25, v43, 16, 1
	v_add3_u32 v25, v43, v25, s81
	v_bfe_u32 v29, v45, 16, 1
	v_lshrrev_b32_e32 v25, 16, v25
	v_add3_u32 v29, v45, v29, s81
	v_and_or_b32 v29, v29, s39, v25
	v_add_u32_e32 v25, s2, v16
	v_and_b32_e32 v30, 0xffffffc0, v25
	v_cmp_gt_i32_e32 vcc, s3, v25
	v_add_u32_e32 v30, v30, v24
	v_mov_b32_e32 v33, v3
	v_cndmask_b32_e32 v25, v25, v30, vcc
	v_ashrrev_i32_e32 v30, 8, v25
	v_ashrrev_i32_e32 v31, 31, v30
	v_lshlrev_b64 v[30:31], 20, v[30:31]
	v_lshlrev_b32_e32 v25, 7, v25
	v_lshl_add_u64 v[30:31], s[0:1], 0, v[30:31]
	v_and_b32_e32 v32, 0x7f80, v25
	v_lshl_add_u64 v[30:31], v[30:31], 0, v[32:33]
	v_lshl_add_u64 v[30:31], v[30:31], 0, v[2:3]
	global_store_dwordx4 v[30:31], v[26:29], off sc0 sc1 nt
	s_waitcnt lgkmcnt(0)

.LBB0_960:
	s_andn2_b64 vcc, exec, s[0:1]
	s_cbranch_vccnz .LBB0_962
	s_load_dwordx2 s[2:3], s[6:7], 0x48
	s_add_i32 s0, s20, 0x6200
	s_and_b32 s23, s0, 0x1fc0
	s_add_i32 s0, s18, 0xfffa8000
	s_and_b32 s0, s0, 0x7c0
	s_add_i32 s1, s22, 0xffffea00
	v_add_u32_e32 v26, s23, v5
	s_lshl_b32 s23, s0, 2
	s_waitcnt lgkmcnt(0)
	s_add_u32 s2, s2, s23
	s_addc_u32 s3, s3, 0
	v_lshlrev_b32_e32 v2, 2, v4
	v_ashrrev_i32_e32 v27, 31, v26
	v_lshl_add_u64 v[28:29], s[2:3], 0, v[2:3]
	v_lshlrev_b64 v[26:27], 13, v[26:27]
	v_lshl_add_u64 v[86:87], v[28:29], 0, v[26:27]
	v_add_co_u32_e32 v26, vcc, s42, v86
	v_add_u32_e32 v2, 0x410, v7
	s_nop 0
	v_addc_co_u32_e32 v27, vcc, 0, v87, vcc
	v_add_co_u32_e32 v30, vcc, s43, v86
	s_lshr_b32 s72, s1, 5
	s_nop 0
	v_addc_co_u32_e32 v31, vcc, 0, v87, vcc
	v_add_co_u32_e32 v34, vcc, s44, v86
	global_load_dwordx4 v[26:29], v[26:27], off nt
	s_nop 0
	global_load_dwordx4 v[30:33], v[30:31], off nt
	v_addc_co_u32_e32 v35, vcc, 0, v87, vcc
	v_add_co_u32_e32 v38, vcc, s46, v86
	s_nop 1
	v_addc_co_u32_e32 v39, vcc, 0, v87, vcc
	global_load_dwordx4 v[34:37], v[34:35], off nt
	s_nop 0
	global_load_dwordx4 v[38:41], v[38:39], off nt
	v_add_co_u32_e32 v42, vcc, s49, v86
	s_nop 1
	v_addc_co_u32_e32 v43, vcc, 0, v87, vcc
	v_add_co_u32_e32 v46, vcc, s50, v86
	s_nop 1
	v_addc_co_u32_e32 v47, vcc, 0, v87, vcc
	global_load_dwordx4 v[42:45], v[42:43], off nt
	s_nop 0
	global_load_dwordx4 v[46:49], v[46:47], off nt
	v_add_co_u32_e32 v50, vcc, s53, v86
	s_nop 1
	v_addc_co_u32_e32 v51, vcc, 0, v87, vcc
	v_add_co_u32_e32 v54, vcc, s55, v86
	s_nop 1
	v_addc_co_u32_e32 v55, vcc, 0, v87, vcc
	global_load_dwordx4 v[50:53], v[50:51], off nt
	s_nop 0
	global_load_dwordx4 v[54:57], v[54:55], off nt
	v_add_co_u32_e32 v58, vcc, s56, v86
	s_nop 1
	v_addc_co_u32_e32 v59, vcc, 0, v87, vcc
	v_add_co_u32_e32 v62, vcc, s57, v86
	s_nop 1
	v_addc_co_u32_e32 v63, vcc, 0, v87, vcc
	global_load_dwordx4 v[58:61], v[58:59], off nt
	s_nop 0
	global_load_dwordx4 v[62:65], v[62:63], off nt
	v_add_co_u32_e32 v66, vcc, s58, v86
	s_nop 1
	v_addc_co_u32_e32 v67, vcc, 0, v87, vcc
	v_add_co_u32_e32 v70, vcc, s61, v86
	s_nop 1
	v_addc_co_u32_e32 v71, vcc, 0, v87, vcc
	global_load_dwordx4 v[66:69], v[66:67], off nt
	s_nop 0
	global_load_dwordx4 v[70:73], v[70:71], off nt
	v_add_co_u32_e32 v74, vcc, s62, v86
	s_nop 1
	v_addc_co_u32_e32 v75, vcc, 0, v87, vcc
	global_load_dwordx4 v[74:77], v[74:75], off nt
	v_add_co_u32_e32 v78, vcc, s63, v86
	s_nop 1
	v_addc_co_u32_e32 v79, vcc, 0, v87, vcc
	global_load_dwordx4 v[78:81], v[78:79], off nt
	v_add_co_u32_e32 v82, vcc, s64, v86
	s_nop 1
	v_addc_co_u32_e32 v83, vcc, 0, v87, vcc
	global_load_dwordx4 v[82:85], v[82:83], off nt
	v_add_co_u32_e32 v86, vcc, s65, v86
	s_nop 1
	v_addc_co_u32_e32 v87, vcc, 0, v87, vcc
	global_load_dwordx4 v[86:89], v[86:87], off nt
	s_waitcnt vmcnt(0)
	ds_write2_b32 v7, v26, v27 offset1:1
	ds_write2_b32 v7, v28, v29 offset0:2 offset1:3
	ds_write2_b32 v2, v30, v31 offset1:1
	v_add_u32_e32 v2, 0x418, v7
	ds_write2_b32 v2, v32, v33 offset1:1
	v_add_u32_e32 v2, 0x820, v7
	ds_write2_b32 v2, v34, v35 offset1:1
	v_add_u32_e32 v2, 0x828, v7
	ds_write2_b32 v2, v36, v37 offset1:1
	v_add_u32_e32 v2, 0xc30, v7
	ds_write2_b32 v2, v38, v39 offset1:1
	v_add_u32_e32 v2, 0xc38, v7
	ds_write2_b32 v2, v40, v41 offset1:1
	v_add_u32_e32 v2, 0x1040, v7
	ds_write2_b32 v2, v42, v43 offset1:1
	v_add_u32_e32 v2, 0x1048, v7
	ds_write2_b32 v2, v44, v45 offset1:1
	v_add_u32_e32 v2, 0x1450, v7
	ds_write2_b32 v2, v46, v47 offset1:1
	v_add_u32_e32 v2, 0x1458, v7
	ds_write2_b32 v2, v48, v49 offset1:1
	v_add_u32_e32 v2, 0x1860, v7
	v_mov_b32_e32 v49, v3
	ds_write2_b32 v2, v50, v51 offset1:1
	v_add_u32_e32 v2, 0x1868, v7
	ds_write2_b32 v2, v52, v53 offset1:1
	v_add_u32_e32 v2, 0x1c70, v7
	ds_write2_b32 v2, v54, v55 offset1:1
	v_add_u32_e32 v2, 0x1c78, v7
	ds_write2_b32 v2, v56, v57 offset1:1
	v_add_u32_e32 v2, 0x2080, v7
	ds_write2_b32 v2, v58, v59 offset1:1
	v_add_u32_e32 v2, 0x2088, v7
	ds_write2_b32 v2, v60, v61 offset1:1
	v_add_u32_e32 v2, 0x2490, v7
	ds_write2_b32 v2, v62, v63 offset1:1
	v_add_u32_e32 v2, 0x2498, v7
	ds_write2_b32 v2, v64, v65 offset1:1
	v_add_u32_e32 v2, 0x28a0, v7
	ds_write2_b32 v2, v66, v67 offset1:1
	v_add_u32_e32 v2, 0x28a8, v7
	ds_write2_b32 v2, v68, v69 offset1:1
	v_add_u32_e32 v2, 0x2cb0, v7
	ds_write2_b32 v2, v70, v71 offset1:1
	v_add_u32_e32 v2, 0x2cb8, v7
	ds_write2_b32 v2, v72, v73 offset1:1
	v_add_u32_e32 v2, 0x30c0, v7
	ds_write2_b32 v2, v74, v75 offset1:1
	v_add_u32_e32 v2, 0x30c8, v7
	ds_write2_b32 v2, v76, v77 offset1:1
	v_add_u32_e32 v2, 0x34d0, v7
	ds_write2_b32 v2, v78, v79 offset1:1
	v_add_u32_e32 v2, 0x34d8, v7
	ds_write2_b32 v2, v80, v81 offset1:1
	v_add_u32_e32 v2, 0x38e0, v7
	ds_write2_b32 v2, v82, v83 offset1:1
	v_add_u32_e32 v2, 0x38e8, v7
	ds_write2_b32 v2, v84, v85 offset1:1
	v_add_u32_e32 v2, 0x3cf0, v7
	ds_write2_b32 v2, v86, v87 offset1:1
	v_add_u32_e32 v2, 0x3cf8, v7
	ds_write2_b32 v2, v88, v89 offset1:1
	s_waitcnt lgkmcnt(0)
	ds_read2_b32 v[30:31], v9 offset1:8
	ds_read2_b32 v[32:33], v9 offset0:65 offset1:73
	ds_read2_b32 v[34:35], v9 offset0:130 offset1:138
	ds_read2_b32 v[36:37], v9 offset0:195 offset1:203
	s_waitcnt lgkmcnt(3)
	v_bfe_u32 v2, v30, 16, 1
	v_add3_u32 v2, v30, v2, s81
	s_waitcnt lgkmcnt(2)
	v_bfe_u32 v25, v32, 16, 1
	v_lshrrev_b32_e32 v2, 16, v2
	v_add3_u32 v25, v32, v25, s81
	v_and_or_b32 v26, v25, s39, v2
	v_add_u32_e32 v25, 0x400, v9
	ds_read2_b32 v[38:39], v25 offset0:4 offset1:12
	ds_read2_b32 v[40:41], v25 offset0:69 offset1:77
	s_waitcnt lgkmcnt(3)
	v_bfe_u32 v2, v34, 16, 1
	v_add3_u32 v2, v34, v2, s81
	s_waitcnt lgkmcnt(2)
	v_bfe_u32 v27, v36, 16, 1
	ds_read2_b32 v[42:43], v25 offset0:134 offset1:142
	v_lshrrev_b32_e32 v2, 16, v2
	v_add3_u32 v27, v36, v27, s81
	ds_read2_b32 v[44:45], v25 offset0:199 offset1:207
	v_and_or_b32 v27, v27, s39, v2
	s_waitcnt lgkmcnt(3)
	v_bfe_u32 v2, v38, 16, 1
	v_add3_u32 v2, v38, v2, s81
	s_waitcnt lgkmcnt(2)
	v_bfe_u32 v28, v40, 16, 1
	v_lshrrev_b32_e32 v2, 16, v2
	v_add3_u32 v28, v40, v28, s81
	v_and_or_b32 v28, v28, s39, v2
	s_waitcnt lgkmcnt(1)
	v_bfe_u32 v2, v42, 16, 1
	v_add3_u32 v2, v42, v2, s81
	s_waitcnt lgkmcnt(0)
	v_bfe_u32 v29, v44, 16, 1
	v_lshrrev_b32_e32 v2, 16, v2
	v_add3_u32 v29, v44, v29, s81
	v_and_or_b32 v29, v29, s39, v2
	v_add_u32_e32 v2, s0, v8
	v_lshrrev_b32_e32 v30, 8, v2
	v_mul_i32_i24_e32 v46, 0x58, v30
	v_ashrrev_i32_e32 v47, 31, v46
	v_lshl_add_u64 v[46:47], v[46:47], 0, s[72:73]
	v_lshlrev_b64 v[46:47], 15, v[46:47]
	v_lshlrev_b32_e32 v2, 7, v2
	v_lshl_add_u64 v[46:47], s[12:13], 0, v[46:47]
	v_and_b32_e32 v2, 0x7f80, v2
	v_lshl_add_u64 v[46:47], v[46:47], 0, v[2:3]
	v_lshlrev_b32_e32 v2, 1, v6
	v_lshl_add_u64 v[46:47], v[46:47], 0, v[2:3]
	global_store_dwordx4 v[46:47], v[26:29], off sc0 sc1 nt
	v_bfe_u32 v30, v45, 16, 1
	v_add3_u32 v30, v45, v30, s81
	v_bfe_u32 v26, v31, 16, 1
	v_add3_u32 v26, v31, v26, s81
	v_bfe_u32 v27, v33, 16, 1
	v_lshrrev_b32_e32 v26, 16, v26
	v_add3_u32 v27, v33, v27, s81
	v_and_or_b32 v26, v27, s39, v26
	v_bfe_u32 v27, v35, 16, 1
	v_add3_u32 v27, v35, v27, s81
	v_bfe_u32 v28, v37, 16, 1
	v_lshrrev_b32_e32 v27, 16, v27
	v_add3_u32 v28, v37, v28, s81
	v_and_or_b32 v27, v28, s39, v27
	v_bfe_u32 v28, v39, 16, 1
	v_add3_u32 v28, v39, v28, s81
	v_bfe_u32 v29, v41, 16, 1
	v_lshrrev_b32_e32 v28, 16, v28
	v_add3_u32 v29, v41, v29, s81
	v_and_or_b32 v28, v29, s39, v28
	v_bfe_u32 v29, v43, 16, 1
	v_add3_u32 v29, v43, v29, s81
	v_lshrrev_b32_e32 v29, 16, v29
	v_add_u32_e32 v32, s0, v10
	v_and_or_b32 v29, v30, s39, v29
	v_lshrrev_b32_e32 v30, 8, v32
	v_mul_i32_i24_e32 v30, 0x58, v30
	v_ashrrev_i32_e32 v31, 31, v30
	v_lshl_add_u64 v[30:31], v[30:31], 0, s[72:73]
	v_lshlrev_b64 v[30:31], 15, v[30:31]
	v_lshlrev_b32_e32 v32, 7, v32
	v_lshl_add_u64 v[30:31], s[12:13], 0, v[30:31]
	v_and_b32_e32 v32, 0x7f80, v32
	v_mov_b32_e32 v33, v3
	v_lshl_add_u64 v[30:31], v[30:31], 0, v[32:33]
	ds_read2_b32 v[34:35], v9 offset0:16 offset1:24
	v_lshl_add_u64 v[30:31], v[30:31], 0, v[2:3]
	global_store_dwordx4 v[30:31], v[26:29], off sc0 sc1 nt
	ds_read2_b32 v[30:31], v9 offset0:81 offset1:89
	ds_read2_b32 v[32:33], v9 offset0:146 offset1:154
	ds_read2_b32 v[36:37], v9 offset0:211 offset1:219
	s_waitcnt lgkmcnt(3)
	v_bfe_u32 v26, v34, 16, 1
	v_add3_u32 v26, v34, v26, s81
	s_waitcnt lgkmcnt(2)
	v_bfe_u32 v27, v30, 16, 1
	ds_read2_b32 v[38:39], v25 offset0:20 offset1:28
	v_lshrrev_b32_e32 v26, 16, v26
	v_add3_u32 v27, v30, v27, s81
	ds_read2_b32 v[40:41], v25 offset0:85 offset1:93
	v_and_or_b32 v26, v27, s39, v26
	s_waitcnt lgkmcnt(3)
	v_bfe_u32 v27, v32, 16, 1
	v_add3_u32 v27, v32, v27, s81
	s_waitcnt lgkmcnt(2)
	v_bfe_u32 v28, v36, 16, 1
	ds_read2_b32 v[42:43], v25 offset0:150 offset1:158
	v_lshrrev_b32_e32 v27, 16, v27
	v_add3_u32 v28, v36, v28, s81
	ds_read2_b32 v[44:45], v25 offset0:215 offset1:223
	v_and_or_b32 v27, v28, s39, v27
	s_waitcnt lgkmcnt(3)
	v_bfe_u32 v28, v38, 16, 1
	v_add3_u32 v28, v38, v28, s81
	s_waitcnt lgkmcnt(2)
	v_bfe_u32 v29, v40, 16, 1
	v_lshrrev_b32_e32 v28, 16, v28
	v_add3_u32 v29, v40, v29, s81
	v_and_or_b32 v28, v29, s39, v28
	s_waitcnt lgkmcnt(1)
	v_bfe_u32 v29, v42, 16, 1
	v_add3_u32 v29, v42, v29, s81
	s_waitcnt lgkmcnt(0)
	v_bfe_u32 v30, v44, 16, 1
	v_lshrrev_b32_e32 v29, 16, v29
	v_add3_u32 v30, v44, v30, s81
	v_and_or_b32 v29, v30, s39, v29
	v_add_u32_e32 v30, s0, v11
	v_lshrrev_b32_e32 v32, 8, v30
	v_mul_i32_i24_e32 v46, 0x58, v32
	v_ashrrev_i32_e32 v47, 31, v46
	v_lshl_add_u64 v[46:47], v[46:47], 0, s[72:73]
	v_lshlrev_b64 v[46:47], 15, v[46:47]
	v_lshlrev_b32_e32 v30, 7, v30
	v_lshl_add_u64 v[46:47], s[12:13], 0, v[46:47]
	v_and_b32_e32 v48, 0x7f80, v30
	v_lshl_add_u64 v[46:47], v[46:47], 0, v[48:49]
	v_lshl_add_u64 v[46:47], v[46:47], 0, v[2:3]
	global_store_dwordx4 v[46:47], v[26:29], off sc0 sc1 nt
	v_bfe_u32 v30, v45, 16, 1
	v_add3_u32 v30, v45, v30, s81
	v_bfe_u32 v26, v35, 16, 1
	v_add3_u32 v26, v35, v26, s81
	v_bfe_u32 v27, v31, 16, 1
	v_lshrrev_b32_e32 v26, 16, v26
	v_add3_u32 v27, v31, v27, s81
	v_and_or_b32 v26, v27, s39, v26
	v_bfe_u32 v27, v33, 16, 1
	v_add3_u32 v27, v33, v27, s81
	v_bfe_u32 v28, v37, 16, 1
	v_lshrrev_b32_e32 v27, 16, v27
	v_add3_u32 v28, v37, v28, s81
	v_and_or_b32 v27, v28, s39, v27
	v_bfe_u32 v28, v39, 16, 1
	v_add3_u32 v28, v39, v28, s81
	v_bfe_u32 v29, v41, 16, 1
	v_lshrrev_b32_e32 v28, 16, v28
	v_add3_u32 v29, v41, v29, s81
	v_and_or_b32 v28, v29, s39, v28
	v_bfe_u32 v29, v43, 16, 1
	v_add3_u32 v29, v43, v29, s81
	v_lshrrev_b32_e32 v29, 16, v29
	v_add_u32_e32 v32, s0, v12
	v_and_or_b32 v29, v30, s39, v29
	v_lshrrev_b32_e32 v30, 8, v32
	v_mul_i32_i24_e32 v30, 0x58, v30
	v_ashrrev_i32_e32 v31, 31, v30
	v_lshl_add_u64 v[30:31], v[30:31], 0, s[72:73]
	v_lshlrev_b64 v[30:31], 15, v[30:31]
	v_lshlrev_b32_e32 v32, 7, v32
	v_lshl_add_u64 v[30:31], s[12:13], 0, v[30:31]
	v_and_b32_e32 v32, 0x7f80, v32
	v_mov_b32_e32 v33, v3
	v_lshl_add_u64 v[30:31], v[30:31], 0, v[32:33]
	ds_read2_b32 v[34:35], v9 offset0:32 offset1:40
	v_lshl_add_u64 v[30:31], v[30:31], 0, v[2:3]
	global_store_dwordx4 v[30:31], v[26:29], off sc0 sc1 nt
	ds_read2_b32 v[30:31], v9 offset0:97 offset1:105
	ds_read2_b32 v[32:33], v9 offset0:162 offset1:170
	ds_read2_b32 v[36:37], v9 offset0:227 offset1:235
	s_waitcnt lgkmcnt(3)
	v_bfe_u32 v26, v34, 16, 1
	v_add3_u32 v26, v34, v26, s81
	s_waitcnt lgkmcnt(2)
	v_bfe_u32 v27, v30, 16, 1
	ds_read2_b32 v[38:39], v25 offset0:36 offset1:44
	v_lshrrev_b32_e32 v26, 16, v26
	v_add3_u32 v27, v30, v27, s81
	ds_read2_b32 v[40:41], v25 offset0:101 offset1:109
	v_and_or_b32 v26, v27, s39, v26
	s_waitcnt lgkmcnt(3)
	v_bfe_u32 v27, v32, 16, 1
	v_add3_u32 v27, v32, v27, s81
	s_waitcnt lgkmcnt(2)
	v_bfe_u32 v28, v36, 16, 1
	ds_read2_b32 v[42:43], v25 offset0:166 offset1:174
	v_lshrrev_b32_e32 v27, 16, v27
	v_add3_u32 v28, v36, v28, s81
	ds_read2_b32 v[44:45], v25 offset0:231 offset1:239
	v_and_or_b32 v27, v28, s39, v27
	s_waitcnt lgkmcnt(3)
	v_bfe_u32 v28, v38, 16, 1
	v_add3_u32 v28, v38, v28, s81
	s_waitcnt lgkmcnt(2)
	v_bfe_u32 v29, v40, 16, 1
	v_lshrrev_b32_e32 v28, 16, v28
	v_add3_u32 v29, v40, v29, s81
	v_and_or_b32 v28, v29, s39, v28
	s_waitcnt lgkmcnt(1)
	v_bfe_u32 v29, v42, 16, 1
	v_add3_u32 v29, v42, v29, s81
	s_waitcnt lgkmcnt(0)
	v_bfe_u32 v30, v44, 16, 1
	v_lshrrev_b32_e32 v29, 16, v29
	v_add3_u32 v30, v44, v30, s81
	v_and_or_b32 v29, v30, s39, v29
	v_add_u32_e32 v30, s0, v13
	v_lshrrev_b32_e32 v32, 8, v30
	v_mul_i32_i24_e32 v46, 0x58, v32
	v_ashrrev_i32_e32 v47, 31, v46
	v_lshl_add_u64 v[46:47], v[46:47], 0, s[72:73]
	v_lshlrev_b64 v[46:47], 15, v[46:47]
	v_lshlrev_b32_e32 v30, 7, v30
	v_lshl_add_u64 v[46:47], s[12:13], 0, v[46:47]
	v_and_b32_e32 v48, 0x7f80, v30
	v_lshl_add_u64 v[46:47], v[46:47], 0, v[48:49]
	v_lshl_add_u64 v[46:47], v[46:47], 0, v[2:3]
	global_store_dwordx4 v[46:47], v[26:29], off sc0 sc1 nt
	v_bfe_u32 v30, v45, 16, 1
	v_add3_u32 v30, v45, v30, s81
	v_bfe_u32 v26, v35, 16, 1
	v_add3_u32 v26, v35, v26, s81
	v_bfe_u32 v27, v31, 16, 1
	v_lshrrev_b32_e32 v26, 16, v26
	v_add3_u32 v27, v31, v27, s81
	v_and_or_b32 v26, v27, s39, v26
	v_bfe_u32 v27, v33, 16, 1
	v_add3_u32 v27, v33, v27, s81
	v_bfe_u32 v28, v37, 16, 1
	v_lshrrev_b32_e32 v27, 16, v27
	v_add3_u32 v28, v37, v28, s81
	v_and_or_b32 v27, v28, s39, v27
	v_bfe_u32 v28, v39, 16, 1
	v_add3_u32 v28, v39, v28, s81
	v_bfe_u32 v29, v41, 16, 1
	v_lshrrev_b32_e32 v28, 16, v28
	v_add3_u32 v29, v41, v29, s81
	v_and_or_b32 v28, v29, s39, v28
	v_bfe_u32 v29, v43, 16, 1
	v_add3_u32 v29, v43, v29, s81
	v_lshrrev_b32_e32 v29, 16, v29
	v_add_u32_e32 v32, s0, v14
	v_and_or_b32 v29, v30, s39, v29
	v_lshrrev_b32_e32 v30, 8, v32
	v_mul_i32_i24_e32 v30, 0x58, v30
	v_ashrrev_i32_e32 v31, 31, v30
	v_lshl_add_u64 v[30:31], v[30:31], 0, s[72:73]
	v_lshlrev_b64 v[30:31], 15, v[30:31]
	v_lshlrev_b32_e32 v32, 7, v32
	v_lshl_add_u64 v[30:31], s[12:13], 0, v[30:31]
	v_and_b32_e32 v32, 0x7f80, v32
	v_mov_b32_e32 v33, v3
	v_lshl_add_u64 v[30:31], v[30:31], 0, v[32:33]
	ds_read2_b32 v[34:35], v9 offset0:48 offset1:56
	v_lshl_add_u64 v[30:31], v[30:31], 0, v[2:3]
	global_store_dwordx4 v[30:31], v[26:29], off sc0 sc1 nt
	ds_read2_b32 v[30:31], v9 offset0:113 offset1:121
	ds_read2_b32 v[32:33], v9 offset0:178 offset1:186
	ds_read2_b32 v[36:37], v9 offset0:243 offset1:251
	s_waitcnt lgkmcnt(3)
	v_bfe_u32 v26, v34, 16, 1
	v_add3_u32 v26, v34, v26, s81
	s_waitcnt lgkmcnt(2)
	v_bfe_u32 v27, v30, 16, 1
	ds_read2_b32 v[38:39], v25 offset0:52 offset1:60
	v_lshrrev_b32_e32 v26, 16, v26
	v_add3_u32 v27, v30, v27, s81
	ds_read2_b32 v[40:41], v25 offset0:117 offset1:125
	v_and_or_b32 v26, v27, s39, v26
	s_waitcnt lgkmcnt(3)
	v_bfe_u32 v27, v32, 16, 1
	ds_read2_b32 v[42:43], v25 offset0:182 offset1:190
	v_add3_u32 v27, v32, v27, s81
	s_waitcnt lgkmcnt(3)
	v_bfe_u32 v28, v36, 16, 1
	ds_read2_b32 v[44:45], v25 offset0:247 offset1:255
	v_lshrrev_b32_e32 v27, 16, v27
	v_add3_u32 v28, v36, v28, s81
	v_and_or_b32 v27, v28, s39, v27
	s_waitcnt lgkmcnt(3)
	v_bfe_u32 v28, v38, 16, 1
	v_add3_u32 v28, v38, v28, s81
	s_waitcnt lgkmcnt(2)
	v_bfe_u32 v29, v40, 16, 1
	v_lshrrev_b32_e32 v28, 16, v28
	v_add3_u32 v29, v40, v29, s81
	s_waitcnt lgkmcnt(1)
	v_bfe_u32 v25, v42, 16, 1
	v_and_or_b32 v28, v29, s39, v28
	v_add3_u32 v25, v42, v25, s81
	s_waitcnt lgkmcnt(0)
	v_bfe_u32 v29, v44, 16, 1
	v_lshrrev_b32_e32 v25, 16, v25
	v_add3_u32 v29, v44, v29, s81
	v_and_or_b32 v29, v29, s39, v25
	v_add_u32_e32 v25, s0, v15
	v_lshrrev_b32_e32 v30, 8, v25
	v_mul_i32_i24_e32 v46, 0x58, v30
	v_ashrrev_i32_e32 v47, 31, v46
	v_lshl_add_u64 v[46:47], v[46:47], 0, s[72:73]
	v_lshlrev_b64 v[46:47], 15, v[46:47]
	v_lshlrev_b32_e32 v25, 7, v25
	v_lshl_add_u64 v[46:47], s[12:13], 0, v[46:47]
	v_and_b32_e32 v48, 0x7f80, v25
	v_lshl_add_u64 v[46:47], v[46:47], 0, v[48:49]
	v_lshl_add_u64 v[46:47], v[46:47], 0, v[2:3]
	v_bfe_u32 v25, v35, 16, 1
	global_store_dwordx4 v[46:47], v[26:29], off sc0 sc1 nt
	v_add3_u32 v25, v35, v25, s81
	v_lshrrev_b32_e32 v25, 16, v25
	v_bfe_u32 v26, v31, 16, 1
	v_add3_u32 v26, v31, v26, s81
	v_and_or_b32 v26, v26, s39, v25
	v_bfe_u32 v25, v33, 16, 1
	v_add3_u32 v25, v33, v25, s81
	v_bfe_u32 v27, v37, 16, 1
	v_lshrrev_b32_e32 v25, 16, v25
	v_add3_u32 v27, v37, v27, s81
	v_and_or_b32 v27, v27, s39, v25
	v_bfe_u32 v25, v39, 16, 1
	v_add3_u32 v25, v39, v25, s81
	v_bfe_u32 v28, v41, 16, 1
	v_lshrrev_b32_e32 v25, 16, v25
	v_add3_u32 v28, v41, v28, s81
	v_and_or_b32 v28, v28, s39, v25
	v_bfe_u32 v25, v43, 16, 1
	v_add3_u32 v25, v43, v25, s81
	v_bfe_u32 v29, v45, 16, 1
	v_lshrrev_b32_e32 v25, 16, v25
	v_add3_u32 v29, v45, v29, s81
	v_and_or_b32 v29, v29, s39, v25
	v_add_u32_e32 v25, s0, v16
	v_lshrrev_b32_e32 v30, 8, v25
	v_mul_i32_i24_e32 v30, 0x58, v30
	v_ashrrev_i32_e32 v31, 31, v30
	v_lshl_add_u64 v[30:31], v[30:31], 0, s[72:73]
	v_lshlrev_b64 v[30:31], 15, v[30:31]
	v_lshlrev_b32_e32 v25, 7, v25
	v_lshl_add_u64 v[30:31], s[12:13], 0, v[30:31]
	v_and_b32_e32 v32, 0x7f80, v25
	v_mov_b32_e32 v33, v3
	v_lshl_add_u64 v[30:31], v[30:31], 0, v[32:33]
	v_lshl_add_u64 v[30:31], v[30:31], 0, v[2:3]
	global_store_dwordx4 v[30:31], v[26:29], off sc0 sc1 nt
	s_waitcnt lgkmcnt(0)

.LBB0_963:
	s_andn2_b64 vcc, exec, s[0:1]
	s_cbranch_vccnz .LBB0_944
	s_mul_hi_i32 s2, s22, 0x2e8ba2e9
	s_lshr_b32 s3, s2, 31
	s_ashr_i32 s2, s2, 5
	s_load_dwordx2 s[0:1], s[6:7], 0x40
	s_add_i32 s2, s2, s3
	s_mul_i32 s23, s2, 0xffffd400
	s_add_i32 s24, s18, s23
	s_ashr_i32 s25, s24, 31
	s_lshl_b64 s[24:25], s[24:25], 2
	s_waitcnt lgkmcnt(0)
	s_add_u32 s0, s0, s24
	s_addc_u32 s1, s1, s25
	v_lshlrev_b32_e32 v2, 2, v4
	v_lshl_add_u32 v25, s2, 6, v5
	v_lshl_add_u64 v[26:27], s[0:1], 0, v[2:3]
	s_mov_b64 s[0:1], 0x5800000
	v_lshl_add_u64 v[86:87], v[26:27], 0, s[0:1]
	v_add_u32_e32 v2, 4, v25
	v_mad_i64_i32 v[26:27], s[0:1], v25, s59, v[86:87]
	v_mad_i64_i32 v[30:31], s[0:1], v2, s59, v[86:87]
	global_load_dwordx4 v[26:29], v[26:27], off nt
	v_add_u32_e32 v2, 8, v25
	global_load_dwordx4 v[30:33], v[30:31], off nt
	v_mad_i64_i32 v[34:35], s[0:1], v2, s59, v[86:87]
	global_load_dwordx4 v[34:37], v[34:35], off nt
	v_add_u32_e32 v2, 12, v25
	v_mad_i64_i32 v[38:39], s[0:1], v2, s59, v[86:87]
	global_load_dwordx4 v[38:41], v[38:39], off nt
	v_add_u32_e32 v2, 16, v25
	v_mad_i64_i32 v[42:43], s[0:1], v2, s59, v[86:87]
	global_load_dwordx4 v[42:45], v[42:43], off nt
	v_add_u32_e32 v2, 20, v25
	v_mad_i64_i32 v[46:47], s[0:1], v2, s59, v[86:87]
	global_load_dwordx4 v[46:49], v[46:47], off nt
	v_add_u32_e32 v2, 24, v25
	v_mad_i64_i32 v[50:51], s[0:1], v2, s59, v[86:87]
	global_load_dwordx4 v[50:53], v[50:51], off nt
	v_add_u32_e32 v2, 28, v25
	v_mad_i64_i32 v[54:55], s[0:1], v2, s59, v[86:87]
	global_load_dwordx4 v[54:57], v[54:55], off nt
	v_add_u32_e32 v2, 32, v25
	v_mad_i64_i32 v[58:59], s[0:1], v2, s59, v[86:87]
	global_load_dwordx4 v[58:61], v[58:59], off nt
	v_add_u32_e32 v2, 36, v25
	v_mad_i64_i32 v[62:63], s[0:1], v2, s59, v[86:87]
	global_load_dwordx4 v[62:65], v[62:63], off nt
	v_add_u32_e32 v2, 40, v25
	v_mad_i64_i32 v[66:67], s[0:1], v2, s59, v[86:87]
	global_load_dwordx4 v[66:69], v[66:67], off nt
	v_add_u32_e32 v2, 44, v25
	v_mad_i64_i32 v[70:71], s[0:1], v2, s59, v[86:87]
	global_load_dwordx4 v[70:73], v[70:71], off nt
	v_add_u32_e32 v2, 48, v25
	v_mad_i64_i32 v[74:75], s[0:1], v2, s59, v[86:87]
	global_load_dwordx4 v[74:77], v[74:75], off nt
	v_add_u32_e32 v2, 52, v25
	v_mad_i64_i32 v[78:79], s[0:1], v2, s59, v[86:87]
	global_load_dwordx4 v[78:81], v[78:79], off nt
	v_add_u32_e32 v2, 56, v25
	v_mad_i64_i32 v[82:83], s[0:1], v2, s59, v[86:87]
	global_load_dwordx4 v[82:85], v[82:83], off nt
	v_add_u32_e32 v2, 60, v25
	v_mad_i64_i32 v[86:87], s[0:1], v2, s59, v[86:87]
	global_load_dwordx4 v[86:89], v[86:87], off nt
	v_add_u32_e32 v2, 0x410, v7
	s_ashr_i32 s3, s2, 31
	s_lshl_b64 s[0:1], s[2:3], 15
	s_mulk_i32 s2, 0x2c00
	s_add_u32 s0, s4, s0
	s_addc_u32 s1, s5, s1
	s_waitcnt vmcnt(0)
	ds_write2_b32 v7, v26, v27 offset1:1
	ds_write2_b32 v7, v28, v29 offset0:2 offset1:3
	v_add_u32_e32 v27, 0x400, v9
	ds_write2_b32 v2, v30, v31 offset1:1
	v_add_u32_e32 v2, 0x418, v7
	ds_write2_b32 v2, v32, v33 offset1:1
	v_add_u32_e32 v2, 0x820, v7
	ds_write2_b32 v2, v34, v35 offset1:1
	v_add_u32_e32 v2, 0x828, v7
	ds_write2_b32 v2, v36, v37 offset1:1
	v_add_u32_e32 v2, 0xc30, v7
	ds_write2_b32 v2, v38, v39 offset1:1
	v_add_u32_e32 v2, 0xc38, v7
	ds_write2_b32 v2, v40, v41 offset1:1
	v_add_u32_e32 v2, 0x1040, v7
	ds_write2_b32 v2, v42, v43 offset1:1
	v_add_u32_e32 v2, 0x1048, v7
	ds_write2_b32 v2, v44, v45 offset1:1
	v_add_u32_e32 v2, 0x1450, v7
	ds_write2_b32 v2, v46, v47 offset1:1
	v_add_u32_e32 v2, 0x1458, v7
	ds_write2_b32 v2, v48, v49 offset1:1
	v_add_u32_e32 v2, 0x1860, v7
	ds_write2_b32 v2, v50, v51 offset1:1
	v_add_u32_e32 v2, 0x1868, v7
	ds_write2_b32 v2, v52, v53 offset1:1
	v_add_u32_e32 v2, 0x1c70, v7
	ds_write2_b32 v2, v54, v55 offset1:1
	v_add_u32_e32 v2, 0x1c78, v7
	ds_write2_b32 v2, v56, v57 offset1:1
	v_add_u32_e32 v2, 0x2080, v7
	ds_write2_b32 v2, v58, v59 offset1:1
	v_add_u32_e32 v2, 0x2088, v7
	ds_write2_b32 v2, v60, v61 offset1:1
	v_add_u32_e32 v2, 0x2490, v7
	ds_write2_b32 v2, v62, v63 offset1:1
	v_add_u32_e32 v2, 0x2498, v7
	ds_write2_b32 v2, v64, v65 offset1:1
	v_add_u32_e32 v2, 0x28a0, v7
	ds_write2_b32 v2, v66, v67 offset1:1
	v_add_u32_e32 v2, 0x28a8, v7
	ds_write2_b32 v2, v68, v69 offset1:1
	v_add_u32_e32 v2, 0x2cb0, v7
	ds_write2_b32 v2, v70, v71 offset1:1
	v_add_u32_e32 v2, 0x2cb8, v7
	ds_write2_b32 v2, v72, v73 offset1:1
	v_add_u32_e32 v2, 0x30c0, v7
	ds_write2_b32 v2, v74, v75 offset1:1
	v_add_u32_e32 v2, 0x30c8, v7
	ds_write2_b32 v2, v76, v77 offset1:1
	v_add_u32_e32 v2, 0x34d0, v7
	ds_write2_b32 v2, v78, v79 offset1:1
	v_add_u32_e32 v2, 0x34d8, v7
	ds_write2_b32 v2, v80, v81 offset1:1
	v_add_u32_e32 v2, 0x38e0, v7
	ds_write2_b32 v2, v82, v83 offset1:1
	v_add_u32_e32 v2, 0x38e8, v7
	ds_write2_b32 v2, v84, v85 offset1:1
	v_add_u32_e32 v2, 0x3cf0, v7
	ds_write2_b32 v2, v86, v87 offset1:1
	v_add_u32_e32 v2, 0x3cf8, v7
	ds_write2_b32 v2, v88, v89 offset1:1
	s_waitcnt lgkmcnt(0)
	ds_read2_b32 v[32:33], v9 offset0:65 offset1:73
	ds_read2_b32 v[34:35], v9 offset1:8
	ds_read2_b32 v[36:37], v9 offset0:130 offset1:138
	ds_read2_b32 v[38:39], v9 offset0:195 offset1:203
	ds_read2_b32 v[40:41], v27 offset0:4 offset1:12
	ds_read2_b32 v[42:43], v27 offset0:69 offset1:77
	ds_read2_b32 v[44:45], v27 offset0:134 offset1:142
	ds_read2_b32 v[46:47], v27 offset0:199 offset1:207
	s_waitcnt lgkmcnt(7)
	v_bfe_u32 v25, v32, 16, 1
	s_waitcnt lgkmcnt(6)
	v_bfe_u32 v2, v34, 16, 1
	v_add3_u32 v2, v34, v2, s81
	v_lshrrev_b32_e32 v2, 16, v2
	v_add3_u32 v25, v32, v25, s81
	v_and_or_b32 v28, v25, s39, v2
	s_waitcnt lgkmcnt(5)
	v_bfe_u32 v2, v36, 16, 1
	v_add3_u32 v2, v36, v2, s81
	s_waitcnt lgkmcnt(4)
	v_bfe_u32 v25, v38, 16, 1
	v_lshrrev_b32_e32 v2, 16, v2
	v_add3_u32 v25, v38, v25, s81
	v_and_or_b32 v29, v25, s39, v2
	s_waitcnt lgkmcnt(3)
	v_bfe_u32 v2, v40, 16, 1
	v_add3_u32 v2, v40, v2, s81
	s_waitcnt lgkmcnt(2)
	v_bfe_u32 v25, v42, 16, 1
	v_lshrrev_b32_e32 v2, 16, v2
	v_add3_u32 v25, v42, v25, s81
	v_and_or_b32 v30, v25, s39, v2
	s_waitcnt lgkmcnt(1)
	v_bfe_u32 v2, v44, 16, 1
	v_add3_u32 v2, v44, v2, s81
	s_waitcnt lgkmcnt(0)
	v_bfe_u32 v25, v46, 16, 1
	v_lshrrev_b32_e32 v2, 16, v2
	v_add3_u32 v25, v46, v25, s81
	v_and_or_b32 v31, v25, s39, v2
	v_add_u32_e32 v25, s18, v8
	v_add_u32_e32 v26, s23, v25
	v_cmp_lt_i32_e32 vcc, s41, v26
	v_mov_b32_e32 v51, v3
	s_nop 0
	v_cndmask_b32_e32 v2, 0, v247, vcc
	v_subrev_u32_e32 v2, s2, v2
	v_add_u32_e32 v2, v25, v2
	v_ashrrev_i32_e32 v48, 7, v2
	v_cndmask_b32_e32 v32, 0, v248, vcc
	v_ashrrev_i32_e32 v49, 31, v48
	v_and_or_b32 v32, v26, s40, v32
	v_lshlrev_b64 v[48:49], 20, v[48:49]
	v_lshl_add_u64 v[48:49], s[0:1], 0, v[48:49]
	v_lshlrev_b32_e32 v2, 7, v32
	v_lshl_add_u64 v[48:49], v[48:49], 0, v[2:3]
	v_lshlrev_b32_e32 v2, 1, v6
	v_lshl_add_u64 v[48:49], v[48:49], 0, v[2:3]
	global_store_dwordx4 v[48:49], v[28:31], off sc0 sc1 nt
	v_bfe_u32 v32, v47, 16, 1
	v_add3_u32 v32, v47, v32, s81
	v_bfe_u32 v28, v35, 16, 1
	v_add3_u32 v28, v35, v28, s81
	v_bfe_u32 v29, v33, 16, 1
	v_lshrrev_b32_e32 v28, 16, v28
	v_add3_u32 v29, v33, v29, s81
	v_and_or_b32 v28, v29, s39, v28
	v_bfe_u32 v29, v37, 16, 1
	v_add3_u32 v29, v37, v29, s81
	v_bfe_u32 v30, v39, 16, 1
	v_lshrrev_b32_e32 v29, 16, v29
	v_add3_u32 v30, v39, v30, s81
	v_and_or_b32 v29, v30, s39, v29
	v_bfe_u32 v30, v41, 16, 1
	v_add3_u32 v30, v41, v30, s81
	v_bfe_u32 v31, v43, 16, 1
	v_lshrrev_b32_e32 v30, 16, v30
	v_add3_u32 v31, v43, v31, s81
	v_and_or_b32 v30, v31, s39, v30
	v_bfe_u32 v31, v45, 16, 1
	v_add3_u32 v31, v45, v31, s81
	v_lshrrev_b32_e32 v31, 16, v31
	v_and_or_b32 v31, v32, s39, v31
	v_add_u32_e32 v32, 8, v26
	v_cmp_lt_i32_e32 vcc, s41, v32
	v_mov_b32_e32 v35, v3
	s_nop 0
	v_cndmask_b32_e32 v33, 0, v247, vcc
	v_subrev_u32_e32 v33, s2, v33
	v_add3_u32 v33, v25, v33, 8
	v_cndmask_b32_e32 v34, 0, v248, vcc
	v_and_or_b32 v34, v32, s40, v34
	v_ashrrev_i32_e32 v32, 7, v33
	v_ashrrev_i32_e32 v33, 31, v32
	v_lshlrev_b64 v[32:33], 20, v[32:33]
	v_lshl_add_u64 v[32:33], s[0:1], 0, v[32:33]
	v_lshlrev_b32_e32 v34, 7, v34
	v_lshl_add_u64 v[32:33], v[32:33], 0, v[34:35]
	v_lshl_add_u64 v[32:33], v[32:33], 0, v[2:3]
	global_store_dwordx4 v[32:33], v[28:31], off sc0 sc1 nt
	ds_read2_b32 v[32:33], v9 offset0:16 offset1:24
	ds_read2_b32 v[34:35], v9 offset0:81 offset1:89
	ds_read2_b32 v[36:37], v9 offset0:146 offset1:154
	ds_read2_b32 v[38:39], v9 offset0:211 offset1:219
	ds_read2_b32 v[40:41], v27 offset0:20 offset1:28
	ds_read2_b32 v[42:43], v27 offset0:85 offset1:93
	ds_read2_b32 v[44:45], v27 offset0:150 offset1:158
	ds_read2_b32 v[46:47], v27 offset0:215 offset1:223
	s_waitcnt lgkmcnt(7)
	v_bfe_u32 v28, v32, 16, 1
	v_add3_u32 v28, v32, v28, s81
	s_waitcnt lgkmcnt(6)
	v_bfe_u32 v29, v34, 16, 1
	v_lshrrev_b32_e32 v28, 16, v28
	v_add3_u32 v29, v34, v29, s81
	v_and_or_b32 v28, v29, s39, v28
	s_waitcnt lgkmcnt(5)
	v_bfe_u32 v29, v36, 16, 1
	v_add3_u32 v29, v36, v29, s81
	s_waitcnt lgkmcnt(4)
	v_bfe_u32 v30, v38, 16, 1
	v_lshrrev_b32_e32 v29, 16, v29
	v_add3_u32 v30, v38, v30, s81
	v_and_or_b32 v29, v30, s39, v29
	s_waitcnt lgkmcnt(3)
	v_bfe_u32 v30, v40, 16, 1
	v_add3_u32 v30, v40, v30, s81
	s_waitcnt lgkmcnt(2)
	v_bfe_u32 v31, v42, 16, 1
	v_lshrrev_b32_e32 v30, 16, v30
	v_add3_u32 v31, v42, v31, s81
	v_and_or_b32 v30, v31, s39, v30
	s_waitcnt lgkmcnt(1)
	v_bfe_u32 v31, v44, 16, 1
	v_add3_u32 v31, v44, v31, s81
	s_waitcnt lgkmcnt(0)
	v_bfe_u32 v32, v46, 16, 1
	v_lshrrev_b32_e32 v31, 16, v31
	v_add3_u32 v32, v46, v32, s81
	v_and_or_b32 v31, v32, s39, v31
	v_add_u32_e32 v32, 16, v26
	v_cmp_lt_i32_e32 vcc, s41, v32
	s_nop 1
	v_cndmask_b32_e32 v34, 0, v247, vcc
	v_subrev_u32_e32 v34, s2, v34
	v_add3_u32 v34, v25, v34, 16
	v_ashrrev_i32_e32 v48, 7, v34
	v_cndmask_b32_e32 v36, 0, v248, vcc
	v_ashrrev_i32_e32 v49, 31, v48
	v_and_or_b32 v32, v32, s40, v36
	v_lshlrev_b64 v[48:49], 20, v[48:49]
	v_lshl_add_u64 v[48:49], s[0:1], 0, v[48:49]
	v_lshlrev_b32_e32 v50, 7, v32
	v_lshl_add_u64 v[48:49], v[48:49], 0, v[50:51]
	v_lshl_add_u64 v[48:49], v[48:49], 0, v[2:3]
	global_store_dwordx4 v[48:49], v[28:31], off sc0 sc1 nt
	v_bfe_u32 v32, v47, 16, 1
	v_add3_u32 v32, v47, v32, s81
	v_bfe_u32 v28, v33, 16, 1
	v_add3_u32 v28, v33, v28, s81
	v_bfe_u32 v29, v35, 16, 1
	v_lshrrev_b32_e32 v28, 16, v28
	v_add3_u32 v29, v35, v29, s81
	v_and_or_b32 v28, v29, s39, v28
	v_bfe_u32 v29, v37, 16, 1
	v_add3_u32 v29, v37, v29, s81
	v_bfe_u32 v30, v39, 16, 1
	v_lshrrev_b32_e32 v29, 16, v29
	v_add3_u32 v30, v39, v30, s81
	v_and_or_b32 v29, v30, s39, v29
	v_bfe_u32 v30, v41, 16, 1
	v_add3_u32 v30, v41, v30, s81
	v_bfe_u32 v31, v43, 16, 1
	v_lshrrev_b32_e32 v30, 16, v30
	v_add3_u32 v31, v43, v31, s81
	v_and_or_b32 v30, v31, s39, v30
	v_bfe_u32 v31, v45, 16, 1
	v_add3_u32 v31, v45, v31, s81
	v_lshrrev_b32_e32 v31, 16, v31
	v_and_or_b32 v31, v32, s39, v31
	v_add_u32_e32 v32, 24, v26
	v_cmp_lt_i32_e32 vcc, s41, v32
	v_mov_b32_e32 v35, v3
	s_nop 0
	v_cndmask_b32_e32 v33, 0, v247, vcc
	v_subrev_u32_e32 v33, s2, v33
	v_add3_u32 v33, v25, v33, 24
	v_cndmask_b32_e32 v34, 0, v248, vcc
	v_and_or_b32 v34, v32, s40, v34
	v_ashrrev_i32_e32 v32, 7, v33
	v_ashrrev_i32_e32 v33, 31, v32
	v_lshlrev_b64 v[32:33], 20, v[32:33]
	v_lshl_add_u64 v[32:33], s[0:1], 0, v[32:33]
	v_lshlrev_b32_e32 v34, 7, v34
	v_lshl_add_u64 v[32:33], v[32:33], 0, v[34:35]
	v_lshl_add_u64 v[32:33], v[32:33], 0, v[2:3]
	global_store_dwordx4 v[32:33], v[28:31], off sc0 sc1 nt
	ds_read2_b32 v[32:33], v9 offset0:32 offset1:40
	ds_read2_b32 v[34:35], v9 offset0:97 offset1:105
	ds_read2_b32 v[36:37], v9 offset0:162 offset1:170
	ds_read2_b32 v[38:39], v9 offset0:227 offset1:235
	ds_read2_b32 v[40:41], v27 offset0:36 offset1:44
	ds_read2_b32 v[42:43], v27 offset0:101 offset1:109
	ds_read2_b32 v[44:45], v27 offset0:166 offset1:174
	ds_read2_b32 v[46:47], v27 offset0:231 offset1:239
	s_waitcnt lgkmcnt(7)
	v_bfe_u32 v28, v32, 16, 1
	v_add3_u32 v28, v32, v28, s81
	s_waitcnt lgkmcnt(6)
	v_bfe_u32 v29, v34, 16, 1
	v_lshrrev_b32_e32 v28, 16, v28
	v_add3_u32 v29, v34, v29, s81
	v_and_or_b32 v28, v29, s39, v28
	s_waitcnt lgkmcnt(5)
	v_bfe_u32 v29, v36, 16, 1
	v_add3_u32 v29, v36, v29, s81
	s_waitcnt lgkmcnt(4)
	v_bfe_u32 v30, v38, 16, 1
	v_lshrrev_b32_e32 v29, 16, v29
	v_add3_u32 v30, v38, v30, s81
	v_and_or_b32 v29, v30, s39, v29
	s_waitcnt lgkmcnt(3)
	v_bfe_u32 v30, v40, 16, 1
	v_add3_u32 v30, v40, v30, s81
	s_waitcnt lgkmcnt(2)
	v_bfe_u32 v31, v42, 16, 1
	v_lshrrev_b32_e32 v30, 16, v30
	v_add3_u32 v31, v42, v31, s81
	v_and_or_b32 v30, v31, s39, v30
	s_waitcnt lgkmcnt(1)
	v_bfe_u32 v31, v44, 16, 1
	v_add3_u32 v31, v44, v31, s81
	s_waitcnt lgkmcnt(0)
	v_bfe_u32 v32, v46, 16, 1
	v_lshrrev_b32_e32 v31, 16, v31
	v_add3_u32 v32, v46, v32, s81
	v_and_or_b32 v31, v32, s39, v31
	v_add_u32_e32 v32, 32, v26
	v_cmp_lt_i32_e32 vcc, s41, v32
	s_nop 1
	v_cndmask_b32_e32 v34, 0, v247, vcc
	v_subrev_u32_e32 v34, s2, v34
	v_add3_u32 v34, v25, v34, 32
	v_ashrrev_i32_e32 v48, 7, v34
	v_cndmask_b32_e32 v36, 0, v248, vcc
	v_ashrrev_i32_e32 v49, 31, v48
	v_and_or_b32 v32, v32, s40, v36
	v_lshlrev_b64 v[48:49], 20, v[48:49]
	v_lshl_add_u64 v[48:49], s[0:1], 0, v[48:49]
	v_lshlrev_b32_e32 v50, 7, v32
	v_lshl_add_u64 v[48:49], v[48:49], 0, v[50:51]
	v_lshl_add_u64 v[48:49], v[48:49], 0, v[2:3]
	global_store_dwordx4 v[48:49], v[28:31], off sc0 sc1 nt
	v_bfe_u32 v32, v47, 16, 1
	v_add3_u32 v32, v47, v32, s81
	v_bfe_u32 v28, v33, 16, 1
	v_add3_u32 v28, v33, v28, s81
	v_bfe_u32 v29, v35, 16, 1
	v_lshrrev_b32_e32 v28, 16, v28
	v_add3_u32 v29, v35, v29, s81
	v_and_or_b32 v28, v29, s39, v28
	v_bfe_u32 v29, v37, 16, 1
	v_add3_u32 v29, v37, v29, s81
	v_bfe_u32 v30, v39, 16, 1
	v_lshrrev_b32_e32 v29, 16, v29
	v_add3_u32 v30, v39, v30, s81
	v_and_or_b32 v29, v30, s39, v29
	v_bfe_u32 v30, v41, 16, 1
	v_add3_u32 v30, v41, v30, s81
	v_bfe_u32 v31, v43, 16, 1
	v_lshrrev_b32_e32 v30, 16, v30
	v_add3_u32 v31, v43, v31, s81
	v_and_or_b32 v30, v31, s39, v30
	v_bfe_u32 v31, v45, 16, 1
	v_add3_u32 v31, v45, v31, s81
	v_lshrrev_b32_e32 v31, 16, v31
	v_and_or_b32 v31, v32, s39, v31
	v_add_u32_e32 v32, 40, v26
	v_cmp_lt_i32_e32 vcc, s41, v32
	v_mov_b32_e32 v35, v3
	s_nop 0
	v_cndmask_b32_e32 v33, 0, v247, vcc
	v_subrev_u32_e32 v33, s2, v33
	v_add3_u32 v33, v25, v33, 40
	v_cndmask_b32_e32 v34, 0, v248, vcc
	v_and_or_b32 v34, v32, s40, v34
	v_ashrrev_i32_e32 v32, 7, v33
	v_ashrrev_i32_e32 v33, 31, v32
	v_lshlrev_b64 v[32:33], 20, v[32:33]
	v_lshl_add_u64 v[32:33], s[0:1], 0, v[32:33]
	v_lshlrev_b32_e32 v34, 7, v34
	v_lshl_add_u64 v[32:33], v[32:33], 0, v[34:35]
	v_lshl_add_u64 v[32:33], v[32:33], 0, v[2:3]
	global_store_dwordx4 v[32:33], v[28:31], off sc0 sc1 nt
	ds_read2_b32 v[32:33], v9 offset0:48 offset1:56
	ds_read2_b32 v[34:35], v9 offset0:113 offset1:121
	ds_read2_b32 v[36:37], v9 offset0:178 offset1:186
	ds_read2_b32 v[38:39], v9 offset0:243 offset1:251
	ds_read2_b32 v[40:41], v27 offset0:52 offset1:60
	ds_read2_b32 v[42:43], v27 offset0:117 offset1:125
	ds_read2_b32 v[44:45], v27 offset0:182 offset1:190
	ds_read2_b32 v[46:47], v27 offset0:247 offset1:255
	s_waitcnt lgkmcnt(7)
	v_bfe_u32 v28, v32, 16, 1
	v_add3_u32 v28, v32, v28, s81
	s_waitcnt lgkmcnt(6)
	v_bfe_u32 v29, v34, 16, 1
	v_lshrrev_b32_e32 v28, 16, v28
	v_add3_u32 v29, v34, v29, s81
	v_and_or_b32 v28, v29, s39, v28
	s_waitcnt lgkmcnt(5)
	v_bfe_u32 v29, v36, 16, 1
	v_add3_u32 v29, v36, v29, s81
	s_waitcnt lgkmcnt(4)
	v_bfe_u32 v30, v38, 16, 1
	v_lshrrev_b32_e32 v29, 16, v29
	v_add3_u32 v30, v38, v30, s81
	v_and_or_b32 v29, v30, s39, v29
	s_waitcnt lgkmcnt(3)
	v_bfe_u32 v30, v40, 16, 1
	v_add3_u32 v30, v40, v30, s81
	s_waitcnt lgkmcnt(2)
	v_bfe_u32 v31, v42, 16, 1
	v_lshrrev_b32_e32 v30, 16, v30
	v_add3_u32 v31, v42, v31, s81
	s_waitcnt lgkmcnt(1)
	v_bfe_u32 v27, v44, 16, 1
	v_and_or_b32 v30, v31, s39, v30
	v_add3_u32 v27, v44, v27, s81
	s_waitcnt lgkmcnt(0)
	v_bfe_u32 v31, v46, 16, 1
	v_lshrrev_b32_e32 v27, 16, v27
	v_add3_u32 v31, v46, v31, s81
	v_and_or_b32 v31, v31, s39, v27
	v_add_u32_e32 v27, 48, v26
	v_cmp_lt_i32_e32 vcc, s41, v27
	v_add_u32_e32 v26, 56, v26
	s_nop 0
	v_cndmask_b32_e32 v32, 0, v247, vcc
	v_subrev_u32_e32 v32, s2, v32
	v_add3_u32 v32, v25, v32, 48
	v_ashrrev_i32_e32 v48, 7, v32
	v_cndmask_b32_e32 v34, 0, v248, vcc
	v_ashrrev_i32_e32 v49, 31, v48
	v_and_or_b32 v27, v27, s40, v34
	v_lshlrev_b64 v[48:49], 20, v[48:49]
	v_lshl_add_u64 v[48:49], s[0:1], 0, v[48:49]
	v_lshlrev_b32_e32 v50, 7, v27
	v_lshl_add_u64 v[48:49], v[48:49], 0, v[50:51]
	v_lshl_add_u64 v[48:49], v[48:49], 0, v[2:3]
	v_bfe_u32 v27, v33, 16, 1
	global_store_dwordx4 v[48:49], v[28:31], off sc0 sc1 nt
	v_add3_u32 v27, v33, v27, s81
	v_lshrrev_b32_e32 v27, 16, v27
	v_bfe_u32 v28, v35, 16, 1
	v_add3_u32 v28, v35, v28, s81
	v_and_or_b32 v28, v28, s39, v27
	v_bfe_u32 v27, v37, 16, 1
	v_add3_u32 v27, v37, v27, s81
	v_bfe_u32 v29, v39, 16, 1
	v_lshrrev_b32_e32 v27, 16, v27
	v_add3_u32 v29, v39, v29, s81
	v_and_or_b32 v29, v29, s39, v27
	v_bfe_u32 v27, v41, 16, 1
	v_add3_u32 v27, v41, v27, s81
	v_bfe_u32 v30, v43, 16, 1
	v_lshrrev_b32_e32 v27, 16, v27
	v_add3_u32 v30, v43, v30, s81
	v_and_or_b32 v30, v30, s39, v27
	v_bfe_u32 v27, v45, 16, 1
	v_add3_u32 v27, v45, v27, s81
	v_bfe_u32 v31, v47, 16, 1
	v_lshrrev_b32_e32 v27, 16, v27
	v_add3_u32 v31, v47, v31, s81
	v_cmp_lt_i32_e32 vcc, s41, v26
	v_and_or_b32 v31, v31, s39, v27
	v_mov_b32_e32 v33, v3
	v_cndmask_b32_e32 v27, 0, v247, vcc
	v_subrev_u32_e32 v27, s2, v27
	v_add3_u32 v25, v25, v27, 56
	v_cndmask_b32_e32 v27, 0, v248, vcc
	v_and_or_b32 v32, v26, s40, v27
	v_ashrrev_i32_e32 v26, 7, v25
	v_ashrrev_i32_e32 v27, 31, v26
	v_lshlrev_b64 v[26:27], 20, v[26:27]
	v_lshl_add_u64 v[26:27], s[0:1], 0, v[26:27]
	v_lshlrev_b32_e32 v32, 7, v32
	v_lshl_add_u64 v[26:27], v[26:27], 0, v[32:33]
	v_lshl_add_u64 v[26:27], v[26:27], 0, v[2:3]
	global_store_dwordx4 v[26:27], v[28:31], off sc0 sc1 nt
	s_waitcnt lgkmcnt(0)
	s_branch .LBB0_944
